# v50 + epint:sc1 (device-scope write-through hint on the 168 GEMM epilogue stores: less dirty L2 to flush at grid barriers)
# speedup vs baseline: 1.0019x; 1.0019x over previous
.LBB0_243:
	v_mbcnt_lo_u32_b32 v4, -1, 0
	v_mbcnt_hi_u32_b32 v4, -1, v4
	s_nop 0
	v_and_or_b32 v102, v4, 15, s3
	v_ashrrev_i32_e32 v4, 1, v4
	v_and_b32_e32 v4, -8, v4
	v_add_u32_e32 v4, s52, v4
	v_ashrrev_i32_e32 v5, 31, v4
	v_lshlrev_b64 v[4:5], 1, v[4:5]
	v_mov_b64_e32 v[6:7], s[36:37]
	v_mad_u64_u32 v[12:13], s[4:5], v102, s19, v[6:7]
	v_lshl_add_u64 v[96:97], v[12:13], 0, v[4:5]
	v_pk_mul_f32 v[14:15], s[0:1], v[158:159] op_sel_hi:[0,1]
	v_pk_mul_f32 v[12:13], s[0:1], v[156:157] op_sel_hi:[0,1]
	v_pk_mul_f32 v[98:99], s[0:1], v[154:155] op_sel_hi:[0,1]
	v_pk_mul_f32 v[100:101], s[0:1], v[152:153] op_sel_hi:[0,1]
	v_cvt_pk_bf16_f32 v12, v12, v13
	v_cvt_pk_bf16_f32 v13, v14, v15
	v_cvt_pk_bf16_f32 v14, v100, v101
	v_cvt_pk_bf16_f32 v15, v98, v99
	global_store_dwordx4 v[96:97], v[12:15], off sc1
	v_pk_mul_f32 v[98:99], s[0:1], v[162:163] op_sel_hi:[0,1]
	v_pk_mul_f32 v[100:101], s[0:1], v[160:161] op_sel_hi:[0,1]
	v_pk_mul_f32 v[14:15], s[0:1], v[142:143] op_sel_hi:[0,1]
	v_pk_mul_f32 v[12:13], s[0:1], v[140:141] op_sel_hi:[0,1]
	v_cvt_pk_bf16_f32 v12, v12, v13
	v_cvt_pk_bf16_f32 v13, v14, v15
	v_cvt_pk_bf16_f32 v14, v100, v101
	v_cvt_pk_bf16_f32 v15, v98, v99
	global_store_dwordx4 v[96:97], v[12:15], off offset:256 sc1
	s_nop 1
	v_or_b32_e32 v12, 16, v102
	v_mad_u64_u32 v[12:13], s[4:5], v12, s19, v[6:7]
	v_lshl_add_u64 v[96:97], v[12:13], 0, v[4:5]
	v_pk_mul_f32 v[14:15], s[0:1], v[150:151] op_sel_hi:[0,1]
	v_pk_mul_f32 v[12:13], s[0:1], v[148:149] op_sel_hi:[0,1]
	v_pk_mul_f32 v[98:99], s[0:1], v[146:147] op_sel_hi:[0,1]
	v_pk_mul_f32 v[100:101], s[0:1], v[144:145] op_sel_hi:[0,1]
	v_cvt_pk_bf16_f32 v12, v12, v13
	v_cvt_pk_bf16_f32 v13, v14, v15
	v_cvt_pk_bf16_f32 v14, v100, v101
	v_cvt_pk_bf16_f32 v15, v98, v99
	global_store_dwordx4 v[96:97], v[12:15], off sc1
	v_pk_mul_f32 v[98:99], s[0:1], v[134:135] op_sel_hi:[0,1]
	v_pk_mul_f32 v[100:101], s[0:1], v[132:133] op_sel_hi:[0,1]
	v_pk_mul_f32 v[14:15], s[0:1], v[138:139] op_sel_hi:[0,1]
	v_pk_mul_f32 v[12:13], s[0:1], v[136:137] op_sel_hi:[0,1]
	v_cvt_pk_bf16_f32 v12, v12, v13
	v_cvt_pk_bf16_f32 v13, v14, v15
	v_cvt_pk_bf16_f32 v14, v100, v101
	v_cvt_pk_bf16_f32 v15, v98, v99
	global_store_dwordx4 v[96:97], v[12:15], off offset:256 sc1
	s_nop 1
	v_or_b32_e32 v12, 32, v102
	v_mad_u64_u32 v[12:13], s[4:5], v12, s19, v[6:7]
	v_lshl_add_u64 v[96:97], v[12:13], 0, v[4:5]
	v_pk_mul_f32 v[14:15], s[0:1], v[46:47] op_sel_hi:[0,1]
	v_pk_mul_f32 v[12:13], s[0:1], v[44:45] op_sel_hi:[0,1]
	v_pk_mul_f32 v[42:43], s[0:1], v[42:43] op_sel_hi:[0,1]
	v_pk_mul_f32 v[40:41], s[0:1], v[40:41] op_sel_hi:[0,1]
	v_cvt_pk_bf16_f32 v12, v12, v13
	v_cvt_pk_bf16_f32 v13, v14, v15
	v_cvt_pk_bf16_f32 v14, v40, v41
	v_cvt_pk_bf16_f32 v15, v42, v43
	global_store_dwordx4 v[96:97], v[12:15], off sc1
	v_pk_mul_f32 v[40:41], s[0:1], v[126:127] op_sel_hi:[0,1]
	v_pk_mul_f32 v[42:43], s[0:1], v[124:125] op_sel_hi:[0,1]
	v_pk_mul_f32 v[14:15], s[0:1], v[130:131] op_sel_hi:[0,1]
	v_pk_mul_f32 v[12:13], s[0:1], v[128:129] op_sel_hi:[0,1]
	v_cvt_pk_bf16_f32 v12, v12, v13
	v_cvt_pk_bf16_f32 v13, v14, v15
	v_cvt_pk_bf16_f32 v14, v42, v43
	v_cvt_pk_bf16_f32 v15, v40, v41
	global_store_dwordx4 v[96:97], v[12:15], off offset:256 sc1
	s_nop 1
	v_or_b32_e32 v12, 48, v102
	v_mad_u64_u32 v[12:13], s[4:5], v12, s19, v[6:7]
	v_lshl_add_u64 v[40:41], v[12:13], 0, v[4:5]
	v_pk_mul_f32 v[14:15], s[0:1], v[34:35] op_sel_hi:[0,1]
	v_pk_mul_f32 v[12:13], s[0:1], v[32:33] op_sel_hi:[0,1]
	v_pk_mul_f32 v[32:33], s[0:1], v[38:39] op_sel_hi:[0,1]
	v_pk_mul_f32 v[34:35], s[0:1], v[36:37] op_sel_hi:[0,1]
	v_cvt_pk_bf16_f32 v12, v12, v13
	v_cvt_pk_bf16_f32 v13, v14, v15
	v_cvt_pk_bf16_f32 v14, v34, v35
	v_cvt_pk_bf16_f32 v15, v32, v33
	global_store_dwordx4 v[40:41], v[12:15], off sc1
	v_pk_mul_f32 v[32:33], s[0:1], v[54:55] op_sel_hi:[0,1]
	v_pk_mul_f32 v[34:35], s[0:1], v[52:53] op_sel_hi:[0,1]
	v_pk_mul_f32 v[14:15], s[0:1], v[50:51] op_sel_hi:[0,1]
	v_pk_mul_f32 v[12:13], s[0:1], v[48:49] op_sel_hi:[0,1]
	v_cvt_pk_bf16_f32 v12, v12, v13
	v_cvt_pk_bf16_f32 v13, v14, v15
	v_cvt_pk_bf16_f32 v14, v34, v35
	v_cvt_pk_bf16_f32 v15, v32, v33
	global_store_dwordx4 v[40:41], v[12:15], off offset:256 sc1
	s_nop 1
	v_add_u32_e32 v12, 0x80, v102
	v_mad_u64_u32 v[12:13], s[4:5], v12, s19, v[6:7]
	v_lshl_add_u64 v[32:33], v[12:13], 0, v[4:5]
	v_pk_mul_f32 v[14:15], s[0:1], v[94:95] op_sel_hi:[0,1]
	v_pk_mul_f32 v[12:13], s[0:1], v[92:93] op_sel_hi:[0,1]
	v_pk_mul_f32 v[34:35], s[0:1], v[90:91] op_sel_hi:[0,1]
	v_pk_mul_f32 v[36:37], s[0:1], v[88:89] op_sel_hi:[0,1]
	v_cvt_pk_bf16_f32 v12, v12, v13
	v_cvt_pk_bf16_f32 v13, v14, v15
	v_cvt_pk_bf16_f32 v14, v36, v37
	v_cvt_pk_bf16_f32 v15, v34, v35
	global_store_dwordx4 v[32:33], v[12:15], off sc1
	v_pk_mul_f32 v[34:35], s[0:1], v[70:71] op_sel_hi:[0,1]
	v_pk_mul_f32 v[36:37], s[0:1], v[68:69] op_sel_hi:[0,1]
	v_pk_mul_f32 v[14:15], s[0:1], v[74:75] op_sel_hi:[0,1]
	v_pk_mul_f32 v[12:13], s[0:1], v[72:73] op_sel_hi:[0,1]
	v_cvt_pk_bf16_f32 v12, v12, v13
	v_cvt_pk_bf16_f32 v13, v14, v15
	v_cvt_pk_bf16_f32 v14, v36, v37
	v_cvt_pk_bf16_f32 v15, v34, v35
	global_store_dwordx4 v[32:33], v[12:15], off offset:256 sc1
	s_nop 1
	v_add_u32_e32 v12, 0x90, v102
	v_mad_u64_u32 v[12:13], s[4:5], v12, s19, v[6:7]
	v_lshl_add_u64 v[32:33], v[12:13], 0, v[4:5]
	v_pk_mul_f32 v[14:15], s[0:1], v[86:87] op_sel_hi:[0,1]
	v_pk_mul_f32 v[12:13], s[0:1], v[84:85] op_sel_hi:[0,1]
	v_pk_mul_f32 v[34:35], s[0:1], v[82:83] op_sel_hi:[0,1]
	v_pk_mul_f32 v[36:37], s[0:1], v[80:81] op_sel_hi:[0,1]
	v_cvt_pk_bf16_f32 v12, v12, v13
	v_cvt_pk_bf16_f32 v13, v14, v15
	v_cvt_pk_bf16_f32 v14, v36, v37
	v_cvt_pk_bf16_f32 v15, v34, v35
	global_store_dwordx4 v[32:33], v[12:15], off sc1
	v_pk_mul_f32 v[34:35], s[0:1], v[62:63] op_sel_hi:[0,1]
	v_pk_mul_f32 v[36:37], s[0:1], v[60:61] op_sel_hi:[0,1]
	v_pk_mul_f32 v[14:15], s[0:1], v[66:67] op_sel_hi:[0,1]
	v_pk_mul_f32 v[12:13], s[0:1], v[64:65] op_sel_hi:[0,1]
	v_cvt_pk_bf16_f32 v12, v12, v13
	v_cvt_pk_bf16_f32 v13, v14, v15
	v_cvt_pk_bf16_f32 v14, v36, v37
	v_cvt_pk_bf16_f32 v15, v34, v35
	global_store_dwordx4 v[32:33], v[12:15], off offset:256 sc1
	s_nop 1
	v_add_u32_e32 v12, 0xa0, v102
	v_mad_u64_u32 v[12:13], s[4:5], v12, s19, v[6:7]
	v_lshl_add_u64 v[32:33], v[12:13], 0, v[4:5]
	v_pk_mul_f32 v[14:15], s[0:1], v[78:79] op_sel_hi:[0,1]
	v_pk_mul_f32 v[12:13], s[0:1], v[76:77] op_sel_hi:[0,1]
	v_pk_mul_f32 v[34:35], s[0:1], v[58:59] op_sel_hi:[0,1]
	v_pk_mul_f32 v[36:37], s[0:1], v[56:57] op_sel_hi:[0,1]
	v_cvt_pk_bf16_f32 v12, v12, v13
	v_cvt_pk_bf16_f32 v13, v14, v15
	v_cvt_pk_bf16_f32 v14, v36, v37
	v_cvt_pk_bf16_f32 v15, v34, v35
	global_store_dwordx4 v[32:33], v[12:15], off sc1
	v_pk_mul_f32 v[22:23], s[0:1], v[22:23] op_sel_hi:[0,1]
	v_pk_mul_f32 v[20:21], s[0:1], v[20:21] op_sel_hi:[0,1]
	v_pk_mul_f32 v[14:15], s[0:1], v[30:31] op_sel_hi:[0,1]
	v_pk_mul_f32 v[12:13], s[0:1], v[28:29] op_sel_hi:[0,1]
	v_cvt_pk_bf16_f32 v12, v12, v13
	v_cvt_pk_bf16_f32 v13, v14, v15
	v_cvt_pk_bf16_f32 v14, v20, v21
	v_cvt_pk_bf16_f32 v15, v22, v23
	global_store_dwordx4 v[32:33], v[12:15], off offset:256 sc1
	s_nop 1
	v_add_u32_e32 v12, 0xb0, v102
	v_mad_u64_u32 v[6:7], s[4:5], v12, s19, v[6:7]
	v_lshl_add_u64 v[12:13], v[6:7], 0, v[4:5]
	v_pk_mul_f32 v[6:7], s[0:1], v[26:27] op_sel_hi:[0,1]
	v_pk_mul_f32 v[4:5], s[0:1], v[24:25] op_sel_hi:[0,1]
	v_pk_mul_f32 v[14:15], s[0:1], v[18:19] op_sel_hi:[0,1]
	v_pk_mul_f32 v[16:17], s[0:1], v[16:17] op_sel_hi:[0,1]
	v_cvt_pk_bf16_f32 v4, v4, v5
	v_cvt_pk_bf16_f32 v5, v6, v7
	v_cvt_pk_bf16_f32 v6, v16, v17
	v_cvt_pk_bf16_f32 v7, v14, v15
	global_store_dwordx4 v[12:13], v[4:7], off sc1
	s_andn2_b64 vcc, exec, s[34:35]
	s_mov_b64 s[4:5], -1
	v_pk_mul_f32 v[4:5], s[0:1], v[10:11] op_sel_hi:[0,1]
	v_pk_mul_f32 v[6:7], s[0:1], v[8:9] op_sel_hi:[0,1]
	v_pk_mul_f32 v[8:9], s[0:1], v[2:3] op_sel_hi:[0,1]
	v_pk_mul_f32 v[2:3], s[0:1], v[0:1] op_sel_hi:[0,1]
	v_cvt_pk_bf16_f32 v0, v6, v7
	v_cvt_pk_bf16_f32 v1, v4, v5
	v_cvt_pk_bf16_f32 v2, v2, v3
	v_cvt_pk_bf16_f32 v3, v8, v9
	global_store_dwordx4 v[12:13], v[0:3], off offset:256 sc1
	s_cbranch_vccnz .LBB0_233
	s_andn2_b64 vcc, exec, s[20:21]
	s_cbranch_vccnz .LBB0_232
	s_barrier
	s_branch .LBB0_232

.LBB0_262:
	v_mbcnt_lo_u32_b32 v128, -1, 0
	v_mbcnt_hi_u32_b32 v128, -1, v128
	s_nop 0
	v_and_or_b32 v144, v128, 15, s3
	v_ashrrev_i32_e32 v128, 1, v128
	v_and_b32_e32 v128, -8, v128
	v_add_u32_e32 v128, s52, v128
	v_ashrrev_i32_e32 v129, 31, v128
	v_lshlrev_b64 v[128:129], 1, v[128:129]
	v_mov_b64_e32 v[132:133], s[36:37]
	v_mad_u64_u32 v[140:141], s[4:5], v144, s21, v[132:133]
	v_pk_mul_f32 v[122:123], s[0:1], v[122:123] op_sel_hi:[0,1]
	v_pk_mul_f32 v[120:121], s[0:1], v[120:121] op_sel_hi:[0,1]
	v_pk_mul_f32 v[142:143], s[0:1], v[114:115] op_sel_hi:[0,1]
	v_pk_mul_f32 v[114:115], s[0:1], v[112:113] op_sel_hi:[0,1]
	v_lshl_add_u64 v[140:141], v[140:141], 0, v[128:129]
	v_cvt_pk_bf16_f32 v112, v120, v121
	v_cvt_pk_bf16_f32 v113, v122, v123
	v_cvt_pk_bf16_f32 v114, v114, v115
	v_cvt_pk_bf16_f32 v115, v142, v143
	global_store_dwordx4 v[140:141], v[112:115], off sc1
	v_pk_mul_f32 v[118:119], s[0:1], v[118:119] op_sel_hi:[0,1]
	v_pk_mul_f32 v[116:117], s[0:1], v[116:117] op_sel_hi:[0,1]
	v_pk_mul_f32 v[114:115], s[0:1], v[126:127] op_sel_hi:[0,1]
	v_pk_mul_f32 v[112:113], s[0:1], v[124:125] op_sel_hi:[0,1]
	v_cvt_pk_bf16_f32 v112, v112, v113
	v_cvt_pk_bf16_f32 v113, v114, v115
	v_cvt_pk_bf16_f32 v114, v116, v117
	v_cvt_pk_bf16_f32 v115, v118, v119
	global_store_dwordx4 v[140:141], v[112:115], off offset:256 sc1
	s_nop 1
	v_or_b32_e32 v112, 16, v144
	v_mad_u64_u32 v[112:113], s[4:5], v112, s21, v[132:133]
	v_pk_mul_f32 v[106:107], s[0:1], v[106:107] op_sel_hi:[0,1]
	v_pk_mul_f32 v[104:105], s[0:1], v[104:105] op_sel_hi:[0,1]
	v_pk_mul_f32 v[114:115], s[0:1], v[98:99] op_sel_hi:[0,1]
	v_pk_mul_f32 v[98:99], s[0:1], v[96:97] op_sel_hi:[0,1]
	v_lshl_add_u64 v[112:113], v[112:113], 0, v[128:129]
	v_cvt_pk_bf16_f32 v96, v104, v105
	v_cvt_pk_bf16_f32 v97, v106, v107
	v_cvt_pk_bf16_f32 v98, v98, v99
	v_cvt_pk_bf16_f32 v99, v114, v115
	global_store_dwordx4 v[112:113], v[96:99], off sc1
	v_pk_mul_f32 v[102:103], s[0:1], v[102:103] op_sel_hi:[0,1]
	v_pk_mul_f32 v[100:101], s[0:1], v[100:101] op_sel_hi:[0,1]
	v_pk_mul_f32 v[98:99], s[0:1], v[110:111] op_sel_hi:[0,1]
	v_pk_mul_f32 v[96:97], s[0:1], v[108:109] op_sel_hi:[0,1]
	v_cvt_pk_bf16_f32 v96, v96, v97
	v_cvt_pk_bf16_f32 v97, v98, v99
	v_cvt_pk_bf16_f32 v98, v100, v101
	v_cvt_pk_bf16_f32 v99, v102, v103
	global_store_dwordx4 v[112:113], v[96:99], off offset:256 sc1
	s_nop 1
	v_or_b32_e32 v96, 32, v144
	v_mad_u64_u32 v[96:97], s[4:5], v96, s21, v[132:133]
	v_pk_mul_f32 v[74:75], s[0:1], v[74:75] op_sel_hi:[0,1]
	v_pk_mul_f32 v[72:73], s[0:1], v[72:73] op_sel_hi:[0,1]
	v_pk_mul_f32 v[98:99], s[0:1], v[66:67] op_sel_hi:[0,1]
	v_pk_mul_f32 v[66:67], s[0:1], v[64:65] op_sel_hi:[0,1]
	v_lshl_add_u64 v[96:97], v[96:97], 0, v[128:129]
	v_cvt_pk_bf16_f32 v64, v72, v73
	v_cvt_pk_bf16_f32 v65, v74, v75
	v_cvt_pk_bf16_f32 v66, v66, v67
	v_cvt_pk_bf16_f32 v67, v98, v99
	global_store_dwordx4 v[96:97], v[64:67], off sc1
	v_pk_mul_f32 v[70:71], s[0:1], v[70:71] op_sel_hi:[0,1]
	v_pk_mul_f32 v[68:69], s[0:1], v[68:69] op_sel_hi:[0,1]
	v_pk_mul_f32 v[66:67], s[0:1], v[78:79] op_sel_hi:[0,1]
	v_pk_mul_f32 v[64:65], s[0:1], v[76:77] op_sel_hi:[0,1]
	v_cvt_pk_bf16_f32 v64, v64, v65
	v_cvt_pk_bf16_f32 v65, v66, v67
	v_cvt_pk_bf16_f32 v66, v68, v69
	v_cvt_pk_bf16_f32 v67, v70, v71
	global_store_dwordx4 v[96:97], v[64:67], off offset:256 sc1
	s_nop 1
	v_or_b32_e32 v64, 48, v144
	v_mad_u64_u32 v[64:65], s[4:5], v64, s21, v[132:133]
	v_pk_mul_f32 v[42:43], s[0:1], v[42:43] op_sel_hi:[0,1]
	v_pk_mul_f32 v[40:41], s[0:1], v[40:41] op_sel_hi:[0,1]
	v_pk_mul_f32 v[66:67], s[0:1], v[34:35] op_sel_hi:[0,1]
	v_pk_mul_f32 v[34:35], s[0:1], v[32:33] op_sel_hi:[0,1]
	v_lshl_add_u64 v[64:65], v[64:65], 0, v[128:129]
	v_cvt_pk_bf16_f32 v32, v40, v41
	v_cvt_pk_bf16_f32 v33, v42, v43
	v_cvt_pk_bf16_f32 v34, v34, v35
	v_cvt_pk_bf16_f32 v35, v66, v67
	global_store_dwordx4 v[64:65], v[32:35], off sc1
	v_pk_mul_f32 v[38:39], s[0:1], v[38:39] op_sel_hi:[0,1]
	v_pk_mul_f32 v[36:37], s[0:1], v[36:37] op_sel_hi:[0,1]
	v_pk_mul_f32 v[34:35], s[0:1], v[46:47] op_sel_hi:[0,1]
	v_pk_mul_f32 v[32:33], s[0:1], v[44:45] op_sel_hi:[0,1]
	v_cvt_pk_bf16_f32 v32, v32, v33
	v_cvt_pk_bf16_f32 v33, v34, v35
	v_cvt_pk_bf16_f32 v34, v36, v37
	v_cvt_pk_bf16_f32 v35, v38, v39
	global_store_dwordx4 v[64:65], v[32:35], off offset:256 sc1
	s_nop 1
	v_add_u32_e32 v32, 0x80, v144
	v_mad_u64_u32 v[32:33], s[4:5], v32, s21, v[132:133]
	v_lshl_add_u64 v[36:37], v[32:33], 0, v[128:129]
	v_pk_mul_f32 v[34:35], s[0:1], v[90:91] op_sel_hi:[0,1]
	v_pk_mul_f32 v[32:33], s[0:1], v[88:89] op_sel_hi:[0,1]
	v_pk_mul_f32 v[38:39], s[0:1], v[82:83] op_sel_hi:[0,1]
	v_pk_mul_f32 v[40:41], s[0:1], v[80:81] op_sel_hi:[0,1]
	v_cvt_pk_bf16_f32 v32, v32, v33
	v_cvt_pk_bf16_f32 v33, v34, v35
	v_cvt_pk_bf16_f32 v34, v40, v41
	v_cvt_pk_bf16_f32 v35, v38, v39
	global_store_dwordx4 v[36:37], v[32:35], off sc1
	v_pk_mul_f32 v[38:39], s[0:1], v[86:87] op_sel_hi:[0,1]
	v_pk_mul_f32 v[40:41], s[0:1], v[84:85] op_sel_hi:[0,1]
	v_pk_mul_f32 v[34:35], s[0:1], v[94:95] op_sel_hi:[0,1]
	v_pk_mul_f32 v[32:33], s[0:1], v[92:93] op_sel_hi:[0,1]
	v_cvt_pk_bf16_f32 v32, v32, v33
	v_cvt_pk_bf16_f32 v33, v34, v35
	v_cvt_pk_bf16_f32 v34, v40, v41
	v_cvt_pk_bf16_f32 v35, v38, v39
	global_store_dwordx4 v[36:37], v[32:35], off offset:256 sc1
	s_nop 1
	v_add_u32_e32 v32, 0x90, v144
	v_mad_u64_u32 v[32:33], s[4:5], v32, s21, v[132:133]
	v_lshl_add_u64 v[36:37], v[32:33], 0, v[128:129]
	v_pk_mul_f32 v[34:35], s[0:1], v[58:59] op_sel_hi:[0,1]
	v_pk_mul_f32 v[32:33], s[0:1], v[56:57] op_sel_hi:[0,1]
	v_pk_mul_f32 v[38:39], s[0:1], v[50:51] op_sel_hi:[0,1]
	v_pk_mul_f32 v[40:41], s[0:1], v[48:49] op_sel_hi:[0,1]
	v_cvt_pk_bf16_f32 v32, v32, v33
	v_cvt_pk_bf16_f32 v33, v34, v35
	v_cvt_pk_bf16_f32 v34, v40, v41
	v_cvt_pk_bf16_f32 v35, v38, v39
	global_store_dwordx4 v[36:37], v[32:35], off sc1
	v_pk_mul_f32 v[38:39], s[0:1], v[54:55] op_sel_hi:[0,1]
	v_pk_mul_f32 v[40:41], s[0:1], v[52:53] op_sel_hi:[0,1]
	v_pk_mul_f32 v[34:35], s[0:1], v[62:63] op_sel_hi:[0,1]
	v_pk_mul_f32 v[32:33], s[0:1], v[60:61] op_sel_hi:[0,1]
	v_cvt_pk_bf16_f32 v32, v32, v33
	v_cvt_pk_bf16_f32 v33, v34, v35
	v_cvt_pk_bf16_f32 v34, v40, v41
	v_cvt_pk_bf16_f32 v35, v38, v39
	global_store_dwordx4 v[36:37], v[32:35], off offset:256 sc1
	s_nop 1
	v_add_u32_e32 v32, 0xa0, v144
	v_mad_u64_u32 v[32:33], s[4:5], v32, s21, v[132:133]
	v_pk_mul_f32 v[26:27], s[0:1], v[26:27] op_sel_hi:[0,1]
	v_pk_mul_f32 v[24:25], s[0:1], v[24:25] op_sel_hi:[0,1]
	v_pk_mul_f32 v[34:35], s[0:1], v[18:19] op_sel_hi:[0,1]
	v_pk_mul_f32 v[18:19], s[0:1], v[16:17] op_sel_hi:[0,1]
	v_lshl_add_u64 v[32:33], v[32:33], 0, v[128:129]
	v_cvt_pk_bf16_f32 v16, v24, v25
	v_cvt_pk_bf16_f32 v17, v26, v27
	v_cvt_pk_bf16_f32 v18, v18, v19
	v_cvt_pk_bf16_f32 v19, v34, v35
	global_store_dwordx4 v[32:33], v[16:19], off sc1
	v_pk_mul_f32 v[22:23], s[0:1], v[22:23] op_sel_hi:[0,1]
	v_pk_mul_f32 v[20:21], s[0:1], v[20:21] op_sel_hi:[0,1]
	v_pk_mul_f32 v[18:19], s[0:1], v[30:31] op_sel_hi:[0,1]
	v_pk_mul_f32 v[16:17], s[0:1], v[28:29] op_sel_hi:[0,1]
	v_cvt_pk_bf16_f32 v16, v16, v17
	v_cvt_pk_bf16_f32 v17, v18, v19
	v_cvt_pk_bf16_f32 v18, v20, v21
	v_cvt_pk_bf16_f32 v19, v22, v23
	global_store_dwordx4 v[32:33], v[16:19], off offset:256 sc1
	s_nop 1
	v_add_u32_e32 v16, 0xb0, v144
	v_mad_u64_u32 v[16:17], s[4:5], v16, s21, v[132:133]
	v_pk_mul_f32 v[10:11], s[0:1], v[10:11] op_sel_hi:[0,1]
	v_pk_mul_f32 v[8:9], s[0:1], v[8:9] op_sel_hi:[0,1]
	v_pk_mul_f32 v[18:19], s[0:1], v[2:3] op_sel_hi:[0,1]
	v_pk_mul_f32 v[2:3], s[0:1], v[0:1] op_sel_hi:[0,1]
	v_lshl_add_u64 v[16:17], v[16:17], 0, v[128:129]
	v_cvt_pk_bf16_f32 v0, v8, v9
	v_cvt_pk_bf16_f32 v1, v10, v11
	v_cvt_pk_bf16_f32 v2, v2, v3
	v_cvt_pk_bf16_f32 v3, v18, v19
	global_store_dwordx4 v[16:17], v[0:3], off sc1
	v_pk_mul_f32 v[6:7], s[0:1], v[6:7] op_sel_hi:[0,1]
	v_pk_mul_f32 v[4:5], s[0:1], v[4:5] op_sel_hi:[0,1]
	v_pk_mul_f32 v[2:3], s[0:1], v[14:15] op_sel_hi:[0,1]
	v_pk_mul_f32 v[0:1], s[0:1], v[12:13] op_sel_hi:[0,1]
	v_cvt_pk_bf16_f32 v0, v0, v1
	v_cvt_pk_bf16_f32 v1, v2, v3
	v_cvt_pk_bf16_f32 v2, v4, v5
	v_cvt_pk_bf16_f32 v3, v6, v7
	s_andn2_b64 vcc, exec, s[34:35]
	s_mov_b64 s[4:5], -1
	global_store_dwordx4 v[16:17], v[0:3], off offset:256 sc1
	s_cbranch_vccnz .LBB0_252
	s_andn2_b64 vcc, exec, s[22:23]
	s_cbranch_vccnz .LBB0_251
	s_barrier
	s_branch .LBB0_251

.LBB0_281:
	v_mbcnt_lo_u32_b32 v140, -1, 0
	v_mbcnt_hi_u32_b32 v140, -1, v140
	s_getpc_b64 s[4:5]
	s_add_u32 s4, s4, _ZL4INVF@rel32@lo+4
	s_addc_u32 s5, s5, _ZL4INVF@rel32@hi+12
	v_ashrrev_i32_e32 v8, 1, v140
	v_and_b32_e32 v8, -8, v8
	v_add_u32_e32 v138, s52, v8
	v_ashrrev_i32_e32 v139, 31, v138
	v_lshl_add_u64 v[20:21], v[138:139], 2, s[4:5]
	global_load_dwordx4 v[8:11], v[20:21], off offset:16
	s_nop 0
	global_load_dwordx4 v[20:23], v[20:21], off
	v_and_or_b32 v148, v140, 15, s3
	v_lshlrev_b64 v[138:139], 1, v[138:139]
	v_add_u32_e32 v140, s30, v148
	v_and_b32_e32 v140, 0xfff, v140
	v_cvt_f32_u32_e32 v149, v140
	v_mov_b64_e32 v[140:141], s[44:45]
	v_mad_u64_u32 v[150:151], s[4:5], v148, s29, v[140:141]
	s_waitcnt vmcnt(0)
	v_mul_f32_e32 v152, v20, v149
	v_mul_f32_e32 v153, 0.15915494, v152
	v_rndne_f32_e32 v153, v153
	v_fmac_f32_e32 v152, 0xc0c90000, v153
	v_fmac_f32_e32 v152, 0xbafdaa22, v153
	v_mul_f32_e32 v153, 0.15915494, v152
	v_sin_f32_e32 v152, v153
	v_cos_f32_e32 v154, v153
	v_mul_f32_e32 v153, v21, v149
	v_mul_f32_e32 v155, 0.15915494, v153
	v_rndne_f32_e32 v155, v155
	v_fmac_f32_e32 v153, 0xc0c90000, v155
	v_fmac_f32_e32 v153, 0xbafdaa22, v155
	v_mul_f32_e32 v155, 0.15915494, v153
	v_sin_f32_e32 v153, v155
	v_cos_f32_e32 v155, v155
	v_pk_mul_f32 v[156:157], v[132:133], v[152:153]
	v_pk_mul_f32 v[132:133], v[132:133], v[154:155]
	v_pk_fma_f32 v[156:157], v[128:129], v[154:155], v[156:157] neg_lo:[0,0,1] neg_hi:[0,0,1]
	v_pk_fma_f32 v[128:129], v[128:129], v[152:153], v[132:133]
	v_mul_f32_e32 v132, v22, v149
	v_mul_f32_e32 v133, 0.15915494, v132
	v_rndne_f32_e32 v133, v133
	v_fmac_f32_e32 v132, 0xc0c90000, v133
	v_fmac_f32_e32 v132, 0xbafdaa22, v133
	v_mul_f32_e32 v133, 0.15915494, v132
	v_sin_f32_e32 v132, v133
	v_cos_f32_e32 v152, v133
	v_mul_f32_e32 v133, v23, v149
	v_mul_f32_e32 v153, 0.15915494, v133
	v_rndne_f32_e32 v153, v153
	v_fmac_f32_e32 v133, 0xc0c90000, v153
	v_fmac_f32_e32 v133, 0xbafdaa22, v153
	v_mul_f32_e32 v153, 0.15915494, v133
	v_sin_f32_e32 v133, v153
	v_cos_f32_e32 v153, v153
	v_pk_mul_f32 v[156:157], s[34:35], v[156:157] op_sel_hi:[0,1]
	v_pk_mul_f32 v[128:129], s[34:35], v[128:129] op_sel_hi:[0,1]
	v_pk_mul_f32 v[154:155], v[134:135], v[132:133]
	v_pk_mul_f32 v[134:135], v[134:135], v[152:153]
	v_pk_fma_f32 v[154:155], v[130:131], v[152:153], v[154:155] neg_lo:[0,0,1] neg_hi:[0,0,1]
	v_pk_fma_f32 v[130:131], v[130:131], v[132:133], v[134:135]
	v_mul_f32_e32 v132, v8, v149
	v_mul_f32_e32 v133, 0.15915494, v132
	v_rndne_f32_e32 v133, v133
	v_fmac_f32_e32 v132, 0xc0c90000, v133
	v_fmac_f32_e32 v132, 0xbafdaa22, v133
	v_mul_f32_e32 v133, 0.15915494, v132
	v_sin_f32_e32 v132, v133
	v_cos_f32_e32 v134, v133
	v_mul_f32_e32 v133, v9, v149
	v_mul_f32_e32 v135, 0.15915494, v133
	v_rndne_f32_e32 v135, v135
	v_fmac_f32_e32 v133, 0xc0c90000, v135
	v_fmac_f32_e32 v133, 0xbafdaa22, v135
	v_mul_f32_e32 v135, 0.15915494, v133
	v_sin_f32_e32 v133, v135
	v_cos_f32_e32 v135, v135
	v_pk_mul_f32 v[154:155], s[34:35], v[154:155] op_sel_hi:[0,1]
	v_pk_mul_f32 v[130:131], s[34:35], v[130:131] op_sel_hi:[0,1]
	v_pk_mul_f32 v[152:153], v[124:125], v[132:133]
	v_pk_mul_f32 v[124:125], v[124:125], v[134:135]
	v_pk_fma_f32 v[152:153], v[120:121], v[134:135], v[152:153] neg_lo:[0,0,1] neg_hi:[0,0,1]
	v_pk_fma_f32 v[120:121], v[120:121], v[132:133], v[124:125]
	v_pk_mul_f32 v[152:153], s[34:35], v[152:153] op_sel_hi:[0,1]
	v_pk_mul_f32 v[124:125], s[34:35], v[120:121] op_sel_hi:[0,1]
	v_mul_f32_e32 v120, v10, v149
	v_mul_f32_e32 v121, 0.15915494, v120
	v_rndne_f32_e32 v121, v121
	v_fmac_f32_e32 v120, 0xc0c90000, v121
	v_fmac_f32_e32 v120, 0xbafdaa22, v121
	v_mul_f32_e32 v121, 0.15915494, v120
	v_sin_f32_e32 v120, v121
	v_cos_f32_e32 v132, v121
	v_mul_f32_e32 v121, v11, v149
	v_mul_f32_e32 v133, 0.15915494, v121
	v_rndne_f32_e32 v133, v133
	v_fmac_f32_e32 v121, 0xc0c90000, v133
	v_fmac_f32_e32 v121, 0xbafdaa22, v133
	v_mul_f32_e32 v133, 0.15915494, v121
	v_sin_f32_e32 v121, v133
	v_cos_f32_e32 v133, v133
	v_pk_mul_f32 v[134:135], v[126:127], v[120:121]
	s_nop 0
	v_pk_fma_f32 v[134:135], v[122:123], v[132:133], v[134:135] neg_lo:[0,0,1] neg_hi:[0,0,1]
	v_pk_mul_f32 v[126:127], v[126:127], v[132:133]
	v_pk_mul_f32 v[134:135], s[34:35], v[134:135] op_sel_hi:[0,1]
	v_pk_fma_f32 v[120:121], v[122:123], v[120:121], v[126:127]
	v_lshl_add_u64 v[132:133], v[150:151], 0, v[138:139]
	v_pk_mul_f32 v[126:127], s[34:35], v[120:121] op_sel_hi:[0,1]
	v_cvt_pk_bf16_f32 v120, v156, v157
	v_cvt_pk_bf16_f32 v121, v154, v155
	v_cvt_pk_bf16_f32 v122, v152, v153
	v_cvt_pk_bf16_f32 v123, v134, v135
	global_store_dwordx4 v[132:133], v[120:123], off sc1
	s_nop 1
	v_cvt_pk_bf16_f32 v120, v128, v129
	v_cvt_pk_bf16_f32 v121, v130, v131
	v_cvt_pk_bf16_f32 v122, v124, v125
	v_cvt_pk_bf16_f32 v123, v126, v127
	global_store_dwordx4 v[132:133], v[120:123], off offset:256 sc1
	s_nop 1
	v_or_b32_e32 v120, 16, v148
	v_add_u32_e32 v121, s30, v120
	v_and_b32_e32 v121, 0xfff, v121
	v_cvt_f32_u32_e32 v128, v121
	v_mad_u64_u32 v[120:121], s[4:5], v120, s29, v[140:141]
	v_mul_f32_e32 v122, v20, v128
	v_mul_f32_e32 v123, 0.15915494, v122
	v_rndne_f32_e32 v123, v123
	v_fmac_f32_e32 v122, 0xc0c90000, v123
	v_fmac_f32_e32 v122, 0xbafdaa22, v123
	v_mul_f32_e32 v123, 0.15915494, v122
	v_sin_f32_e32 v122, v123
	v_cos_f32_e32 v124, v123
	v_mul_f32_e32 v123, v21, v128
	v_mul_f32_e32 v125, 0.15915494, v123
	v_rndne_f32_e32 v125, v125
	v_fmac_f32_e32 v123, 0xc0c90000, v125
	v_fmac_f32_e32 v123, 0xbafdaa22, v125
	v_mul_f32_e32 v125, 0.15915494, v123
	v_sin_f32_e32 v123, v125
	v_cos_f32_e32 v125, v125
	v_pk_mul_f32 v[126:127], v[116:117], v[122:123]
	v_pk_mul_f32 v[116:117], v[116:117], v[124:125]
	v_pk_fma_f32 v[126:127], v[112:113], v[124:125], v[126:127] neg_lo:[0,0,1] neg_hi:[0,0,1]
	v_pk_fma_f32 v[112:113], v[112:113], v[122:123], v[116:117]
	v_mul_f32_e32 v116, v22, v128
	v_mul_f32_e32 v117, 0.15915494, v116
	v_rndne_f32_e32 v117, v117
	v_fmac_f32_e32 v116, 0xc0c90000, v117
	v_fmac_f32_e32 v116, 0xbafdaa22, v117
	v_mul_f32_e32 v117, 0.15915494, v116
	v_sin_f32_e32 v116, v117
	v_cos_f32_e32 v122, v117
	v_mul_f32_e32 v117, v23, v128
	v_mul_f32_e32 v123, 0.15915494, v117
	v_rndne_f32_e32 v123, v123
	v_fmac_f32_e32 v117, 0xc0c90000, v123
	v_fmac_f32_e32 v117, 0xbafdaa22, v123
	v_mul_f32_e32 v123, 0.15915494, v117
	v_sin_f32_e32 v117, v123
	v_cos_f32_e32 v123, v123
	v_pk_mul_f32 v[126:127], s[34:35], v[126:127] op_sel_hi:[0,1]
	v_pk_mul_f32 v[112:113], s[34:35], v[112:113] op_sel_hi:[0,1]
	v_pk_mul_f32 v[124:125], v[118:119], v[116:117]
	v_pk_mul_f32 v[118:119], v[118:119], v[122:123]
	v_pk_fma_f32 v[124:125], v[114:115], v[122:123], v[124:125] neg_lo:[0,0,1] neg_hi:[0,0,1]
	v_pk_fma_f32 v[114:115], v[114:115], v[116:117], v[118:119]
	v_mul_f32_e32 v116, v8, v128
	v_mul_f32_e32 v117, 0.15915494, v116
	v_rndne_f32_e32 v117, v117
	v_fmac_f32_e32 v116, 0xc0c90000, v117
	v_fmac_f32_e32 v116, 0xbafdaa22, v117
	v_mul_f32_e32 v117, 0.15915494, v116
	v_sin_f32_e32 v116, v117
	v_cos_f32_e32 v118, v117
	v_mul_f32_e32 v117, v9, v128
	v_mul_f32_e32 v119, 0.15915494, v117
	v_rndne_f32_e32 v119, v119
	v_fmac_f32_e32 v117, 0xc0c90000, v119
	v_fmac_f32_e32 v117, 0xbafdaa22, v119
	v_mul_f32_e32 v119, 0.15915494, v117
	v_sin_f32_e32 v117, v119
	v_cos_f32_e32 v119, v119
	v_pk_mul_f32 v[124:125], s[34:35], v[124:125] op_sel_hi:[0,1]
	v_pk_mul_f32 v[114:115], s[34:35], v[114:115] op_sel_hi:[0,1]
	v_pk_mul_f32 v[122:123], v[108:109], v[116:117]
	v_pk_mul_f32 v[108:109], v[108:109], v[118:119]
	v_pk_fma_f32 v[122:123], v[104:105], v[118:119], v[122:123] neg_lo:[0,0,1] neg_hi:[0,0,1]
	v_pk_fma_f32 v[104:105], v[104:105], v[116:117], v[108:109]
	v_pk_mul_f32 v[122:123], s[34:35], v[122:123] op_sel_hi:[0,1]
	v_pk_mul_f32 v[108:109], s[34:35], v[104:105] op_sel_hi:[0,1]
	v_mul_f32_e32 v104, v10, v128
	v_mul_f32_e32 v105, 0.15915494, v104
	v_rndne_f32_e32 v105, v105
	v_fmac_f32_e32 v104, 0xc0c90000, v105
	v_fmac_f32_e32 v104, 0xbafdaa22, v105
	v_mul_f32_e32 v105, 0.15915494, v104
	v_sin_f32_e32 v104, v105
	v_cos_f32_e32 v116, v105
	v_mul_f32_e32 v105, v11, v128
	v_mul_f32_e32 v117, 0.15915494, v105
	v_rndne_f32_e32 v117, v117
	v_fmac_f32_e32 v105, 0xc0c90000, v117
	v_fmac_f32_e32 v105, 0xbafdaa22, v117
	v_mul_f32_e32 v117, 0.15915494, v105
	v_sin_f32_e32 v105, v117
	v_cos_f32_e32 v117, v117
	v_pk_mul_f32 v[118:119], v[110:111], v[104:105]
	s_nop 0
	v_pk_fma_f32 v[118:119], v[106:107], v[116:117], v[118:119] neg_lo:[0,0,1] neg_hi:[0,0,1]
	v_pk_mul_f32 v[110:111], v[110:111], v[116:117]
	v_pk_mul_f32 v[118:119], s[34:35], v[118:119] op_sel_hi:[0,1]
	v_pk_fma_f32 v[104:105], v[106:107], v[104:105], v[110:111]
	v_lshl_add_u64 v[116:117], v[120:121], 0, v[138:139]
	v_pk_mul_f32 v[110:111], s[34:35], v[104:105] op_sel_hi:[0,1]
	v_cvt_pk_bf16_f32 v104, v126, v127
	v_cvt_pk_bf16_f32 v105, v124, v125
	v_cvt_pk_bf16_f32 v106, v122, v123
	v_cvt_pk_bf16_f32 v107, v118, v119
	global_store_dwordx4 v[116:117], v[104:107], off sc1
	s_nop 1
	v_cvt_pk_bf16_f32 v104, v112, v113
	v_cvt_pk_bf16_f32 v105, v114, v115
	v_cvt_pk_bf16_f32 v106, v108, v109
	v_cvt_pk_bf16_f32 v107, v110, v111
	global_store_dwordx4 v[116:117], v[104:107], off offset:256 sc1
	s_nop 1
	v_or_b32_e32 v104, 32, v148
	v_add_u32_e32 v105, s30, v104
	v_and_b32_e32 v105, 0xfff, v105
	v_cvt_f32_u32_e32 v112, v105
	v_mad_u64_u32 v[104:105], s[4:5], v104, s29, v[140:141]
	v_mul_f32_e32 v106, v20, v112
	v_mul_f32_e32 v107, 0.15915494, v106
	v_rndne_f32_e32 v107, v107
	v_fmac_f32_e32 v106, 0xc0c90000, v107
	v_fmac_f32_e32 v106, 0xbafdaa22, v107
	v_mul_f32_e32 v107, 0.15915494, v106
	v_sin_f32_e32 v106, v107
	v_cos_f32_e32 v108, v107
	v_mul_f32_e32 v107, v21, v112
	v_mul_f32_e32 v109, 0.15915494, v107
	v_rndne_f32_e32 v109, v109
	v_fmac_f32_e32 v107, 0xc0c90000, v109
	v_fmac_f32_e32 v107, 0xbafdaa22, v109
	v_mul_f32_e32 v109, 0.15915494, v107
	v_sin_f32_e32 v107, v109
	v_cos_f32_e32 v109, v109
	v_pk_mul_f32 v[110:111], v[100:101], v[106:107]
	v_pk_mul_f32 v[100:101], v[100:101], v[108:109]
	v_pk_fma_f32 v[110:111], v[96:97], v[108:109], v[110:111] neg_lo:[0,0,1] neg_hi:[0,0,1]
	v_pk_fma_f32 v[96:97], v[96:97], v[106:107], v[100:101]
	v_mul_f32_e32 v100, v22, v112
	v_mul_f32_e32 v101, 0.15915494, v100
	v_rndne_f32_e32 v101, v101
	v_fmac_f32_e32 v100, 0xc0c90000, v101
	v_fmac_f32_e32 v100, 0xbafdaa22, v101
	v_mul_f32_e32 v101, 0.15915494, v100
	v_sin_f32_e32 v100, v101
	v_cos_f32_e32 v106, v101
	v_mul_f32_e32 v101, v23, v112
	v_mul_f32_e32 v107, 0.15915494, v101
	v_rndne_f32_e32 v107, v107
	v_fmac_f32_e32 v101, 0xc0c90000, v107
	v_fmac_f32_e32 v101, 0xbafdaa22, v107
	v_mul_f32_e32 v107, 0.15915494, v101
	v_sin_f32_e32 v101, v107
	v_cos_f32_e32 v107, v107
	v_pk_mul_f32 v[110:111], s[34:35], v[110:111] op_sel_hi:[0,1]
	v_pk_mul_f32 v[96:97], s[34:35], v[96:97] op_sel_hi:[0,1]
	v_pk_mul_f32 v[108:109], v[102:103], v[100:101]
	v_pk_mul_f32 v[102:103], v[102:103], v[106:107]
	v_pk_fma_f32 v[108:109], v[98:99], v[106:107], v[108:109] neg_lo:[0,0,1] neg_hi:[0,0,1]
	v_pk_fma_f32 v[98:99], v[98:99], v[100:101], v[102:103]
	v_mul_f32_e32 v100, v8, v112
	v_mul_f32_e32 v101, 0.15915494, v100
	v_rndne_f32_e32 v101, v101
	v_fmac_f32_e32 v100, 0xc0c90000, v101
	v_fmac_f32_e32 v100, 0xbafdaa22, v101
	v_mul_f32_e32 v101, 0.15915494, v100
	v_sin_f32_e32 v100, v101
	v_cos_f32_e32 v102, v101
	v_mul_f32_e32 v101, v9, v112
	v_mul_f32_e32 v103, 0.15915494, v101
	v_rndne_f32_e32 v103, v103
	v_fmac_f32_e32 v101, 0xc0c90000, v103
	v_fmac_f32_e32 v101, 0xbafdaa22, v103
	v_mul_f32_e32 v103, 0.15915494, v101
	v_sin_f32_e32 v101, v103
	v_cos_f32_e32 v103, v103
	v_pk_mul_f32 v[108:109], s[34:35], v[108:109] op_sel_hi:[0,1]
	v_pk_mul_f32 v[98:99], s[34:35], v[98:99] op_sel_hi:[0,1]
	v_pk_mul_f32 v[106:107], v[92:93], v[100:101]
	v_pk_mul_f32 v[92:93], v[92:93], v[102:103]
	v_pk_fma_f32 v[106:107], v[88:89], v[102:103], v[106:107] neg_lo:[0,0,1] neg_hi:[0,0,1]
	v_pk_fma_f32 v[88:89], v[88:89], v[100:101], v[92:93]
	v_pk_mul_f32 v[106:107], s[34:35], v[106:107] op_sel_hi:[0,1]
	v_pk_mul_f32 v[92:93], s[34:35], v[88:89] op_sel_hi:[0,1]
	v_mul_f32_e32 v88, v10, v112
	v_mul_f32_e32 v89, 0.15915494, v88
	v_rndne_f32_e32 v89, v89
	v_fmac_f32_e32 v88, 0xc0c90000, v89
	v_fmac_f32_e32 v88, 0xbafdaa22, v89
	v_mul_f32_e32 v89, 0.15915494, v88
	v_sin_f32_e32 v88, v89
	v_cos_f32_e32 v100, v89
	v_mul_f32_e32 v89, v11, v112
	v_mul_f32_e32 v101, 0.15915494, v89
	v_rndne_f32_e32 v101, v101
	v_fmac_f32_e32 v89, 0xc0c90000, v101
	v_fmac_f32_e32 v89, 0xbafdaa22, v101
	v_mul_f32_e32 v101, 0.15915494, v89
	v_sin_f32_e32 v89, v101
	v_cos_f32_e32 v101, v101
	v_pk_mul_f32 v[102:103], v[94:95], v[88:89]
	s_nop 0
	v_pk_fma_f32 v[102:103], v[90:91], v[100:101], v[102:103] neg_lo:[0,0,1] neg_hi:[0,0,1]
	v_pk_mul_f32 v[94:95], v[94:95], v[100:101]
	v_pk_mul_f32 v[102:103], s[34:35], v[102:103] op_sel_hi:[0,1]
	v_pk_fma_f32 v[88:89], v[90:91], v[88:89], v[94:95]
	v_lshl_add_u64 v[100:101], v[104:105], 0, v[138:139]
	v_pk_mul_f32 v[94:95], s[34:35], v[88:89] op_sel_hi:[0,1]
	v_cvt_pk_bf16_f32 v88, v110, v111
	v_cvt_pk_bf16_f32 v89, v108, v109
	v_cvt_pk_bf16_f32 v90, v106, v107
	v_cvt_pk_bf16_f32 v91, v102, v103
	global_store_dwordx4 v[100:101], v[88:91], off sc1
	s_nop 1
	v_cvt_pk_bf16_f32 v88, v96, v97
	v_cvt_pk_bf16_f32 v89, v98, v99
	v_cvt_pk_bf16_f32 v90, v92, v93
	v_cvt_pk_bf16_f32 v91, v94, v95
	global_store_dwordx4 v[100:101], v[88:91], off offset:256 sc1
	s_nop 1
	v_or_b32_e32 v88, 48, v148
	v_add_u32_e32 v89, s30, v88
	v_and_b32_e32 v89, 0xfff, v89
	v_cvt_f32_u32_e32 v96, v89
	v_mad_u64_u32 v[88:89], s[4:5], v88, s29, v[140:141]
	v_mul_f32_e32 v90, v20, v96
	v_mul_f32_e32 v91, 0.15915494, v90
	v_rndne_f32_e32 v91, v91
	v_fmac_f32_e32 v90, 0xc0c90000, v91
	v_fmac_f32_e32 v90, 0xbafdaa22, v91
	v_mul_f32_e32 v91, 0.15915494, v90
	v_sin_f32_e32 v90, v91
	v_cos_f32_e32 v92, v91
	v_mul_f32_e32 v91, v21, v96
	v_mul_f32_e32 v93, 0.15915494, v91
	v_rndne_f32_e32 v93, v93
	v_fmac_f32_e32 v91, 0xc0c90000, v93
	v_fmac_f32_e32 v91, 0xbafdaa22, v93
	v_mul_f32_e32 v93, 0.15915494, v91
	v_sin_f32_e32 v91, v93
	v_cos_f32_e32 v93, v93
	v_pk_mul_f32 v[94:95], v[84:85], v[90:91]
	v_pk_mul_f32 v[84:85], v[84:85], v[92:93]
	v_pk_fma_f32 v[94:95], v[80:81], v[92:93], v[94:95] neg_lo:[0,0,1] neg_hi:[0,0,1]
	v_pk_fma_f32 v[80:81], v[80:81], v[90:91], v[84:85]
	v_mul_f32_e32 v84, v22, v96
	v_mul_f32_e32 v85, 0.15915494, v84
	v_rndne_f32_e32 v85, v85
	v_fmac_f32_e32 v84, 0xc0c90000, v85
	v_fmac_f32_e32 v84, 0xbafdaa22, v85
	v_mul_f32_e32 v85, 0.15915494, v84
	v_sin_f32_e32 v84, v85
	v_cos_f32_e32 v90, v85
	v_mul_f32_e32 v85, v23, v96
	v_mul_f32_e32 v91, 0.15915494, v85
	v_rndne_f32_e32 v91, v91
	v_fmac_f32_e32 v85, 0xc0c90000, v91
	v_fmac_f32_e32 v85, 0xbafdaa22, v91
	v_mul_f32_e32 v91, 0.15915494, v85
	v_sin_f32_e32 v85, v91
	v_cos_f32_e32 v91, v91
	v_pk_mul_f32 v[94:95], s[34:35], v[94:95] op_sel_hi:[0,1]
	v_pk_mul_f32 v[80:81], s[34:35], v[80:81] op_sel_hi:[0,1]
	v_pk_mul_f32 v[92:93], v[86:87], v[84:85]
	v_pk_mul_f32 v[86:87], v[86:87], v[90:91]
	v_pk_fma_f32 v[92:93], v[82:83], v[90:91], v[92:93] neg_lo:[0,0,1] neg_hi:[0,0,1]
	v_pk_fma_f32 v[82:83], v[82:83], v[84:85], v[86:87]
	v_mul_f32_e32 v84, v8, v96
	v_mul_f32_e32 v85, 0.15915494, v84
	v_rndne_f32_e32 v85, v85
	v_fmac_f32_e32 v84, 0xc0c90000, v85
	v_fmac_f32_e32 v84, 0xbafdaa22, v85
	v_mul_f32_e32 v85, 0.15915494, v84
	v_sin_f32_e32 v84, v85
	v_cos_f32_e32 v86, v85
	v_mul_f32_e32 v85, v9, v96
	v_mul_f32_e32 v87, 0.15915494, v85
	v_rndne_f32_e32 v87, v87
	v_fmac_f32_e32 v85, 0xc0c90000, v87
	v_fmac_f32_e32 v85, 0xbafdaa22, v87
	v_mul_f32_e32 v87, 0.15915494, v85
	v_sin_f32_e32 v85, v87
	v_cos_f32_e32 v87, v87
	v_pk_mul_f32 v[92:93], s[34:35], v[92:93] op_sel_hi:[0,1]
	v_pk_mul_f32 v[82:83], s[34:35], v[82:83] op_sel_hi:[0,1]
	v_pk_mul_f32 v[90:91], v[76:77], v[84:85]
	v_pk_mul_f32 v[76:77], v[76:77], v[86:87]
	v_pk_fma_f32 v[90:91], v[72:73], v[86:87], v[90:91] neg_lo:[0,0,1] neg_hi:[0,0,1]
	v_pk_fma_f32 v[72:73], v[72:73], v[84:85], v[76:77]
	v_pk_mul_f32 v[90:91], s[34:35], v[90:91] op_sel_hi:[0,1]
	v_pk_mul_f32 v[76:77], s[34:35], v[72:73] op_sel_hi:[0,1]
	v_mul_f32_e32 v72, v10, v96
	v_mul_f32_e32 v73, 0.15915494, v72
	v_rndne_f32_e32 v73, v73
	v_fmac_f32_e32 v72, 0xc0c90000, v73
	v_fmac_f32_e32 v72, 0xbafdaa22, v73
	v_mul_f32_e32 v73, 0.15915494, v72
	v_sin_f32_e32 v72, v73
	v_cos_f32_e32 v84, v73
	v_mul_f32_e32 v73, v11, v96
	v_mul_f32_e32 v85, 0.15915494, v73
	v_rndne_f32_e32 v85, v85
	v_fmac_f32_e32 v73, 0xc0c90000, v85
	v_fmac_f32_e32 v73, 0xbafdaa22, v85
	v_mul_f32_e32 v85, 0.15915494, v73
	v_sin_f32_e32 v73, v85
	v_cos_f32_e32 v85, v85
	v_pk_mul_f32 v[86:87], v[78:79], v[72:73]
	s_nop 0
	v_pk_fma_f32 v[86:87], v[74:75], v[84:85], v[86:87] neg_lo:[0,0,1] neg_hi:[0,0,1]
	v_pk_mul_f32 v[78:79], v[78:79], v[84:85]
	v_pk_mul_f32 v[86:87], s[34:35], v[86:87] op_sel_hi:[0,1]
	v_pk_fma_f32 v[72:73], v[74:75], v[72:73], v[78:79]
	v_lshl_add_u64 v[84:85], v[88:89], 0, v[138:139]
	v_pk_mul_f32 v[78:79], s[34:35], v[72:73] op_sel_hi:[0,1]
	v_cvt_pk_bf16_f32 v72, v94, v95
	v_cvt_pk_bf16_f32 v73, v92, v93
	v_cvt_pk_bf16_f32 v74, v90, v91
	v_cvt_pk_bf16_f32 v75, v86, v87
	global_store_dwordx4 v[84:85], v[72:75], off sc1
	s_nop 1
	v_cvt_pk_bf16_f32 v72, v80, v81
	v_cvt_pk_bf16_f32 v73, v82, v83
	v_cvt_pk_bf16_f32 v74, v76, v77
	v_cvt_pk_bf16_f32 v75, v78, v79
	global_store_dwordx4 v[84:85], v[72:75], off offset:256 sc1
	s_nop 1
	v_add_u32_e32 v72, 0x80, v148
	v_add_u32_e32 v73, s30, v72
	v_and_b32_e32 v73, 0xfff, v73
	v_cvt_f32_u32_e32 v80, v73
	v_mad_u64_u32 v[72:73], s[4:5], v72, s29, v[140:141]
	v_mul_f32_e32 v74, v20, v80
	v_mul_f32_e32 v75, 0.15915494, v74
	v_rndne_f32_e32 v75, v75
	v_fmac_f32_e32 v74, 0xc0c90000, v75
	v_fmac_f32_e32 v74, 0xbafdaa22, v75
	v_mul_f32_e32 v75, 0.15915494, v74
	v_sin_f32_e32 v74, v75
	v_cos_f32_e32 v76, v75
	v_mul_f32_e32 v75, v21, v80
	v_mul_f32_e32 v77, 0.15915494, v75
	v_rndne_f32_e32 v77, v77
	v_fmac_f32_e32 v75, 0xc0c90000, v77
	v_fmac_f32_e32 v75, 0xbafdaa22, v77
	v_mul_f32_e32 v77, 0.15915494, v75
	v_sin_f32_e32 v75, v77
	v_cos_f32_e32 v77, v77
	v_pk_mul_f32 v[78:79], v[68:69], v[74:75]
	v_pk_mul_f32 v[68:69], v[68:69], v[76:77]
	v_pk_fma_f32 v[78:79], v[64:65], v[76:77], v[78:79] neg_lo:[0,0,1] neg_hi:[0,0,1]
	v_pk_fma_f32 v[64:65], v[64:65], v[74:75], v[68:69]
	v_mul_f32_e32 v68, v22, v80
	v_mul_f32_e32 v69, 0.15915494, v68
	v_rndne_f32_e32 v69, v69
	v_fmac_f32_e32 v68, 0xc0c90000, v69
	v_fmac_f32_e32 v68, 0xbafdaa22, v69
	v_mul_f32_e32 v69, 0.15915494, v68
	v_sin_f32_e32 v68, v69
	v_cos_f32_e32 v74, v69
	v_mul_f32_e32 v69, v23, v80
	v_mul_f32_e32 v75, 0.15915494, v69
	v_rndne_f32_e32 v75, v75
	v_fmac_f32_e32 v69, 0xc0c90000, v75
	v_fmac_f32_e32 v69, 0xbafdaa22, v75
	v_mul_f32_e32 v75, 0.15915494, v69
	v_sin_f32_e32 v69, v75
	v_cos_f32_e32 v75, v75
	v_pk_mul_f32 v[78:79], s[34:35], v[78:79] op_sel_hi:[0,1]
	v_pk_mul_f32 v[64:65], s[34:35], v[64:65] op_sel_hi:[0,1]
	v_pk_mul_f32 v[76:77], v[70:71], v[68:69]
	v_pk_mul_f32 v[70:71], v[70:71], v[74:75]
	v_pk_fma_f32 v[76:77], v[66:67], v[74:75], v[76:77] neg_lo:[0,0,1] neg_hi:[0,0,1]
	v_pk_fma_f32 v[66:67], v[66:67], v[68:69], v[70:71]
	v_mul_f32_e32 v68, v8, v80
	v_mul_f32_e32 v69, 0.15915494, v68
	v_rndne_f32_e32 v69, v69
	v_fmac_f32_e32 v68, 0xc0c90000, v69
	v_fmac_f32_e32 v68, 0xbafdaa22, v69
	v_mul_f32_e32 v69, 0.15915494, v68
	v_sin_f32_e32 v68, v69
	v_cos_f32_e32 v70, v69
	v_mul_f32_e32 v69, v9, v80
	v_mul_f32_e32 v71, 0.15915494, v69
	v_rndne_f32_e32 v71, v71
	v_fmac_f32_e32 v69, 0xc0c90000, v71
	v_fmac_f32_e32 v69, 0xbafdaa22, v71
	v_mul_f32_e32 v71, 0.15915494, v69
	v_sin_f32_e32 v69, v71
	v_cos_f32_e32 v71, v71
	v_pk_mul_f32 v[76:77], s[34:35], v[76:77] op_sel_hi:[0,1]
	v_pk_mul_f32 v[66:67], s[34:35], v[66:67] op_sel_hi:[0,1]
	v_pk_mul_f32 v[74:75], v[60:61], v[68:69]
	v_pk_mul_f32 v[60:61], v[60:61], v[70:71]
	v_pk_fma_f32 v[74:75], v[56:57], v[70:71], v[74:75] neg_lo:[0,0,1] neg_hi:[0,0,1]
	v_pk_fma_f32 v[56:57], v[56:57], v[68:69], v[60:61]
	v_pk_mul_f32 v[74:75], s[34:35], v[74:75] op_sel_hi:[0,1]
	v_pk_mul_f32 v[60:61], s[34:35], v[56:57] op_sel_hi:[0,1]
	v_mul_f32_e32 v56, v10, v80
	v_mul_f32_e32 v57, 0.15915494, v56
	v_rndne_f32_e32 v57, v57
	v_fmac_f32_e32 v56, 0xc0c90000, v57
	v_fmac_f32_e32 v56, 0xbafdaa22, v57
	v_mul_f32_e32 v57, 0.15915494, v56
	v_sin_f32_e32 v56, v57
	v_cos_f32_e32 v68, v57
	v_mul_f32_e32 v57, v11, v80
	v_mul_f32_e32 v69, 0.15915494, v57
	v_rndne_f32_e32 v69, v69
	v_fmac_f32_e32 v57, 0xc0c90000, v69
	v_fmac_f32_e32 v57, 0xbafdaa22, v69
	v_mul_f32_e32 v69, 0.15915494, v57
	v_sin_f32_e32 v57, v69
	v_cos_f32_e32 v69, v69
	v_pk_mul_f32 v[70:71], v[62:63], v[56:57]
	s_nop 0
	v_pk_fma_f32 v[70:71], v[58:59], v[68:69], v[70:71] neg_lo:[0,0,1] neg_hi:[0,0,1]
	v_pk_mul_f32 v[62:63], v[62:63], v[68:69]
	v_pk_mul_f32 v[70:71], s[34:35], v[70:71] op_sel_hi:[0,1]
	v_pk_fma_f32 v[56:57], v[58:59], v[56:57], v[62:63]
	v_lshl_add_u64 v[68:69], v[72:73], 0, v[138:139]
	v_pk_mul_f32 v[62:63], s[34:35], v[56:57] op_sel_hi:[0,1]
	v_cvt_pk_bf16_f32 v56, v78, v79
	v_cvt_pk_bf16_f32 v57, v76, v77
	v_cvt_pk_bf16_f32 v58, v74, v75
	v_cvt_pk_bf16_f32 v59, v70, v71
	global_store_dwordx4 v[68:69], v[56:59], off sc1
	s_nop 1
	v_cvt_pk_bf16_f32 v56, v64, v65
	v_cvt_pk_bf16_f32 v57, v66, v67
	v_cvt_pk_bf16_f32 v58, v60, v61
	v_cvt_pk_bf16_f32 v59, v62, v63
	global_store_dwordx4 v[68:69], v[56:59], off offset:256 sc1
	s_nop 1
	v_add_u32_e32 v56, 0x90, v148
	v_add_u32_e32 v57, s30, v56
	v_and_b32_e32 v57, 0xfff, v57
	v_cvt_f32_u32_e32 v64, v57
	v_mad_u64_u32 v[56:57], s[4:5], v56, s29, v[140:141]
	v_mul_f32_e32 v58, v20, v64
	v_mul_f32_e32 v59, 0.15915494, v58
	v_rndne_f32_e32 v59, v59
	v_fmac_f32_e32 v58, 0xc0c90000, v59
	v_fmac_f32_e32 v58, 0xbafdaa22, v59
	v_mul_f32_e32 v59, 0.15915494, v58
	v_sin_f32_e32 v58, v59
	v_cos_f32_e32 v60, v59
	v_mul_f32_e32 v59, v21, v64
	v_mul_f32_e32 v61, 0.15915494, v59
	v_rndne_f32_e32 v61, v61
	v_fmac_f32_e32 v59, 0xc0c90000, v61
	v_fmac_f32_e32 v59, 0xbafdaa22, v61
	v_mul_f32_e32 v61, 0.15915494, v59
	v_sin_f32_e32 v59, v61
	v_cos_f32_e32 v61, v61
	v_pk_mul_f32 v[62:63], v[52:53], v[58:59]
	v_pk_mul_f32 v[52:53], v[52:53], v[60:61]
	v_pk_fma_f32 v[62:63], v[48:49], v[60:61], v[62:63] neg_lo:[0,0,1] neg_hi:[0,0,1]
	v_pk_fma_f32 v[48:49], v[48:49], v[58:59], v[52:53]
	v_mul_f32_e32 v52, v22, v64
	v_mul_f32_e32 v53, 0.15915494, v52
	v_rndne_f32_e32 v53, v53
	v_fmac_f32_e32 v52, 0xc0c90000, v53
	v_fmac_f32_e32 v52, 0xbafdaa22, v53
	v_mul_f32_e32 v53, 0.15915494, v52
	v_sin_f32_e32 v52, v53
	v_cos_f32_e32 v58, v53
	v_mul_f32_e32 v53, v23, v64
	v_mul_f32_e32 v59, 0.15915494, v53
	v_rndne_f32_e32 v59, v59
	v_fmac_f32_e32 v53, 0xc0c90000, v59
	v_fmac_f32_e32 v53, 0xbafdaa22, v59
	v_mul_f32_e32 v59, 0.15915494, v53
	v_sin_f32_e32 v53, v59
	v_cos_f32_e32 v59, v59
	v_pk_mul_f32 v[62:63], s[34:35], v[62:63] op_sel_hi:[0,1]
	v_pk_mul_f32 v[48:49], s[34:35], v[48:49] op_sel_hi:[0,1]
	v_pk_mul_f32 v[60:61], v[54:55], v[52:53]
	v_pk_mul_f32 v[54:55], v[54:55], v[58:59]
	v_pk_fma_f32 v[60:61], v[50:51], v[58:59], v[60:61] neg_lo:[0,0,1] neg_hi:[0,0,1]
	v_pk_fma_f32 v[50:51], v[50:51], v[52:53], v[54:55]
	v_mul_f32_e32 v52, v8, v64
	v_mul_f32_e32 v53, 0.15915494, v52
	v_rndne_f32_e32 v53, v53
	v_fmac_f32_e32 v52, 0xc0c90000, v53
	v_fmac_f32_e32 v52, 0xbafdaa22, v53
	v_mul_f32_e32 v53, 0.15915494, v52
	v_sin_f32_e32 v52, v53
	v_cos_f32_e32 v54, v53
	v_mul_f32_e32 v53, v9, v64
	v_mul_f32_e32 v55, 0.15915494, v53
	v_rndne_f32_e32 v55, v55
	v_fmac_f32_e32 v53, 0xc0c90000, v55
	v_fmac_f32_e32 v53, 0xbafdaa22, v55
	v_mul_f32_e32 v55, 0.15915494, v53
	v_sin_f32_e32 v53, v55
	v_cos_f32_e32 v55, v55
	v_pk_mul_f32 v[60:61], s[34:35], v[60:61] op_sel_hi:[0,1]
	v_pk_mul_f32 v[50:51], s[34:35], v[50:51] op_sel_hi:[0,1]
	v_pk_mul_f32 v[58:59], v[44:45], v[52:53]
	v_pk_mul_f32 v[44:45], v[44:45], v[54:55]
	v_pk_fma_f32 v[58:59], v[40:41], v[54:55], v[58:59] neg_lo:[0,0,1] neg_hi:[0,0,1]
	v_pk_fma_f32 v[40:41], v[40:41], v[52:53], v[44:45]
	v_pk_mul_f32 v[58:59], s[34:35], v[58:59] op_sel_hi:[0,1]
	v_pk_mul_f32 v[44:45], s[34:35], v[40:41] op_sel_hi:[0,1]
	v_mul_f32_e32 v40, v10, v64
	v_mul_f32_e32 v41, 0.15915494, v40
	v_rndne_f32_e32 v41, v41
	v_fmac_f32_e32 v40, 0xc0c90000, v41
	v_fmac_f32_e32 v40, 0xbafdaa22, v41
	v_mul_f32_e32 v41, 0.15915494, v40
	v_sin_f32_e32 v40, v41
	v_cos_f32_e32 v52, v41
	v_mul_f32_e32 v41, v11, v64
	v_mul_f32_e32 v53, 0.15915494, v41
	v_rndne_f32_e32 v53, v53
	v_fmac_f32_e32 v41, 0xc0c90000, v53
	v_fmac_f32_e32 v41, 0xbafdaa22, v53
	v_mul_f32_e32 v53, 0.15915494, v41
	v_sin_f32_e32 v41, v53
	v_cos_f32_e32 v53, v53
	v_pk_mul_f32 v[54:55], v[46:47], v[40:41]
	s_nop 0
	v_pk_fma_f32 v[54:55], v[42:43], v[52:53], v[54:55] neg_lo:[0,0,1] neg_hi:[0,0,1]
	v_pk_mul_f32 v[46:47], v[46:47], v[52:53]
	v_pk_mul_f32 v[54:55], s[34:35], v[54:55] op_sel_hi:[0,1]
	v_pk_fma_f32 v[40:41], v[42:43], v[40:41], v[46:47]
	v_lshl_add_u64 v[52:53], v[56:57], 0, v[138:139]
	v_pk_mul_f32 v[46:47], s[34:35], v[40:41] op_sel_hi:[0,1]
	v_cvt_pk_bf16_f32 v40, v62, v63
	v_cvt_pk_bf16_f32 v41, v60, v61
	v_cvt_pk_bf16_f32 v42, v58, v59
	v_cvt_pk_bf16_f32 v43, v54, v55
	global_store_dwordx4 v[52:53], v[40:43], off sc1
	s_nop 1
	v_cvt_pk_bf16_f32 v40, v48, v49
	v_cvt_pk_bf16_f32 v41, v50, v51
	v_cvt_pk_bf16_f32 v42, v44, v45
	v_cvt_pk_bf16_f32 v43, v46, v47
	global_store_dwordx4 v[52:53], v[40:43], off offset:256 sc1
	s_nop 1
	v_add_u32_e32 v40, 0xa0, v148
	v_add_u32_e32 v41, s30, v40
	v_and_b32_e32 v41, 0xfff, v41
	v_cvt_f32_u32_e32 v48, v41
	v_mad_u64_u32 v[40:41], s[4:5], v40, s29, v[140:141]
	v_mul_f32_e32 v42, v20, v48
	v_mul_f32_e32 v43, 0.15915494, v42
	v_rndne_f32_e32 v43, v43
	v_fmac_f32_e32 v42, 0xc0c90000, v43
	v_fmac_f32_e32 v42, 0xbafdaa22, v43
	v_mul_f32_e32 v43, 0.15915494, v42
	v_sin_f32_e32 v42, v43
	v_cos_f32_e32 v44, v43
	v_mul_f32_e32 v43, v21, v48
	v_mul_f32_e32 v45, 0.15915494, v43
	v_rndne_f32_e32 v45, v45
	v_fmac_f32_e32 v43, 0xc0c90000, v45
	v_fmac_f32_e32 v43, 0xbafdaa22, v45
	v_mul_f32_e32 v45, 0.15915494, v43
	v_sin_f32_e32 v43, v45
	v_cos_f32_e32 v45, v45
	v_pk_mul_f32 v[46:47], v[36:37], v[42:43]
	v_pk_mul_f32 v[36:37], v[36:37], v[44:45]
	v_pk_fma_f32 v[46:47], v[32:33], v[44:45], v[46:47] neg_lo:[0,0,1] neg_hi:[0,0,1]
	v_pk_fma_f32 v[32:33], v[32:33], v[42:43], v[36:37]
	v_mul_f32_e32 v36, v22, v48
	v_mul_f32_e32 v37, 0.15915494, v36
	v_rndne_f32_e32 v37, v37
	v_fmac_f32_e32 v36, 0xc0c90000, v37
	v_fmac_f32_e32 v36, 0xbafdaa22, v37
	v_mul_f32_e32 v37, 0.15915494, v36
	v_sin_f32_e32 v36, v37
	v_cos_f32_e32 v42, v37
	v_mul_f32_e32 v37, v23, v48
	v_mul_f32_e32 v43, 0.15915494, v37
	v_rndne_f32_e32 v43, v43
	v_fmac_f32_e32 v37, 0xc0c90000, v43
	v_fmac_f32_e32 v37, 0xbafdaa22, v43
	v_mul_f32_e32 v43, 0.15915494, v37
	v_sin_f32_e32 v37, v43
	v_cos_f32_e32 v43, v43
	v_pk_mul_f32 v[46:47], s[34:35], v[46:47] op_sel_hi:[0,1]
	v_pk_mul_f32 v[32:33], s[34:35], v[32:33] op_sel_hi:[0,1]
	v_pk_mul_f32 v[44:45], v[38:39], v[36:37]
	v_pk_mul_f32 v[38:39], v[38:39], v[42:43]
	v_pk_fma_f32 v[44:45], v[34:35], v[42:43], v[44:45] neg_lo:[0,0,1] neg_hi:[0,0,1]
	v_pk_fma_f32 v[34:35], v[34:35], v[36:37], v[38:39]
	v_mul_f32_e32 v36, v8, v48
	v_mul_f32_e32 v37, 0.15915494, v36
	v_rndne_f32_e32 v37, v37
	v_fmac_f32_e32 v36, 0xc0c90000, v37
	v_fmac_f32_e32 v36, 0xbafdaa22, v37
	v_mul_f32_e32 v37, 0.15915494, v36
	v_sin_f32_e32 v36, v37
	v_cos_f32_e32 v38, v37
	v_mul_f32_e32 v37, v9, v48
	v_mul_f32_e32 v39, 0.15915494, v37
	v_rndne_f32_e32 v39, v39
	v_fmac_f32_e32 v37, 0xc0c90000, v39
	v_fmac_f32_e32 v37, 0xbafdaa22, v39
	v_mul_f32_e32 v39, 0.15915494, v37
	v_sin_f32_e32 v37, v39
	v_cos_f32_e32 v39, v39
	v_pk_mul_f32 v[44:45], s[34:35], v[44:45] op_sel_hi:[0,1]
	v_pk_mul_f32 v[34:35], s[34:35], v[34:35] op_sel_hi:[0,1]
	v_pk_mul_f32 v[42:43], v[28:29], v[36:37]
	v_pk_mul_f32 v[28:29], v[28:29], v[38:39]
	v_pk_fma_f32 v[42:43], v[24:25], v[38:39], v[42:43] neg_lo:[0,0,1] neg_hi:[0,0,1]
	v_pk_fma_f32 v[24:25], v[24:25], v[36:37], v[28:29]
	v_pk_mul_f32 v[42:43], s[34:35], v[42:43] op_sel_hi:[0,1]
	v_pk_mul_f32 v[28:29], s[34:35], v[24:25] op_sel_hi:[0,1]
	v_mul_f32_e32 v24, v10, v48
	v_mul_f32_e32 v25, 0.15915494, v24
	v_rndne_f32_e32 v25, v25
	v_fmac_f32_e32 v24, 0xc0c90000, v25
	v_fmac_f32_e32 v24, 0xbafdaa22, v25
	v_mul_f32_e32 v25, 0.15915494, v24
	v_sin_f32_e32 v24, v25
	v_cos_f32_e32 v36, v25
	v_mul_f32_e32 v25, v11, v48
	v_mul_f32_e32 v37, 0.15915494, v25
	v_rndne_f32_e32 v37, v37
	v_fmac_f32_e32 v25, 0xc0c90000, v37
	v_fmac_f32_e32 v25, 0xbafdaa22, v37
	v_mul_f32_e32 v37, 0.15915494, v25
	v_sin_f32_e32 v25, v37
	v_cos_f32_e32 v37, v37
	v_pk_mul_f32 v[38:39], v[30:31], v[24:25]
	s_nop 0
	v_pk_fma_f32 v[38:39], v[26:27], v[36:37], v[38:39] neg_lo:[0,0,1] neg_hi:[0,0,1]
	v_pk_mul_f32 v[30:31], v[30:31], v[36:37]
	v_pk_mul_f32 v[38:39], s[34:35], v[38:39] op_sel_hi:[0,1]
	v_pk_fma_f32 v[24:25], v[26:27], v[24:25], v[30:31]
	v_lshl_add_u64 v[36:37], v[40:41], 0, v[138:139]
	v_pk_mul_f32 v[30:31], s[34:35], v[24:25] op_sel_hi:[0,1]
	v_cvt_pk_bf16_f32 v24, v46, v47
	v_cvt_pk_bf16_f32 v25, v44, v45
	v_cvt_pk_bf16_f32 v26, v42, v43
	v_cvt_pk_bf16_f32 v27, v38, v39
	global_store_dwordx4 v[36:37], v[24:27], off sc1
	s_nop 1
	v_cvt_pk_bf16_f32 v24, v32, v33
	v_cvt_pk_bf16_f32 v25, v34, v35
	v_cvt_pk_bf16_f32 v26, v28, v29
	v_cvt_pk_bf16_f32 v27, v30, v31
	global_store_dwordx4 v[36:37], v[24:27], off offset:256 sc1
	s_nop 1
	v_add_u32_e32 v24, 0xb0, v148
	v_add_u32_e32 v25, s30, v24
	v_and_b32_e32 v25, 0xfff, v25
	v_cvt_f32_u32_e32 v30, v25
	v_mad_u64_u32 v[24:25], s[4:5], v24, s29, v[140:141]
	s_mov_b64 s[4:5], -1
	v_mul_f32_e32 v20, v20, v30
	v_mul_f32_e32 v21, v21, v30
	v_mul_f32_e32 v26, 0.15915494, v20
	v_mul_f32_e32 v27, 0.15915494, v21
	v_rndne_f32_e32 v26, v26
	v_rndne_f32_e32 v27, v27
	v_fmac_f32_e32 v20, 0xc0c90000, v26
	v_fmac_f32_e32 v21, 0xc0c90000, v27
	v_fmac_f32_e32 v20, 0xbafdaa22, v26
	v_fmac_f32_e32 v21, 0xbafdaa22, v27
	v_mul_f32_e32 v26, 0.15915494, v20
	v_mul_f32_e32 v27, 0.15915494, v21
	v_sin_f32_e32 v20, v26
	v_cos_f32_e32 v26, v26
	v_sin_f32_e32 v21, v27
	v_cos_f32_e32 v27, v27
	v_mul_f32_e32 v8, v8, v30
	v_mul_f32_e32 v9, v9, v30
	v_pk_mul_f32 v[28:29], v[16:17], v[20:21]
	v_pk_mul_f32 v[16:17], v[16:17], v[26:27]
	v_pk_fma_f32 v[28:29], v[12:13], v[26:27], v[28:29] neg_lo:[0,0,1] neg_hi:[0,0,1]
	v_pk_fma_f32 v[12:13], v[12:13], v[20:21], v[16:17]
	v_mul_f32_e32 v16, v22, v30
	v_mul_f32_e32 v17, 0.15915494, v16
	v_rndne_f32_e32 v17, v17
	v_fmac_f32_e32 v16, 0xc0c90000, v17
	v_fmac_f32_e32 v16, 0xbafdaa22, v17
	v_mul_f32_e32 v17, 0.15915494, v16
	v_sin_f32_e32 v16, v17
	v_cos_f32_e32 v20, v17
	v_mul_f32_e32 v17, v23, v30
	v_mul_f32_e32 v21, 0.15915494, v17
	v_rndne_f32_e32 v21, v21
	v_fmac_f32_e32 v17, 0xc0c90000, v21
	v_fmac_f32_e32 v17, 0xbafdaa22, v21
	v_mul_f32_e32 v21, 0.15915494, v17
	v_sin_f32_e32 v17, v21
	v_cos_f32_e32 v21, v21
	v_pk_mul_f32 v[28:29], s[34:35], v[28:29] op_sel_hi:[0,1]
	v_pk_mul_f32 v[12:13], s[34:35], v[12:13] op_sel_hi:[0,1]
	v_pk_mul_f32 v[22:23], v[18:19], v[16:17]
	v_pk_mul_f32 v[18:19], v[18:19], v[20:21]
	v_pk_fma_f32 v[22:23], v[14:15], v[20:21], v[22:23] neg_lo:[0,0,1] neg_hi:[0,0,1]
	v_pk_fma_f32 v[14:15], v[14:15], v[16:17], v[18:19]
	v_mul_f32_e32 v16, 0.15915494, v8
	v_mul_f32_e32 v17, 0.15915494, v9
	v_rndne_f32_e32 v16, v16
	v_rndne_f32_e32 v17, v17
	v_fmac_f32_e32 v8, 0xc0c90000, v16
	v_fmac_f32_e32 v9, 0xc0c90000, v17
	v_fmac_f32_e32 v8, 0xbafdaa22, v16
	v_fmac_f32_e32 v9, 0xbafdaa22, v17
	v_mul_f32_e32 v16, 0.15915494, v8
	v_mul_f32_e32 v17, 0.15915494, v9
	v_sin_f32_e32 v8, v16
	v_cos_f32_e32 v16, v16
	v_sin_f32_e32 v9, v17
	v_cos_f32_e32 v17, v17
	v_pk_mul_f32 v[22:23], s[34:35], v[22:23] op_sel_hi:[0,1]
	v_pk_mul_f32 v[14:15], s[34:35], v[14:15] op_sel_hi:[0,1]
	v_pk_mul_f32 v[18:19], v[4:5], v[8:9]
	v_pk_mul_f32 v[4:5], v[4:5], v[16:17]
	v_pk_fma_f32 v[18:19], v[0:1], v[16:17], v[18:19] neg_lo:[0,0,1] neg_hi:[0,0,1]
	v_pk_fma_f32 v[0:1], v[0:1], v[8:9], v[4:5]
	v_pk_mul_f32 v[18:19], s[34:35], v[18:19] op_sel_hi:[0,1]
	v_pk_mul_f32 v[4:5], s[34:35], v[0:1] op_sel_hi:[0,1]
	v_mul_f32_e32 v0, v10, v30
	v_mul_f32_e32 v1, 0.15915494, v0
	v_rndne_f32_e32 v1, v1
	v_fmac_f32_e32 v0, 0xc0c90000, v1
	v_fmac_f32_e32 v0, 0xbafdaa22, v1
	v_mul_f32_e32 v1, 0.15915494, v0
	v_sin_f32_e32 v0, v1
	v_cos_f32_e32 v8, v1
	v_mul_f32_e32 v1, v11, v30
	v_mul_f32_e32 v9, 0.15915494, v1
	v_rndne_f32_e32 v9, v9
	v_fmac_f32_e32 v1, 0xc0c90000, v9
	v_fmac_f32_e32 v1, 0xbafdaa22, v9
	v_mul_f32_e32 v9, 0.15915494, v1
	v_sin_f32_e32 v1, v9
	v_cos_f32_e32 v9, v9
	s_andn2_b64 vcc, exec, s[36:37]
	v_pk_mul_f32 v[10:11], v[6:7], v[0:1]
	s_nop 0
	v_pk_fma_f32 v[10:11], v[2:3], v[8:9], v[10:11] neg_lo:[0,0,1] neg_hi:[0,0,1]
	v_pk_mul_f32 v[6:7], v[6:7], v[8:9]
	v_pk_mul_f32 v[10:11], s[34:35], v[10:11] op_sel_hi:[0,1]
	v_pk_fma_f32 v[0:1], v[2:3], v[0:1], v[6:7]
	v_lshl_add_u64 v[8:9], v[24:25], 0, v[138:139]
	v_pk_mul_f32 v[6:7], s[34:35], v[0:1] op_sel_hi:[0,1]
	v_cvt_pk_bf16_f32 v0, v28, v29
	v_cvt_pk_bf16_f32 v1, v22, v23
	v_cvt_pk_bf16_f32 v2, v18, v19
	v_cvt_pk_bf16_f32 v3, v10, v11
	global_store_dwordx4 v[8:9], v[0:3], off sc1
	s_nop 1
	v_cvt_pk_bf16_f32 v0, v12, v13
	v_cvt_pk_bf16_f32 v1, v14, v15
	v_cvt_pk_bf16_f32 v2, v4, v5
	v_cvt_pk_bf16_f32 v3, v6, v7
	global_store_dwordx4 v[8:9], v[0:3], off offset:256 sc1
	s_cbranch_vccnz .LBB0_271
	s_andn2_b64 vcc, exec, s[16:17]
	s_cbranch_vccnz .LBB0_270
	s_barrier
	s_branch .LBB0_270

.LBB0_300:
	v_mbcnt_lo_u32_b32 v130, -1, 0
	v_mbcnt_hi_u32_b32 v130, -1, v130
	s_nop 0
	v_and_or_b32 v142, v130, 15, s3
	v_ashrrev_i32_e32 v130, 1, v130
	v_and_b32_e32 v130, -8, v130
	v_add_u32_e32 v130, s52, v130
	v_ashrrev_i32_e32 v131, 31, v130
	v_lshlrev_b64 v[130:131], 1, v[130:131]
	v_pk_mul_f32 v[124:125], s[18:19], v[124:125] op_sel_hi:[0,1]
	v_mul_f32_e32 v143, 0xbfb8aa3b, v124
	v_exp_f32_e32 v143, v143
	v_pk_mul_f32 v[126:127], s[18:19], v[126:127] op_sel_hi:[0,1]
	v_pk_mul_f32 v[120:121], s[18:19], v[120:121] op_sel_hi:[0,1]
	v_mov_b64_e32 v[132:133], s[40:41]
	v_add_f32_e32 v143, 1.0, v143
	v_rcp_f32_e32 v144, v143
	v_mul_f32_e32 v143, 0xbfb8aa3b, v125
	v_exp_f32_e32 v143, v143
	v_mad_u64_u32 v[134:135], s[4:5], v142, s31, v[132:133]
	v_lshl_add_u64 v[134:135], v[134:135], 0, v[130:131]
	v_add_f32_e32 v143, 1.0, v143
	v_rcp_f32_e32 v145, v143
	v_mul_f32_e32 v143, 0xbfb8aa3b, v126
	v_exp_f32_e32 v143, v143
	v_pk_mul_f32 v[116:117], s[18:19], v[116:117] op_sel_hi:[0,1]
	v_pk_mul_f32 v[124:125], v[124:125], v[144:145]
	v_pk_mul_f32 v[118:119], s[18:19], v[118:119] op_sel_hi:[0,1]
	v_add_f32_e32 v143, 1.0, v143
	v_rcp_f32_e32 v144, v143
	v_mul_f32_e32 v143, 0xbfb8aa3b, v127
	v_exp_f32_e32 v143, v143
	v_pk_mul_f32 v[112:113], s[18:19], v[112:113] op_sel_hi:[0,1]
	v_add_f32_e32 v143, 1.0, v143
	v_rcp_f32_e32 v145, v143
	v_mul_f32_e32 v143, 0xbfb8aa3b, v120
	v_exp_f32_e32 v143, v143
	v_pk_mul_f32 v[126:127], v[126:127], v[144:145]
	v_add_f32_e32 v143, 1.0, v143
	v_rcp_f32_e32 v144, v143
	v_mul_f32_e32 v143, 0xbfb8aa3b, v121
	v_exp_f32_e32 v143, v143
	s_nop 0
	v_add_f32_e32 v143, 1.0, v143
	v_rcp_f32_e32 v145, v143
	s_nop 0
	v_pk_mul_f32 v[144:145], v[120:121], v[144:145]
	v_pk_mul_f32 v[120:121], s[18:19], v[122:123] op_sel_hi:[0,1]
	v_mul_f32_e32 v122, 0xbfb8aa3b, v120
	v_mul_f32_e32 v123, 0xbfb8aa3b, v121
	v_exp_f32_e32 v122, v122
	v_exp_f32_e32 v123, v123
	v_add_f32_e32 v122, 1.0, v122
	v_add_f32_e32 v123, 1.0, v123
	v_rcp_f32_e32 v122, v122
	v_rcp_f32_e32 v123, v123
	s_nop 0
	v_pk_mul_f32 v[146:147], v[120:121], v[122:123]
	v_cvt_pk_bf16_f32 v120, v124, v125
	v_cvt_pk_bf16_f32 v121, v126, v127
	v_cvt_pk_bf16_f32 v122, v144, v145
	v_cvt_pk_bf16_f32 v123, v146, v147
	global_store_dwordx4 v[134:135], v[120:123], off sc1
	s_nop 1
	v_mul_f32_e32 v120, 0xbfb8aa3b, v116
	v_mul_f32_e32 v121, 0xbfb8aa3b, v117
	v_exp_f32_e32 v120, v120
	v_exp_f32_e32 v121, v121
	v_add_f32_e32 v120, 1.0, v120
	v_add_f32_e32 v121, 1.0, v121
	v_rcp_f32_e32 v120, v120
	v_rcp_f32_e32 v121, v121
	s_nop 0
	v_pk_mul_f32 v[116:117], v[116:117], v[120:121]
	v_mul_f32_e32 v120, 0xbfb8aa3b, v118
	v_mul_f32_e32 v121, 0xbfb8aa3b, v119
	v_exp_f32_e32 v120, v120
	v_exp_f32_e32 v121, v121
	v_add_f32_e32 v120, 1.0, v120
	v_add_f32_e32 v121, 1.0, v121
	v_rcp_f32_e32 v120, v120
	v_rcp_f32_e32 v121, v121
	s_nop 0
	v_pk_mul_f32 v[118:119], v[118:119], v[120:121]
	v_mul_f32_e32 v120, 0xbfb8aa3b, v112
	v_mul_f32_e32 v121, 0xbfb8aa3b, v113
	v_exp_f32_e32 v120, v120
	v_exp_f32_e32 v121, v121
	v_add_f32_e32 v120, 1.0, v120
	v_add_f32_e32 v121, 1.0, v121
	v_rcp_f32_e32 v120, v120
	v_rcp_f32_e32 v121, v121
	s_nop 0
	v_pk_mul_f32 v[120:121], v[112:113], v[120:121]
	v_pk_mul_f32 v[112:113], s[18:19], v[114:115] op_sel_hi:[0,1]
	v_mul_f32_e32 v114, 0xbfb8aa3b, v112
	v_mul_f32_e32 v115, 0xbfb8aa3b, v113
	v_exp_f32_e32 v114, v114
	v_exp_f32_e32 v115, v115
	v_add_f32_e32 v114, 1.0, v114
	v_add_f32_e32 v115, 1.0, v115
	v_rcp_f32_e32 v114, v114
	v_rcp_f32_e32 v115, v115
	s_nop 0
	v_pk_mul_f32 v[122:123], v[112:113], v[114:115]
	v_cvt_pk_bf16_f32 v112, v116, v117
	v_cvt_pk_bf16_f32 v113, v118, v119
	v_cvt_pk_bf16_f32 v114, v120, v121
	v_cvt_pk_bf16_f32 v115, v122, v123
	global_store_dwordx4 v[134:135], v[112:115], off offset:256 sc1
	v_pk_mul_f32 v[108:109], s[18:19], v[108:109] op_sel_hi:[0,1]
	s_nop 0
	v_mul_f32_e32 v114, 0xbfb8aa3b, v108
	v_mul_f32_e32 v115, 0xbfb8aa3b, v109
	v_exp_f32_e32 v114, v114
	v_exp_f32_e32 v115, v115
	v_pk_mul_f32 v[110:111], s[18:19], v[110:111] op_sel_hi:[0,1]
	v_pk_mul_f32 v[104:105], s[18:19], v[104:105] op_sel_hi:[0,1]
	v_add_f32_e32 v114, 1.0, v114
	v_add_f32_e32 v115, 1.0, v115
	v_rcp_f32_e32 v114, v114
	v_rcp_f32_e32 v115, v115
	v_or_b32_e32 v112, 16, v142
	v_mad_u64_u32 v[112:113], s[4:5], v112, s31, v[132:133]
	v_pk_mul_f32 v[108:109], v[108:109], v[114:115]
	v_mul_f32_e32 v114, 0xbfb8aa3b, v110
	v_mul_f32_e32 v115, 0xbfb8aa3b, v111
	v_exp_f32_e32 v114, v114
	v_exp_f32_e32 v115, v115
	v_lshl_add_u64 v[112:113], v[112:113], 0, v[130:131]
	v_pk_mul_f32 v[100:101], s[18:19], v[100:101] op_sel_hi:[0,1]
	v_add_f32_e32 v114, 1.0, v114
	v_add_f32_e32 v115, 1.0, v115
	v_rcp_f32_e32 v114, v114
	v_rcp_f32_e32 v115, v115
	v_pk_mul_f32 v[102:103], s[18:19], v[102:103] op_sel_hi:[0,1]
	v_pk_mul_f32 v[96:97], s[18:19], v[96:97] op_sel_hi:[0,1]
	v_pk_mul_f32 v[110:111], v[110:111], v[114:115]
	v_mul_f32_e32 v114, 0xbfb8aa3b, v104
	v_mul_f32_e32 v115, 0xbfb8aa3b, v105
	v_exp_f32_e32 v114, v114
	v_exp_f32_e32 v115, v115
	v_add_f32_e32 v114, 1.0, v114
	v_add_f32_e32 v115, 1.0, v115
	v_rcp_f32_e32 v114, v114
	v_rcp_f32_e32 v115, v115
	s_nop 0
	v_pk_mul_f32 v[114:115], v[104:105], v[114:115]
	v_pk_mul_f32 v[104:105], s[18:19], v[106:107] op_sel_hi:[0,1]
	v_mul_f32_e32 v106, 0xbfb8aa3b, v104
	v_mul_f32_e32 v107, 0xbfb8aa3b, v105
	v_exp_f32_e32 v106, v106
	v_exp_f32_e32 v107, v107
	v_add_f32_e32 v106, 1.0, v106
	v_add_f32_e32 v107, 1.0, v107
	v_rcp_f32_e32 v106, v106
	v_rcp_f32_e32 v107, v107
	s_nop 0
	v_pk_mul_f32 v[116:117], v[104:105], v[106:107]
	v_cvt_pk_bf16_f32 v104, v108, v109
	v_cvt_pk_bf16_f32 v105, v110, v111
	v_cvt_pk_bf16_f32 v106, v114, v115
	v_cvt_pk_bf16_f32 v107, v116, v117
	global_store_dwordx4 v[112:113], v[104:107], off sc1
	s_nop 1
	v_mul_f32_e32 v104, 0xbfb8aa3b, v100
	v_mul_f32_e32 v105, 0xbfb8aa3b, v101
	v_exp_f32_e32 v104, v104
	v_exp_f32_e32 v105, v105
	v_add_f32_e32 v104, 1.0, v104
	v_add_f32_e32 v105, 1.0, v105
	v_rcp_f32_e32 v104, v104
	v_rcp_f32_e32 v105, v105
	s_nop 0
	v_pk_mul_f32 v[100:101], v[100:101], v[104:105]
	v_mul_f32_e32 v104, 0xbfb8aa3b, v102
	v_mul_f32_e32 v105, 0xbfb8aa3b, v103
	v_exp_f32_e32 v104, v104
	v_exp_f32_e32 v105, v105
	v_add_f32_e32 v104, 1.0, v104
	v_add_f32_e32 v105, 1.0, v105
	v_rcp_f32_e32 v104, v104
	v_rcp_f32_e32 v105, v105
	s_nop 0
	v_pk_mul_f32 v[102:103], v[102:103], v[104:105]
	v_mul_f32_e32 v104, 0xbfb8aa3b, v96
	v_mul_f32_e32 v105, 0xbfb8aa3b, v97
	v_exp_f32_e32 v104, v104
	v_exp_f32_e32 v105, v105
	v_add_f32_e32 v104, 1.0, v104
	v_add_f32_e32 v105, 1.0, v105
	v_rcp_f32_e32 v104, v104
	v_rcp_f32_e32 v105, v105
	s_nop 0
	v_pk_mul_f32 v[104:105], v[96:97], v[104:105]
	v_pk_mul_f32 v[96:97], s[18:19], v[98:99] op_sel_hi:[0,1]
	v_mul_f32_e32 v98, 0xbfb8aa3b, v96
	v_mul_f32_e32 v99, 0xbfb8aa3b, v97
	v_exp_f32_e32 v98, v98
	v_exp_f32_e32 v99, v99
	v_add_f32_e32 v98, 1.0, v98
	v_add_f32_e32 v99, 1.0, v99
	v_rcp_f32_e32 v98, v98
	v_rcp_f32_e32 v99, v99
	s_nop 0
	v_pk_mul_f32 v[106:107], v[96:97], v[98:99]
	v_cvt_pk_bf16_f32 v96, v100, v101
	v_cvt_pk_bf16_f32 v97, v102, v103
	v_cvt_pk_bf16_f32 v98, v104, v105
	v_cvt_pk_bf16_f32 v99, v106, v107
	global_store_dwordx4 v[112:113], v[96:99], off offset:256 sc1
	v_pk_mul_f32 v[92:93], s[18:19], v[92:93] op_sel_hi:[0,1]
	s_nop 0
	v_mul_f32_e32 v98, 0xbfb8aa3b, v92
	v_mul_f32_e32 v99, 0xbfb8aa3b, v93
	v_exp_f32_e32 v98, v98
	v_exp_f32_e32 v99, v99
	v_pk_mul_f32 v[94:95], s[18:19], v[94:95] op_sel_hi:[0,1]
	v_pk_mul_f32 v[88:89], s[18:19], v[88:89] op_sel_hi:[0,1]
	v_add_f32_e32 v98, 1.0, v98
	v_add_f32_e32 v99, 1.0, v99
	v_rcp_f32_e32 v98, v98
	v_rcp_f32_e32 v99, v99
	v_or_b32_e32 v96, 32, v142
	v_mad_u64_u32 v[96:97], s[4:5], v96, s31, v[132:133]
	v_pk_mul_f32 v[92:93], v[92:93], v[98:99]
	v_mul_f32_e32 v98, 0xbfb8aa3b, v94
	v_mul_f32_e32 v99, 0xbfb8aa3b, v95
	v_exp_f32_e32 v98, v98
	v_exp_f32_e32 v99, v99
	v_lshl_add_u64 v[96:97], v[96:97], 0, v[130:131]
	v_pk_mul_f32 v[84:85], s[18:19], v[84:85] op_sel_hi:[0,1]
	v_add_f32_e32 v98, 1.0, v98
	v_add_f32_e32 v99, 1.0, v99
	v_rcp_f32_e32 v98, v98
	v_rcp_f32_e32 v99, v99
	v_pk_mul_f32 v[86:87], s[18:19], v[86:87] op_sel_hi:[0,1]
	v_pk_mul_f32 v[80:81], s[18:19], v[80:81] op_sel_hi:[0,1]
	v_pk_mul_f32 v[94:95], v[94:95], v[98:99]
	v_mul_f32_e32 v98, 0xbfb8aa3b, v88
	v_mul_f32_e32 v99, 0xbfb8aa3b, v89
	v_exp_f32_e32 v98, v98
	v_exp_f32_e32 v99, v99
	v_add_f32_e32 v98, 1.0, v98
	v_add_f32_e32 v99, 1.0, v99
	v_rcp_f32_e32 v98, v98
	v_rcp_f32_e32 v99, v99
	s_nop 0
	v_pk_mul_f32 v[98:99], v[88:89], v[98:99]
	v_pk_mul_f32 v[88:89], s[18:19], v[90:91] op_sel_hi:[0,1]
	v_mul_f32_e32 v90, 0xbfb8aa3b, v88
	v_mul_f32_e32 v91, 0xbfb8aa3b, v89
	v_exp_f32_e32 v90, v90
	v_exp_f32_e32 v91, v91
	v_add_f32_e32 v90, 1.0, v90
	v_add_f32_e32 v91, 1.0, v91
	v_rcp_f32_e32 v90, v90
	v_rcp_f32_e32 v91, v91
	s_nop 0
	v_pk_mul_f32 v[100:101], v[88:89], v[90:91]
	v_cvt_pk_bf16_f32 v88, v92, v93
	v_cvt_pk_bf16_f32 v89, v94, v95
	v_cvt_pk_bf16_f32 v90, v98, v99
	v_cvt_pk_bf16_f32 v91, v100, v101
	global_store_dwordx4 v[96:97], v[88:91], off sc1
	s_nop 1
	v_mul_f32_e32 v88, 0xbfb8aa3b, v84
	v_mul_f32_e32 v89, 0xbfb8aa3b, v85
	v_exp_f32_e32 v88, v88
	v_exp_f32_e32 v89, v89
	v_add_f32_e32 v88, 1.0, v88
	v_add_f32_e32 v89, 1.0, v89
	v_rcp_f32_e32 v88, v88
	v_rcp_f32_e32 v89, v89
	s_nop 0
	v_pk_mul_f32 v[84:85], v[84:85], v[88:89]
	v_mul_f32_e32 v88, 0xbfb8aa3b, v86
	v_mul_f32_e32 v89, 0xbfb8aa3b, v87
	v_exp_f32_e32 v88, v88
	v_exp_f32_e32 v89, v89
	v_add_f32_e32 v88, 1.0, v88
	v_add_f32_e32 v89, 1.0, v89
	v_rcp_f32_e32 v88, v88
	v_rcp_f32_e32 v89, v89
	s_nop 0
	v_pk_mul_f32 v[86:87], v[86:87], v[88:89]
	v_mul_f32_e32 v88, 0xbfb8aa3b, v80
	v_mul_f32_e32 v89, 0xbfb8aa3b, v81
	v_exp_f32_e32 v88, v88
	v_exp_f32_e32 v89, v89
	v_add_f32_e32 v88, 1.0, v88
	v_add_f32_e32 v89, 1.0, v89
	v_rcp_f32_e32 v88, v88
	v_rcp_f32_e32 v89, v89
	s_nop 0
	v_pk_mul_f32 v[88:89], v[80:81], v[88:89]
	v_pk_mul_f32 v[80:81], s[18:19], v[82:83] op_sel_hi:[0,1]
	v_mul_f32_e32 v82, 0xbfb8aa3b, v80
	v_mul_f32_e32 v83, 0xbfb8aa3b, v81
	v_exp_f32_e32 v82, v82
	v_exp_f32_e32 v83, v83
	v_add_f32_e32 v82, 1.0, v82
	v_add_f32_e32 v83, 1.0, v83
	v_rcp_f32_e32 v82, v82
	v_rcp_f32_e32 v83, v83
	s_nop 0
	v_pk_mul_f32 v[90:91], v[80:81], v[82:83]
	v_cvt_pk_bf16_f32 v80, v84, v85
	v_cvt_pk_bf16_f32 v81, v86, v87
	v_cvt_pk_bf16_f32 v82, v88, v89
	v_cvt_pk_bf16_f32 v83, v90, v91
	global_store_dwordx4 v[96:97], v[80:83], off offset:256 sc1
	v_pk_mul_f32 v[76:77], s[18:19], v[76:77] op_sel_hi:[0,1]
	s_nop 0
	v_mul_f32_e32 v82, 0xbfb8aa3b, v76
	v_mul_f32_e32 v83, 0xbfb8aa3b, v77
	v_exp_f32_e32 v82, v82
	v_exp_f32_e32 v83, v83
	v_pk_mul_f32 v[78:79], s[18:19], v[78:79] op_sel_hi:[0,1]
	v_pk_mul_f32 v[72:73], s[18:19], v[72:73] op_sel_hi:[0,1]
	v_add_f32_e32 v82, 1.0, v82
	v_add_f32_e32 v83, 1.0, v83
	v_rcp_f32_e32 v82, v82
	v_rcp_f32_e32 v83, v83
	v_or_b32_e32 v80, 48, v142
	v_mad_u64_u32 v[80:81], s[4:5], v80, s31, v[132:133]
	v_pk_mul_f32 v[76:77], v[76:77], v[82:83]
	v_mul_f32_e32 v82, 0xbfb8aa3b, v78
	v_mul_f32_e32 v83, 0xbfb8aa3b, v79
	v_exp_f32_e32 v82, v82
	v_exp_f32_e32 v83, v83
	v_lshl_add_u64 v[80:81], v[80:81], 0, v[130:131]
	v_pk_mul_f32 v[68:69], s[18:19], v[68:69] op_sel_hi:[0,1]
	v_add_f32_e32 v82, 1.0, v82
	v_add_f32_e32 v83, 1.0, v83
	v_rcp_f32_e32 v82, v82
	v_rcp_f32_e32 v83, v83
	v_pk_mul_f32 v[70:71], s[18:19], v[70:71] op_sel_hi:[0,1]
	v_pk_mul_f32 v[64:65], s[18:19], v[64:65] op_sel_hi:[0,1]
	v_pk_mul_f32 v[78:79], v[78:79], v[82:83]
	v_mul_f32_e32 v82, 0xbfb8aa3b, v72
	v_mul_f32_e32 v83, 0xbfb8aa3b, v73
	v_exp_f32_e32 v82, v82
	v_exp_f32_e32 v83, v83
	v_add_f32_e32 v82, 1.0, v82
	v_add_f32_e32 v83, 1.0, v83
	v_rcp_f32_e32 v82, v82
	v_rcp_f32_e32 v83, v83
	s_nop 0
	v_pk_mul_f32 v[82:83], v[72:73], v[82:83]
	v_pk_mul_f32 v[72:73], s[18:19], v[74:75] op_sel_hi:[0,1]
	v_mul_f32_e32 v74, 0xbfb8aa3b, v72
	v_mul_f32_e32 v75, 0xbfb8aa3b, v73
	v_exp_f32_e32 v74, v74
	v_exp_f32_e32 v75, v75
	v_add_f32_e32 v74, 1.0, v74
	v_add_f32_e32 v75, 1.0, v75
	v_rcp_f32_e32 v74, v74
	v_rcp_f32_e32 v75, v75
	s_nop 0
	v_pk_mul_f32 v[84:85], v[72:73], v[74:75]
	v_cvt_pk_bf16_f32 v72, v76, v77
	v_cvt_pk_bf16_f32 v73, v78, v79
	v_cvt_pk_bf16_f32 v74, v82, v83
	v_cvt_pk_bf16_f32 v75, v84, v85
	global_store_dwordx4 v[80:81], v[72:75], off sc1
	s_nop 1
	v_mul_f32_e32 v72, 0xbfb8aa3b, v68
	v_mul_f32_e32 v73, 0xbfb8aa3b, v69
	v_exp_f32_e32 v72, v72
	v_exp_f32_e32 v73, v73
	v_add_f32_e32 v72, 1.0, v72
	v_add_f32_e32 v73, 1.0, v73
	v_rcp_f32_e32 v72, v72
	v_rcp_f32_e32 v73, v73
	s_nop 0
	v_pk_mul_f32 v[68:69], v[68:69], v[72:73]
	v_mul_f32_e32 v72, 0xbfb8aa3b, v70
	v_mul_f32_e32 v73, 0xbfb8aa3b, v71
	v_exp_f32_e32 v72, v72
	v_exp_f32_e32 v73, v73
	v_add_f32_e32 v72, 1.0, v72
	v_add_f32_e32 v73, 1.0, v73
	v_rcp_f32_e32 v72, v72
	v_rcp_f32_e32 v73, v73
	s_nop 0
	v_pk_mul_f32 v[70:71], v[70:71], v[72:73]
	v_mul_f32_e32 v72, 0xbfb8aa3b, v64
	v_mul_f32_e32 v73, 0xbfb8aa3b, v65
	v_exp_f32_e32 v72, v72
	v_exp_f32_e32 v73, v73
	v_add_f32_e32 v72, 1.0, v72
	v_add_f32_e32 v73, 1.0, v73
	v_rcp_f32_e32 v72, v72
	v_rcp_f32_e32 v73, v73
	s_nop 0
	v_pk_mul_f32 v[72:73], v[64:65], v[72:73]
	v_pk_mul_f32 v[64:65], s[18:19], v[66:67] op_sel_hi:[0,1]
	v_mul_f32_e32 v66, 0xbfb8aa3b, v64
	v_mul_f32_e32 v67, 0xbfb8aa3b, v65
	v_exp_f32_e32 v66, v66
	v_exp_f32_e32 v67, v67
	v_add_f32_e32 v66, 1.0, v66
	v_add_f32_e32 v67, 1.0, v67
	v_rcp_f32_e32 v66, v66
	v_rcp_f32_e32 v67, v67
	s_nop 0
	v_pk_mul_f32 v[74:75], v[64:65], v[66:67]
	v_cvt_pk_bf16_f32 v64, v68, v69
	v_cvt_pk_bf16_f32 v65, v70, v71
	v_cvt_pk_bf16_f32 v66, v72, v73
	v_cvt_pk_bf16_f32 v67, v74, v75
	global_store_dwordx4 v[80:81], v[64:67], off offset:256 sc1
	s_nop 1
	v_add_u32_e32 v64, 0x80, v142
	v_pk_mul_f32 v[60:61], s[18:19], v[60:61] op_sel_hi:[0,1]
	v_mul_f32_e32 v66, 0xbfb8aa3b, v60
	v_mul_f32_e32 v67, 0xbfb8aa3b, v61
	v_exp_f32_e32 v66, v66
	v_exp_f32_e32 v67, v67
	v_pk_mul_f32 v[62:63], s[18:19], v[62:63] op_sel_hi:[0,1]
	v_pk_mul_f32 v[56:57], s[18:19], v[56:57] op_sel_hi:[0,1]
	v_add_f32_e32 v66, 1.0, v66
	v_add_f32_e32 v67, 1.0, v67
	v_rcp_f32_e32 v66, v66
	v_rcp_f32_e32 v67, v67
	v_mad_u64_u32 v[64:65], s[4:5], v64, s31, v[132:133]
	v_lshl_add_u64 v[64:65], v[64:65], 0, v[130:131]
	v_pk_mul_f32 v[60:61], v[60:61], v[66:67]
	v_mul_f32_e32 v66, 0xbfb8aa3b, v62
	v_mul_f32_e32 v67, 0xbfb8aa3b, v63
	v_exp_f32_e32 v66, v66
	v_exp_f32_e32 v67, v67
	v_pk_mul_f32 v[52:53], s[18:19], v[52:53] op_sel_hi:[0,1]
	v_pk_mul_f32 v[54:55], s[18:19], v[54:55] op_sel_hi:[0,1]
	v_add_f32_e32 v66, 1.0, v66
	v_add_f32_e32 v67, 1.0, v67
	v_rcp_f32_e32 v66, v66
	v_rcp_f32_e32 v67, v67
	v_pk_mul_f32 v[48:49], s[18:19], v[48:49] op_sel_hi:[0,1]
	v_pk_mul_f32 v[62:63], v[62:63], v[66:67]
	v_mul_f32_e32 v66, 0xbfb8aa3b, v56
	v_mul_f32_e32 v67, 0xbfb8aa3b, v57
	v_exp_f32_e32 v66, v66
	v_exp_f32_e32 v67, v67
	v_add_f32_e32 v66, 1.0, v66
	v_add_f32_e32 v67, 1.0, v67
	v_rcp_f32_e32 v66, v66
	v_rcp_f32_e32 v67, v67
	s_nop 0
	v_pk_mul_f32 v[66:67], v[56:57], v[66:67]
	v_pk_mul_f32 v[56:57], s[18:19], v[58:59] op_sel_hi:[0,1]
	v_mul_f32_e32 v58, 0xbfb8aa3b, v56
	v_mul_f32_e32 v59, 0xbfb8aa3b, v57
	v_exp_f32_e32 v58, v58
	v_exp_f32_e32 v59, v59
	v_add_f32_e32 v58, 1.0, v58
	v_add_f32_e32 v59, 1.0, v59
	v_rcp_f32_e32 v58, v58
	v_rcp_f32_e32 v59, v59
	s_nop 0
	v_pk_mul_f32 v[68:69], v[56:57], v[58:59]
	v_cvt_pk_bf16_f32 v56, v60, v61
	v_cvt_pk_bf16_f32 v57, v62, v63
	v_cvt_pk_bf16_f32 v58, v66, v67
	v_cvt_pk_bf16_f32 v59, v68, v69
	global_store_dwordx4 v[64:65], v[56:59], off sc1
	s_nop 1
	v_mul_f32_e32 v56, 0xbfb8aa3b, v52
	v_mul_f32_e32 v57, 0xbfb8aa3b, v53
	v_exp_f32_e32 v56, v56
	v_exp_f32_e32 v57, v57
	v_add_f32_e32 v56, 1.0, v56
	v_add_f32_e32 v57, 1.0, v57
	v_rcp_f32_e32 v56, v56
	v_rcp_f32_e32 v57, v57
	s_nop 0
	v_pk_mul_f32 v[52:53], v[52:53], v[56:57]
	v_mul_f32_e32 v56, 0xbfb8aa3b, v54
	v_mul_f32_e32 v57, 0xbfb8aa3b, v55
	v_exp_f32_e32 v56, v56
	v_exp_f32_e32 v57, v57
	v_add_f32_e32 v56, 1.0, v56
	v_add_f32_e32 v57, 1.0, v57
	v_rcp_f32_e32 v56, v56
	v_rcp_f32_e32 v57, v57
	s_nop 0
	v_pk_mul_f32 v[54:55], v[54:55], v[56:57]
	v_mul_f32_e32 v56, 0xbfb8aa3b, v48
	v_mul_f32_e32 v57, 0xbfb8aa3b, v49
	v_exp_f32_e32 v56, v56
	v_exp_f32_e32 v57, v57
	v_add_f32_e32 v56, 1.0, v56
	v_add_f32_e32 v57, 1.0, v57
	v_rcp_f32_e32 v56, v56
	v_rcp_f32_e32 v57, v57
	s_nop 0
	v_pk_mul_f32 v[56:57], v[48:49], v[56:57]
	v_pk_mul_f32 v[48:49], s[18:19], v[50:51] op_sel_hi:[0,1]
	v_mul_f32_e32 v50, 0xbfb8aa3b, v48
	v_mul_f32_e32 v51, 0xbfb8aa3b, v49
	v_exp_f32_e32 v50, v50
	v_exp_f32_e32 v51, v51
	v_add_f32_e32 v50, 1.0, v50
	v_add_f32_e32 v51, 1.0, v51
	v_rcp_f32_e32 v50, v50
	v_rcp_f32_e32 v51, v51
	s_nop 0
	v_pk_mul_f32 v[58:59], v[48:49], v[50:51]
	v_cvt_pk_bf16_f32 v48, v52, v53
	v_cvt_pk_bf16_f32 v49, v54, v55
	v_cvt_pk_bf16_f32 v50, v56, v57
	v_cvt_pk_bf16_f32 v51, v58, v59
	global_store_dwordx4 v[64:65], v[48:51], off offset:256 sc1
	v_pk_mul_f32 v[44:45], s[18:19], v[44:45] op_sel_hi:[0,1]
	s_nop 0
	v_mul_f32_e32 v50, 0xbfb8aa3b, v44
	v_mul_f32_e32 v51, 0xbfb8aa3b, v45
	v_exp_f32_e32 v50, v50
	v_exp_f32_e32 v51, v51
	v_pk_mul_f32 v[46:47], s[18:19], v[46:47] op_sel_hi:[0,1]
	v_pk_mul_f32 v[40:41], s[18:19], v[40:41] op_sel_hi:[0,1]
	v_add_f32_e32 v50, 1.0, v50
	v_add_f32_e32 v51, 1.0, v51
	v_rcp_f32_e32 v50, v50
	v_rcp_f32_e32 v51, v51
	v_add_u32_e32 v48, 0x90, v142
	v_mad_u64_u32 v[48:49], s[4:5], v48, s31, v[132:133]
	v_pk_mul_f32 v[44:45], v[44:45], v[50:51]
	v_mul_f32_e32 v50, 0xbfb8aa3b, v46
	v_mul_f32_e32 v51, 0xbfb8aa3b, v47
	v_exp_f32_e32 v50, v50
	v_exp_f32_e32 v51, v51
	v_lshl_add_u64 v[48:49], v[48:49], 0, v[130:131]
	v_pk_mul_f32 v[36:37], s[18:19], v[36:37] op_sel_hi:[0,1]
	v_add_f32_e32 v50, 1.0, v50
	v_add_f32_e32 v51, 1.0, v51
	v_rcp_f32_e32 v50, v50
	v_rcp_f32_e32 v51, v51
	v_pk_mul_f32 v[38:39], s[18:19], v[38:39] op_sel_hi:[0,1]
	v_pk_mul_f32 v[32:33], s[18:19], v[32:33] op_sel_hi:[0,1]
	v_pk_mul_f32 v[46:47], v[46:47], v[50:51]
	v_mul_f32_e32 v50, 0xbfb8aa3b, v40
	v_mul_f32_e32 v51, 0xbfb8aa3b, v41
	v_exp_f32_e32 v50, v50
	v_exp_f32_e32 v51, v51
	v_add_f32_e32 v50, 1.0, v50
	v_add_f32_e32 v51, 1.0, v51
	v_rcp_f32_e32 v50, v50
	v_rcp_f32_e32 v51, v51
	s_nop 0
	v_pk_mul_f32 v[50:51], v[40:41], v[50:51]
	v_pk_mul_f32 v[40:41], s[18:19], v[42:43] op_sel_hi:[0,1]
	v_mul_f32_e32 v42, 0xbfb8aa3b, v40
	v_mul_f32_e32 v43, 0xbfb8aa3b, v41
	v_exp_f32_e32 v42, v42
	v_exp_f32_e32 v43, v43
	v_add_f32_e32 v42, 1.0, v42
	v_add_f32_e32 v43, 1.0, v43
	v_rcp_f32_e32 v42, v42
	v_rcp_f32_e32 v43, v43
	s_nop 0
	v_pk_mul_f32 v[52:53], v[40:41], v[42:43]
	v_cvt_pk_bf16_f32 v40, v44, v45
	v_cvt_pk_bf16_f32 v41, v46, v47
	v_cvt_pk_bf16_f32 v42, v50, v51
	v_cvt_pk_bf16_f32 v43, v52, v53
	global_store_dwordx4 v[48:49], v[40:43], off sc1
	s_nop 1
	v_mul_f32_e32 v40, 0xbfb8aa3b, v36
	v_mul_f32_e32 v41, 0xbfb8aa3b, v37
	v_exp_f32_e32 v40, v40
	v_exp_f32_e32 v41, v41
	v_add_f32_e32 v40, 1.0, v40
	v_add_f32_e32 v41, 1.0, v41
	v_rcp_f32_e32 v40, v40
	v_rcp_f32_e32 v41, v41
	s_nop 0
	v_pk_mul_f32 v[36:37], v[36:37], v[40:41]
	v_mul_f32_e32 v40, 0xbfb8aa3b, v38
	v_mul_f32_e32 v41, 0xbfb8aa3b, v39
	v_exp_f32_e32 v40, v40
	v_exp_f32_e32 v41, v41
	v_add_f32_e32 v40, 1.0, v40
	v_add_f32_e32 v41, 1.0, v41
	v_rcp_f32_e32 v40, v40
	v_rcp_f32_e32 v41, v41
	s_nop 0
	v_pk_mul_f32 v[38:39], v[38:39], v[40:41]
	v_mul_f32_e32 v40, 0xbfb8aa3b, v32
	v_mul_f32_e32 v41, 0xbfb8aa3b, v33
	v_exp_f32_e32 v40, v40
	v_exp_f32_e32 v41, v41
	v_add_f32_e32 v40, 1.0, v40
	v_add_f32_e32 v41, 1.0, v41
	v_rcp_f32_e32 v40, v40
	v_rcp_f32_e32 v41, v41
	s_nop 0
	v_pk_mul_f32 v[40:41], v[32:33], v[40:41]
	v_pk_mul_f32 v[32:33], s[18:19], v[34:35] op_sel_hi:[0,1]
	v_mul_f32_e32 v34, 0xbfb8aa3b, v32
	v_mul_f32_e32 v35, 0xbfb8aa3b, v33
	v_exp_f32_e32 v34, v34
	v_exp_f32_e32 v35, v35
	v_add_f32_e32 v34, 1.0, v34
	v_add_f32_e32 v35, 1.0, v35
	v_rcp_f32_e32 v34, v34
	v_rcp_f32_e32 v35, v35
	s_nop 0
	v_pk_mul_f32 v[42:43], v[32:33], v[34:35]
	v_cvt_pk_bf16_f32 v32, v36, v37
	v_cvt_pk_bf16_f32 v33, v38, v39
	v_cvt_pk_bf16_f32 v34, v40, v41
	v_cvt_pk_bf16_f32 v35, v42, v43
	global_store_dwordx4 v[48:49], v[32:35], off offset:256 sc1
	v_pk_mul_f32 v[28:29], s[18:19], v[28:29] op_sel_hi:[0,1]
	s_nop 0
	v_mul_f32_e32 v34, 0xbfb8aa3b, v28
	v_mul_f32_e32 v35, 0xbfb8aa3b, v29
	v_exp_f32_e32 v34, v34
	v_exp_f32_e32 v35, v35
	v_pk_mul_f32 v[30:31], s[18:19], v[30:31] op_sel_hi:[0,1]
	v_pk_mul_f32 v[24:25], s[18:19], v[24:25] op_sel_hi:[0,1]
	v_add_f32_e32 v34, 1.0, v34
	v_add_f32_e32 v35, 1.0, v35
	v_rcp_f32_e32 v34, v34
	v_rcp_f32_e32 v35, v35
	v_add_u32_e32 v32, 0xa0, v142
	v_mad_u64_u32 v[32:33], s[4:5], v32, s31, v[132:133]
	v_pk_mul_f32 v[28:29], v[28:29], v[34:35]
	v_mul_f32_e32 v34, 0xbfb8aa3b, v30
	v_mul_f32_e32 v35, 0xbfb8aa3b, v31
	v_exp_f32_e32 v34, v34
	v_exp_f32_e32 v35, v35
	v_lshl_add_u64 v[32:33], v[32:33], 0, v[130:131]
	v_pk_mul_f32 v[20:21], s[18:19], v[20:21] op_sel_hi:[0,1]
	v_add_f32_e32 v34, 1.0, v34
	v_add_f32_e32 v35, 1.0, v35
	v_rcp_f32_e32 v34, v34
	v_rcp_f32_e32 v35, v35
	v_pk_mul_f32 v[22:23], s[18:19], v[22:23] op_sel_hi:[0,1]
	v_pk_mul_f32 v[16:17], s[18:19], v[16:17] op_sel_hi:[0,1]
	v_pk_mul_f32 v[30:31], v[30:31], v[34:35]
	v_mul_f32_e32 v34, 0xbfb8aa3b, v24
	v_mul_f32_e32 v35, 0xbfb8aa3b, v25
	v_exp_f32_e32 v34, v34
	v_exp_f32_e32 v35, v35
	v_add_f32_e32 v34, 1.0, v34
	v_add_f32_e32 v35, 1.0, v35
	v_rcp_f32_e32 v34, v34
	v_rcp_f32_e32 v35, v35
	s_nop 0
	v_pk_mul_f32 v[34:35], v[24:25], v[34:35]
	v_pk_mul_f32 v[24:25], s[18:19], v[26:27] op_sel_hi:[0,1]
	v_mul_f32_e32 v26, 0xbfb8aa3b, v24
	v_mul_f32_e32 v27, 0xbfb8aa3b, v25
	v_exp_f32_e32 v26, v26
	v_exp_f32_e32 v27, v27
	v_add_f32_e32 v26, 1.0, v26
	v_add_f32_e32 v27, 1.0, v27
	v_rcp_f32_e32 v26, v26
	v_rcp_f32_e32 v27, v27
	s_nop 0
	v_pk_mul_f32 v[36:37], v[24:25], v[26:27]
	v_cvt_pk_bf16_f32 v24, v28, v29
	v_cvt_pk_bf16_f32 v25, v30, v31
	v_cvt_pk_bf16_f32 v26, v34, v35
	v_cvt_pk_bf16_f32 v27, v36, v37
	global_store_dwordx4 v[32:33], v[24:27], off sc1
	s_nop 1
	v_mul_f32_e32 v24, 0xbfb8aa3b, v20
	v_mul_f32_e32 v25, 0xbfb8aa3b, v21
	v_exp_f32_e32 v24, v24
	v_exp_f32_e32 v25, v25
	v_add_f32_e32 v24, 1.0, v24
	v_add_f32_e32 v25, 1.0, v25
	v_rcp_f32_e32 v24, v24
	v_rcp_f32_e32 v25, v25
	s_nop 0
	v_pk_mul_f32 v[20:21], v[20:21], v[24:25]
	v_mul_f32_e32 v24, 0xbfb8aa3b, v22
	v_mul_f32_e32 v25, 0xbfb8aa3b, v23
	v_exp_f32_e32 v24, v24
	v_exp_f32_e32 v25, v25
	v_add_f32_e32 v24, 1.0, v24
	v_add_f32_e32 v25, 1.0, v25
	v_rcp_f32_e32 v24, v24
	v_rcp_f32_e32 v25, v25
	s_nop 0
	v_pk_mul_f32 v[22:23], v[22:23], v[24:25]
	v_mul_f32_e32 v24, 0xbfb8aa3b, v16
	v_mul_f32_e32 v25, 0xbfb8aa3b, v17
	v_exp_f32_e32 v24, v24
	v_exp_f32_e32 v25, v25
	v_add_f32_e32 v24, 1.0, v24
	v_add_f32_e32 v25, 1.0, v25
	v_rcp_f32_e32 v24, v24
	v_rcp_f32_e32 v25, v25
	s_nop 0
	v_pk_mul_f32 v[24:25], v[16:17], v[24:25]
	v_pk_mul_f32 v[16:17], s[18:19], v[18:19] op_sel_hi:[0,1]
	v_mul_f32_e32 v18, 0xbfb8aa3b, v16
	v_mul_f32_e32 v19, 0xbfb8aa3b, v17
	v_exp_f32_e32 v18, v18
	v_exp_f32_e32 v19, v19
	v_add_f32_e32 v18, 1.0, v18
	v_add_f32_e32 v19, 1.0, v19
	v_rcp_f32_e32 v18, v18
	v_rcp_f32_e32 v19, v19
	s_nop 0
	v_pk_mul_f32 v[26:27], v[16:17], v[18:19]
	v_cvt_pk_bf16_f32 v16, v20, v21
	v_cvt_pk_bf16_f32 v17, v22, v23
	v_cvt_pk_bf16_f32 v18, v24, v25
	v_cvt_pk_bf16_f32 v19, v26, v27
	global_store_dwordx4 v[32:33], v[16:19], off offset:256 sc1
	v_pk_mul_f32 v[12:13], s[18:19], v[12:13] op_sel_hi:[0,1]
	s_nop 0
	v_mul_f32_e32 v18, 0xbfb8aa3b, v12
	v_mul_f32_e32 v19, 0xbfb8aa3b, v13
	v_exp_f32_e32 v18, v18
	v_exp_f32_e32 v19, v19
	v_pk_mul_f32 v[14:15], s[18:19], v[14:15] op_sel_hi:[0,1]
	v_pk_mul_f32 v[8:9], s[18:19], v[8:9] op_sel_hi:[0,1]
	v_add_f32_e32 v18, 1.0, v18
	v_add_f32_e32 v19, 1.0, v19
	v_rcp_f32_e32 v18, v18
	v_rcp_f32_e32 v19, v19
	v_add_u32_e32 v16, 0xb0, v142
	v_mad_u64_u32 v[16:17], s[4:5], v16, s31, v[132:133]
	v_pk_mul_f32 v[12:13], v[12:13], v[18:19]
	v_mul_f32_e32 v18, 0xbfb8aa3b, v14
	v_mul_f32_e32 v19, 0xbfb8aa3b, v15
	v_exp_f32_e32 v18, v18
	v_exp_f32_e32 v19, v19
	v_lshl_add_u64 v[16:17], v[16:17], 0, v[130:131]
	v_pk_mul_f32 v[4:5], s[18:19], v[4:5] op_sel_hi:[0,1]
	v_add_f32_e32 v18, 1.0, v18
	v_add_f32_e32 v19, 1.0, v19
	v_rcp_f32_e32 v18, v18
	v_rcp_f32_e32 v19, v19
	v_pk_mul_f32 v[6:7], s[18:19], v[6:7] op_sel_hi:[0,1]
	v_pk_mul_f32 v[0:1], s[18:19], v[0:1] op_sel_hi:[0,1]
	s_mov_b64 s[4:5], -1
	v_pk_mul_f32 v[14:15], v[14:15], v[18:19]
	v_mul_f32_e32 v18, 0xbfb8aa3b, v8
	v_mul_f32_e32 v19, 0xbfb8aa3b, v9
	v_exp_f32_e32 v18, v18
	v_exp_f32_e32 v19, v19
	s_andn2_b64 vcc, exec, s[28:29]
	v_add_f32_e32 v18, 1.0, v18
	v_add_f32_e32 v19, 1.0, v19
	v_rcp_f32_e32 v18, v18
	v_rcp_f32_e32 v19, v19
	s_nop 0
	v_pk_mul_f32 v[18:19], v[8:9], v[18:19]
	v_pk_mul_f32 v[8:9], s[18:19], v[10:11] op_sel_hi:[0,1]
	v_mul_f32_e32 v10, 0xbfb8aa3b, v8
	v_mul_f32_e32 v11, 0xbfb8aa3b, v9
	v_exp_f32_e32 v10, v10
	v_exp_f32_e32 v11, v11
	v_add_f32_e32 v10, 1.0, v10
	v_add_f32_e32 v11, 1.0, v11
	v_rcp_f32_e32 v10, v10
	v_rcp_f32_e32 v11, v11
	s_nop 0
	v_pk_mul_f32 v[20:21], v[8:9], v[10:11]
	v_cvt_pk_bf16_f32 v8, v12, v13
	v_cvt_pk_bf16_f32 v9, v14, v15
	v_cvt_pk_bf16_f32 v10, v18, v19
	v_cvt_pk_bf16_f32 v11, v20, v21
	global_store_dwordx4 v[16:17], v[8:11], off sc1
	s_nop 1
	v_mul_f32_e32 v8, 0xbfb8aa3b, v4
	v_mul_f32_e32 v9, 0xbfb8aa3b, v5
	v_exp_f32_e32 v8, v8
	v_exp_f32_e32 v9, v9
	v_add_f32_e32 v8, 1.0, v8
	v_add_f32_e32 v9, 1.0, v9
	v_rcp_f32_e32 v8, v8
	v_rcp_f32_e32 v9, v9
	s_nop 0
	v_pk_mul_f32 v[4:5], v[4:5], v[8:9]
	v_mul_f32_e32 v8, 0xbfb8aa3b, v6
	v_mul_f32_e32 v9, 0xbfb8aa3b, v7
	v_exp_f32_e32 v8, v8
	v_exp_f32_e32 v9, v9
	v_add_f32_e32 v8, 1.0, v8
	v_add_f32_e32 v9, 1.0, v9
	v_rcp_f32_e32 v8, v8
	v_rcp_f32_e32 v9, v9
	s_nop 0
	v_pk_mul_f32 v[6:7], v[6:7], v[8:9]
	v_mul_f32_e32 v8, 0xbfb8aa3b, v0
	v_mul_f32_e32 v9, 0xbfb8aa3b, v1
	v_exp_f32_e32 v8, v8
	v_exp_f32_e32 v9, v9
	v_add_f32_e32 v8, 1.0, v8
	v_add_f32_e32 v9, 1.0, v9
	v_rcp_f32_e32 v8, v8
	v_rcp_f32_e32 v9, v9
	s_nop 0
	v_pk_mul_f32 v[8:9], v[0:1], v[8:9]
	v_pk_mul_f32 v[0:1], s[18:19], v[2:3] op_sel_hi:[0,1]
	v_mul_f32_e32 v2, 0xbfb8aa3b, v0
	v_mul_f32_e32 v3, 0xbfb8aa3b, v1
	v_exp_f32_e32 v2, v2
	v_exp_f32_e32 v3, v3
	v_add_f32_e32 v2, 1.0, v2
	v_add_f32_e32 v3, 1.0, v3
	v_rcp_f32_e32 v2, v2
	v_rcp_f32_e32 v3, v3
	s_nop 0
	v_pk_mul_f32 v[10:11], v[0:1], v[2:3]
	v_cvt_pk_bf16_f32 v0, v4, v5
	v_cvt_pk_bf16_f32 v1, v6, v7
	v_cvt_pk_bf16_f32 v2, v8, v9
	v_cvt_pk_bf16_f32 v3, v10, v11
	global_store_dwordx4 v[16:17], v[0:3], off offset:256 sc1
	s_cbranch_vccnz .LBB0_290
	s_andn2_b64 vcc, exec, s[20:21]
	s_cbranch_vccnz .LBB0_289
	s_barrier
	s_branch .LBB0_289

.LBB0_319:
	v_mbcnt_lo_u32_b32 v4, -1, 0
	v_mbcnt_hi_u32_b32 v4, -1, v4
	s_nop 0
	v_and_or_b32 v12, v4, 15, s3
	v_ashrrev_i32_e32 v4, 1, v4
	v_and_b32_e32 v4, -8, v4
	v_add_u32_e32 v4, s52, v4
	v_ashrrev_i32_e32 v5, 31, v4
	v_lshlrev_b64 v[4:5], 1, v[4:5]
	v_mul_f32_e32 v69, s48, v242
	v_mul_f32_e32 v70, s48, v243
	v_mul_f32_e32 v71, s48, v120
	v_mul_f32_e32 v80, s48, v121
	v_mul_f32_e32 v69, 0xbfb8aa3b, v69
	v_mul_f32_e32 v70, 0xbfb8aa3b, v70
	v_mul_f32_e32 v71, 0xbfb8aa3b, v71
	v_mul_f32_e32 v80, 0xbfb8aa3b, v80
	v_exp_f32_e32 v69, v69
	v_exp_f32_e32 v70, v70
	v_exp_f32_e32 v71, v71
	v_exp_f32_e32 v80, v80
	v_mul_f32_e32 v13, s48, v240
	v_mul_f32_e32 v68, s48, v241
	v_mul_f32_e32 v81, s48, v122
	v_mul_f32_e32 v82, s48, v123
	v_mul_f32_e32 v13, 0xbfb8aa3b, v13
	v_mul_f32_e32 v68, 0xbfb8aa3b, v68
	v_add_f32_e32 v69, 1.0, v69
	v_add_f32_e32 v70, 1.0, v70
	v_add_f32_e32 v71, 1.0, v71
	v_add_f32_e32 v80, 1.0, v80
	v_mul_f32_e32 v81, 0xbfb8aa3b, v81
	v_mul_f32_e32 v82, 0xbfb8aa3b, v82
	v_exp_f32_e32 v13, v13
	v_exp_f32_e32 v68, v68
	v_rcp_f32_e32 v69, v69
	v_rcp_f32_e32 v70, v70
	v_rcp_f32_e32 v71, v71
	v_exp_f32_e32 v81, v81
	v_exp_f32_e32 v82, v82
	v_rcp_f32_e32 v80, v80
	v_add_f32_e32 v13, 1.0, v13
	v_add_f32_e32 v68, 1.0, v68
	v_add_f32_e32 v81, 1.0, v81
	v_add_f32_e32 v82, 1.0, v82
	v_cvt_pk_bf16_f32 v69, v69, v70
	v_cvt_pk_bf16_f32 v70, v71, v80
	v_mul_f32_e32 v80, s48, v185
	v_rcp_f32_e32 v13, v13
	v_rcp_f32_e32 v68, v68
	v_rcp_f32_e32 v81, v81
	v_rcp_f32_e32 v82, v82
	v_mul_f32_e32 v80, 0xbfb8aa3b, v80
	v_exp_f32_e32 v80, v80
	v_mov_b64_e32 v[6:7], s[30:31]
	v_mad_u64_u32 v[14:15], s[4:5], v12, s21, v[6:7]
	v_lshl_add_u64 v[14:15], v[14:15], 0, v[4:5]
	v_cvt_pk_bf16_f32 v68, v13, v68
	v_cvt_pk_bf16_f32 v71, v81, v82
	v_mul_f32_e32 v13, s48, v184
	global_store_dwordx4 v[14:15], v[68:71], off sc1
	v_mul_f32_e32 v81, s48, v182
	v_mul_f32_e32 v82, s48, v183
	v_add_f32_e32 v68, 1.0, v80
	v_mul_f32_e32 v69, s48, v186
	v_mul_f32_e32 v70, s48, v187
	v_mul_f32_e32 v71, s48, v180
	v_mul_f32_e32 v80, s48, v181
	v_mul_f32_e32 v13, 0xbfb8aa3b, v13
	v_mul_f32_e32 v69, 0xbfb8aa3b, v69
	v_mul_f32_e32 v70, 0xbfb8aa3b, v70
	v_mul_f32_e32 v71, 0xbfb8aa3b, v71
	v_mul_f32_e32 v80, 0xbfb8aa3b, v80
	v_mul_f32_e32 v81, 0xbfb8aa3b, v81
	v_mul_f32_e32 v82, 0xbfb8aa3b, v82
	v_exp_f32_e32 v13, v13
	v_exp_f32_e32 v69, v69
	v_exp_f32_e32 v70, v70
	v_exp_f32_e32 v71, v71
	v_exp_f32_e32 v80, v80
	v_exp_f32_e32 v81, v81
	v_exp_f32_e32 v82, v82
	v_add_f32_e32 v13, 1.0, v13
	v_add_f32_e32 v69, 1.0, v69
	v_add_f32_e32 v70, 1.0, v70
	v_add_f32_e32 v71, 1.0, v71
	v_add_f32_e32 v80, 1.0, v80
	v_add_f32_e32 v81, 1.0, v81
	v_add_f32_e32 v82, 1.0, v82
	v_rcp_f32_e32 v13, v13
	v_rcp_f32_e32 v68, v68
	v_rcp_f32_e32 v69, v69
	v_rcp_f32_e32 v70, v70
	v_rcp_f32_e32 v71, v71
	v_rcp_f32_e32 v80, v80
	v_rcp_f32_e32 v81, v81
	v_rcp_f32_e32 v82, v82
	v_cvt_pk_bf16_f32 v68, v13, v68
	v_cvt_pk_bf16_f32 v69, v69, v70
	v_cvt_pk_bf16_f32 v70, v71, v80
	v_cvt_pk_bf16_f32 v71, v81, v82
	global_store_dwordx4 v[14:15], v[68:71], off offset:256 sc1
	s_nop 1
	v_mul_f32_e32 v69, s48, v114
	v_mul_f32_e32 v70, s48, v115
	v_mul_f32_e32 v71, s48, v104
	v_mul_f32_e32 v80, s48, v105
	v_mul_f32_e32 v69, 0xbfb8aa3b, v69
	v_mul_f32_e32 v70, 0xbfb8aa3b, v70
	v_mul_f32_e32 v71, 0xbfb8aa3b, v71
	v_mul_f32_e32 v80, 0xbfb8aa3b, v80
	v_exp_f32_e32 v69, v69
	v_exp_f32_e32 v70, v70
	v_exp_f32_e32 v71, v71
	v_exp_f32_e32 v80, v80
	v_or_b32_e32 v13, 16, v12
	v_mad_u64_u32 v[14:15], s[4:5], v13, s21, v[6:7]
	v_mul_f32_e32 v13, s48, v112
	v_mul_f32_e32 v68, s48, v113
	v_mul_f32_e32 v81, s48, v106
	v_mul_f32_e32 v82, s48, v107
	v_mul_f32_e32 v13, 0xbfb8aa3b, v13
	v_mul_f32_e32 v68, 0xbfb8aa3b, v68
	v_add_f32_e32 v69, 1.0, v69
	v_add_f32_e32 v70, 1.0, v70
	v_add_f32_e32 v71, 1.0, v71
	v_add_f32_e32 v80, 1.0, v80
	v_mul_f32_e32 v81, 0xbfb8aa3b, v81
	v_mul_f32_e32 v82, 0xbfb8aa3b, v82
	v_exp_f32_e32 v13, v13
	v_exp_f32_e32 v68, v68
	v_rcp_f32_e32 v69, v69
	v_rcp_f32_e32 v70, v70
	v_rcp_f32_e32 v71, v71
	v_exp_f32_e32 v81, v81
	v_exp_f32_e32 v82, v82
	v_rcp_f32_e32 v80, v80
	v_add_f32_e32 v13, 1.0, v13
	v_add_f32_e32 v68, 1.0, v68
	v_add_f32_e32 v81, 1.0, v81
	v_add_f32_e32 v82, 1.0, v82
	v_cvt_pk_bf16_f32 v69, v69, v70
	v_cvt_pk_bf16_f32 v70, v71, v80
	v_mul_f32_e32 v80, s48, v117
	v_rcp_f32_e32 v13, v13
	v_rcp_f32_e32 v68, v68
	v_rcp_f32_e32 v81, v81
	v_rcp_f32_e32 v82, v82
	v_mul_f32_e32 v80, 0xbfb8aa3b, v80
	v_exp_f32_e32 v80, v80
	v_lshl_add_u64 v[14:15], v[14:15], 0, v[4:5]
	v_cvt_pk_bf16_f32 v68, v13, v68
	v_cvt_pk_bf16_f32 v71, v81, v82
	v_mul_f32_e32 v13, s48, v116
	global_store_dwordx4 v[14:15], v[68:71], off sc1
	v_mul_f32_e32 v81, s48, v110
	v_mul_f32_e32 v82, s48, v111
	v_add_f32_e32 v68, 1.0, v80
	v_mul_f32_e32 v69, s48, v118
	v_mul_f32_e32 v70, s48, v119
	v_mul_f32_e32 v71, s48, v108
	v_mul_f32_e32 v80, s48, v109
	v_mul_f32_e32 v13, 0xbfb8aa3b, v13
	v_mul_f32_e32 v69, 0xbfb8aa3b, v69
	v_mul_f32_e32 v70, 0xbfb8aa3b, v70
	v_mul_f32_e32 v71, 0xbfb8aa3b, v71
	v_mul_f32_e32 v80, 0xbfb8aa3b, v80
	v_mul_f32_e32 v81, 0xbfb8aa3b, v81
	v_mul_f32_e32 v82, 0xbfb8aa3b, v82
	v_exp_f32_e32 v13, v13
	v_exp_f32_e32 v69, v69
	v_exp_f32_e32 v70, v70
	v_exp_f32_e32 v71, v71
	v_exp_f32_e32 v80, v80
	v_exp_f32_e32 v81, v81
	v_exp_f32_e32 v82, v82
	v_add_f32_e32 v13, 1.0, v13
	v_add_f32_e32 v69, 1.0, v69
	v_add_f32_e32 v70, 1.0, v70
	v_add_f32_e32 v71, 1.0, v71
	v_add_f32_e32 v80, 1.0, v80
	v_add_f32_e32 v81, 1.0, v81
	v_add_f32_e32 v82, 1.0, v82
	v_rcp_f32_e32 v13, v13
	v_rcp_f32_e32 v68, v68
	v_rcp_f32_e32 v69, v69
	v_rcp_f32_e32 v70, v70
	v_rcp_f32_e32 v71, v71
	v_rcp_f32_e32 v80, v80
	v_rcp_f32_e32 v81, v81
	v_rcp_f32_e32 v82, v82
	v_cvt_pk_bf16_f32 v68, v13, v68
	v_cvt_pk_bf16_f32 v69, v69, v70
	v_cvt_pk_bf16_f32 v70, v71, v80
	v_cvt_pk_bf16_f32 v71, v81, v82
	global_store_dwordx4 v[14:15], v[68:71], off offset:256 sc1
	s_nop 1
	v_mul_f32_e32 v69, s48, v102
	v_mul_f32_e32 v70, s48, v103
	v_mul_f32_e32 v71, s48, v92
	v_mul_f32_e32 v80, s48, v93
	v_mul_f32_e32 v69, 0xbfb8aa3b, v69
	v_mul_f32_e32 v70, 0xbfb8aa3b, v70
	v_mul_f32_e32 v71, 0xbfb8aa3b, v71
	v_mul_f32_e32 v80, 0xbfb8aa3b, v80
	v_exp_f32_e32 v69, v69
	v_exp_f32_e32 v70, v70
	v_exp_f32_e32 v71, v71
	v_exp_f32_e32 v80, v80
	v_or_b32_e32 v13, 32, v12
	v_mad_u64_u32 v[14:15], s[4:5], v13, s21, v[6:7]
	v_mul_f32_e32 v13, s48, v100
	v_mul_f32_e32 v68, s48, v101
	v_mul_f32_e32 v81, s48, v94
	v_mul_f32_e32 v82, s48, v95
	v_mul_f32_e32 v13, 0xbfb8aa3b, v13
	v_mul_f32_e32 v68, 0xbfb8aa3b, v68
	v_add_f32_e32 v69, 1.0, v69
	v_add_f32_e32 v70, 1.0, v70
	v_add_f32_e32 v71, 1.0, v71
	v_add_f32_e32 v80, 1.0, v80
	v_mul_f32_e32 v81, 0xbfb8aa3b, v81
	v_mul_f32_e32 v82, 0xbfb8aa3b, v82
	v_exp_f32_e32 v13, v13
	v_exp_f32_e32 v68, v68
	v_rcp_f32_e32 v69, v69
	v_rcp_f32_e32 v70, v70
	v_rcp_f32_e32 v71, v71
	v_exp_f32_e32 v81, v81
	v_exp_f32_e32 v82, v82
	v_rcp_f32_e32 v80, v80
	v_add_f32_e32 v13, 1.0, v13
	v_add_f32_e32 v68, 1.0, v68
	v_add_f32_e32 v81, 1.0, v81
	v_add_f32_e32 v82, 1.0, v82
	v_cvt_pk_bf16_f32 v69, v69, v70
	v_cvt_pk_bf16_f32 v70, v71, v80
	v_mul_f32_e32 v80, s48, v97
	v_rcp_f32_e32 v13, v13
	v_rcp_f32_e32 v68, v68
	v_rcp_f32_e32 v81, v81
	v_rcp_f32_e32 v82, v82
	v_mul_f32_e32 v80, 0xbfb8aa3b, v80
	v_exp_f32_e32 v80, v80
	v_lshl_add_u64 v[14:15], v[14:15], 0, v[4:5]
	v_cvt_pk_bf16_f32 v68, v13, v68
	v_cvt_pk_bf16_f32 v71, v81, v82
	v_mul_f32_e32 v13, s48, v96
	global_store_dwordx4 v[14:15], v[68:71], off sc1
	v_mul_f32_e32 v81, s48, v90
	v_mul_f32_e32 v82, s48, v91
	v_add_f32_e32 v68, 1.0, v80
	v_mul_f32_e32 v69, s48, v98
	v_mul_f32_e32 v70, s48, v99
	v_mul_f32_e32 v71, s48, v88
	v_mul_f32_e32 v80, s48, v89
	v_mul_f32_e32 v13, 0xbfb8aa3b, v13
	v_mul_f32_e32 v69, 0xbfb8aa3b, v69
	v_mul_f32_e32 v70, 0xbfb8aa3b, v70
	v_mul_f32_e32 v71, 0xbfb8aa3b, v71
	v_mul_f32_e32 v80, 0xbfb8aa3b, v80
	v_mul_f32_e32 v81, 0xbfb8aa3b, v81
	v_mul_f32_e32 v82, 0xbfb8aa3b, v82
	v_exp_f32_e32 v13, v13
	v_exp_f32_e32 v69, v69
	v_exp_f32_e32 v70, v70
	v_exp_f32_e32 v71, v71
	v_exp_f32_e32 v80, v80
	v_exp_f32_e32 v81, v81
	v_exp_f32_e32 v82, v82
	v_add_f32_e32 v13, 1.0, v13
	v_add_f32_e32 v69, 1.0, v69
	v_add_f32_e32 v70, 1.0, v70
	v_add_f32_e32 v71, 1.0, v71
	v_add_f32_e32 v80, 1.0, v80
	v_add_f32_e32 v81, 1.0, v81
	v_add_f32_e32 v82, 1.0, v82
	v_rcp_f32_e32 v13, v13
	v_rcp_f32_e32 v68, v68
	v_rcp_f32_e32 v69, v69
	v_rcp_f32_e32 v70, v70
	v_rcp_f32_e32 v71, v71
	v_rcp_f32_e32 v80, v80
	v_rcp_f32_e32 v81, v81
	v_rcp_f32_e32 v82, v82
	v_cvt_pk_bf16_f32 v68, v13, v68
	v_cvt_pk_bf16_f32 v69, v69, v70
	v_cvt_pk_bf16_f32 v70, v71, v80
	v_cvt_pk_bf16_f32 v71, v81, v82
	global_store_dwordx4 v[14:15], v[68:71], off offset:256 sc1
	v_or_b32_e32 v13, 48, v12
	v_mad_u64_u32 v[14:15], s[4:5], v13, s21, v[6:7]
	v_mul_f32_e32 v13, s48, v188
	v_mul_f32_e32 v68, s48, v189
	v_mul_f32_e32 v69, s48, v190
	v_mul_f32_e32 v70, s48, v191
	v_mul_f32_e32 v71, s48, v144
	v_mul_f32_e32 v80, s48, v145
	v_mul_f32_e32 v81, s48, v146
	v_mul_f32_e32 v82, s48, v147
	v_mul_f32_e32 v13, 0xbfb8aa3b, v13
	v_mul_f32_e32 v68, 0xbfb8aa3b, v68
	v_mul_f32_e32 v69, 0xbfb8aa3b, v69
	v_mul_f32_e32 v70, 0xbfb8aa3b, v70
	v_mul_f32_e32 v71, 0xbfb8aa3b, v71
	v_mul_f32_e32 v80, 0xbfb8aa3b, v80
	v_mul_f32_e32 v81, 0xbfb8aa3b, v81
	v_mul_f32_e32 v82, 0xbfb8aa3b, v82
	v_exp_f32_e32 v13, v13
	v_exp_f32_e32 v68, v68
	v_exp_f32_e32 v69, v69
	v_exp_f32_e32 v70, v70
	v_exp_f32_e32 v71, v71
	v_exp_f32_e32 v80, v80
	v_exp_f32_e32 v81, v81
	v_exp_f32_e32 v82, v82
	v_mul_f32_e32 v56, s48, v56
	v_add_f32_e32 v13, 1.0, v13
	v_add_f32_e32 v68, 1.0, v68
	v_add_f32_e32 v69, 1.0, v69
	v_add_f32_e32 v70, 1.0, v70
	v_add_f32_e32 v71, 1.0, v71
	v_add_f32_e32 v80, 1.0, v80
	v_add_f32_e32 v81, 1.0, v81
	v_add_f32_e32 v82, 1.0, v82
	v_mul_f32_e32 v56, 0xbfb8aa3b, v56
	v_mul_f32_e32 v57, s48, v57
	v_rcp_f32_e32 v13, v13
	v_rcp_f32_e32 v68, v68
	v_rcp_f32_e32 v69, v69
	v_rcp_f32_e32 v70, v70
	v_rcp_f32_e32 v71, v71
	v_rcp_f32_e32 v80, v80
	v_rcp_f32_e32 v81, v81
	v_rcp_f32_e32 v82, v82
	v_exp_f32_e32 v56, v56
	v_mul_f32_e32 v57, 0xbfb8aa3b, v57
	v_exp_f32_e32 v57, v57
	v_lshl_add_u64 v[14:15], v[14:15], 0, v[4:5]
	v_cvt_pk_bf16_f32 v68, v13, v68
	v_cvt_pk_bf16_f32 v69, v69, v70
	v_cvt_pk_bf16_f32 v70, v71, v80
	v_cvt_pk_bf16_f32 v71, v81, v82
	v_add_f32_e32 v56, 1.0, v56
	global_store_dwordx4 v[14:15], v[68:71], off sc1
	v_mul_f32_e32 v13, s48, v72
	v_mul_f32_e32 v72, s48, v73
	v_rcp_f32_e32 v71, v56
	v_add_f32_e32 v56, 1.0, v57
	v_mul_f32_e32 v57, s48, v58
	v_mul_f32_e32 v69, s48, v74
	v_mul_f32_e32 v70, s48, v75
	v_mul_f32_e32 v57, 0xbfb8aa3b, v57
	v_mul_f32_e32 v58, s48, v59
	v_mul_f32_e32 v13, 0xbfb8aa3b, v13
	v_mul_f32_e32 v72, 0xbfb8aa3b, v72
	v_mul_f32_e32 v69, 0xbfb8aa3b, v69
	v_mul_f32_e32 v70, 0xbfb8aa3b, v70
	v_exp_f32_e32 v57, v57
	v_mul_f32_e32 v58, 0xbfb8aa3b, v58
	v_exp_f32_e32 v13, v13
	v_exp_f32_e32 v72, v72
	v_exp_f32_e32 v69, v69
	v_exp_f32_e32 v70, v70
	v_exp_f32_e32 v58, v58
	v_rcp_f32_e32 v59, v56
	v_add_f32_e32 v56, 1.0, v57
	v_add_f32_e32 v13, 1.0, v13
	v_add_f32_e32 v68, 1.0, v72
	v_add_f32_e32 v69, 1.0, v69
	v_add_f32_e32 v70, 1.0, v70
	v_rcp_f32_e32 v72, v56
	v_add_f32_e32 v56, 1.0, v58
	v_rcp_f32_e32 v13, v13
	v_rcp_f32_e32 v68, v68
	v_rcp_f32_e32 v69, v69
	v_rcp_f32_e32 v70, v70
	v_rcp_f32_e32 v73, v56
	v_cvt_pk_bf16_f32 v56, v13, v68
	v_cvt_pk_bf16_f32 v58, v71, v59
	v_cvt_pk_bf16_f32 v57, v69, v70
	v_cvt_pk_bf16_f32 v59, v72, v73
	global_store_dwordx4 v[14:15], v[56:59], off offset:256 sc1
	v_add_u32_e32 v13, 0x80, v12
	v_mad_u64_u32 v[14:15], s[4:5], v13, s21, v[6:7]
	v_mul_f32_e32 v13, s48, v84
	v_mul_f32_e32 v56, s48, v85
	v_mul_f32_e32 v57, s48, v86
	v_mul_f32_e32 v58, s48, v87
	v_mul_f32_e32 v59, s48, v64
	v_mul_f32_e32 v64, s48, v65
	v_mul_f32_e32 v65, s48, v66
	v_mul_f32_e32 v66, s48, v67
	v_mul_f32_e32 v13, 0xbfb8aa3b, v13
	v_mul_f32_e32 v56, 0xbfb8aa3b, v56
	v_mul_f32_e32 v57, 0xbfb8aa3b, v57
	v_mul_f32_e32 v58, 0xbfb8aa3b, v58
	v_mul_f32_e32 v59, 0xbfb8aa3b, v59
	v_mul_f32_e32 v64, 0xbfb8aa3b, v64
	v_mul_f32_e32 v65, 0xbfb8aa3b, v65
	v_mul_f32_e32 v66, 0xbfb8aa3b, v66
	v_exp_f32_e32 v13, v13
	v_exp_f32_e32 v56, v56
	v_exp_f32_e32 v57, v57
	v_exp_f32_e32 v58, v58
	v_exp_f32_e32 v59, v59
	v_exp_f32_e32 v64, v64
	v_exp_f32_e32 v65, v65
	v_exp_f32_e32 v66, v66
	v_add_f32_e32 v13, 1.0, v13
	v_add_f32_e32 v56, 1.0, v56
	v_add_f32_e32 v57, 1.0, v57
	v_add_f32_e32 v58, 1.0, v58
	v_add_f32_e32 v59, 1.0, v59
	v_add_f32_e32 v64, 1.0, v64
	v_add_f32_e32 v65, 1.0, v65
	v_add_f32_e32 v66, 1.0, v66
	v_rcp_f32_e32 v13, v13
	v_rcp_f32_e32 v56, v56
	v_rcp_f32_e32 v57, v57
	v_rcp_f32_e32 v58, v58
	v_rcp_f32_e32 v59, v59
	v_rcp_f32_e32 v64, v64
	v_rcp_f32_e32 v65, v65
	v_rcp_f32_e32 v66, v66
	v_lshl_add_u64 v[14:15], v[14:15], 0, v[4:5]
	v_cvt_pk_bf16_f32 v56, v13, v56
	v_cvt_pk_bf16_f32 v57, v57, v58
	v_cvt_pk_bf16_f32 v58, v59, v64
	v_cvt_pk_bf16_f32 v59, v65, v66
	v_mul_f32_e32 v13, s48, v76
	v_mul_f32_e32 v64, s48, v77
	global_store_dwordx4 v[14:15], v[56:59], off sc1
	v_mul_f32_e32 v13, 0xbfb8aa3b, v13
	v_mul_f32_e32 v64, 0xbfb8aa3b, v64
	v_mul_f32_e32 v57, s48, v78
	v_mul_f32_e32 v58, s48, v79
	v_mul_f32_e32 v59, s48, v60
	v_mul_f32_e32 v60, s48, v61
	v_mul_f32_e32 v61, s48, v62
	v_mul_f32_e32 v62, s48, v63
	v_mul_f32_e32 v57, 0xbfb8aa3b, v57
	v_mul_f32_e32 v58, 0xbfb8aa3b, v58
	v_mul_f32_e32 v59, 0xbfb8aa3b, v59
	v_mul_f32_e32 v60, 0xbfb8aa3b, v60
	v_mul_f32_e32 v61, 0xbfb8aa3b, v61
	v_mul_f32_e32 v62, 0xbfb8aa3b, v62
	v_exp_f32_e32 v13, v13
	v_exp_f32_e32 v64, v64
	v_exp_f32_e32 v57, v57
	v_exp_f32_e32 v58, v58
	v_exp_f32_e32 v59, v59
	v_exp_f32_e32 v60, v60
	v_exp_f32_e32 v61, v61
	v_exp_f32_e32 v62, v62
	v_add_f32_e32 v13, 1.0, v13
	v_add_f32_e32 v56, 1.0, v64
	v_add_f32_e32 v57, 1.0, v57
	v_add_f32_e32 v58, 1.0, v58
	v_add_f32_e32 v59, 1.0, v59
	v_add_f32_e32 v60, 1.0, v60
	v_add_f32_e32 v61, 1.0, v61
	v_add_f32_e32 v62, 1.0, v62
	v_rcp_f32_e32 v13, v13
	v_rcp_f32_e32 v56, v56
	v_rcp_f32_e32 v57, v57
	v_rcp_f32_e32 v58, v58
	v_rcp_f32_e32 v59, v59
	v_rcp_f32_e32 v60, v60
	v_rcp_f32_e32 v61, v61
	v_rcp_f32_e32 v62, v62
	v_cvt_pk_bf16_f32 v56, v13, v56
	v_cvt_pk_bf16_f32 v57, v57, v58
	v_cvt_pk_bf16_f32 v58, v59, v60
	v_cvt_pk_bf16_f32 v59, v61, v62
	global_store_dwordx4 v[14:15], v[56:59], off offset:256 sc1
	v_mul_f32_e32 v44, s48, v44
	v_mul_f32_e32 v44, 0xbfb8aa3b, v44
	v_mul_f32_e32 v45, s48, v45
	v_exp_f32_e32 v44, v44
	v_mul_f32_e32 v45, 0xbfb8aa3b, v45
	v_exp_f32_e32 v45, v45
	v_add_u32_e32 v13, 0x90, v12
	v_add_f32_e32 v44, 1.0, v44
	v_mad_u64_u32 v[14:15], s[4:5], v13, s21, v[6:7]
	v_mul_f32_e32 v13, s48, v52
	v_mul_f32_e32 v52, s48, v53
	v_mul_f32_e32 v53, s48, v54
	v_mul_f32_e32 v54, s48, v55
	v_rcp_f32_e32 v55, v44
	v_add_f32_e32 v44, 1.0, v45
	v_mul_f32_e32 v45, s48, v46
	v_mul_f32_e32 v45, 0xbfb8aa3b, v45
	v_mul_f32_e32 v46, s48, v47
	v_mul_f32_e32 v13, 0xbfb8aa3b, v13
	v_mul_f32_e32 v52, 0xbfb8aa3b, v52
	v_mul_f32_e32 v53, 0xbfb8aa3b, v53
	v_mul_f32_e32 v54, 0xbfb8aa3b, v54
	v_exp_f32_e32 v45, v45
	v_mul_f32_e32 v46, 0xbfb8aa3b, v46
	v_exp_f32_e32 v13, v13
	v_exp_f32_e32 v52, v52
	v_exp_f32_e32 v53, v53
	v_exp_f32_e32 v54, v54
	v_exp_f32_e32 v46, v46
	v_rcp_f32_e32 v47, v44
	v_add_f32_e32 v44, 1.0, v45
	v_mul_f32_e32 v40, s48, v40
	v_add_f32_e32 v13, 1.0, v13
	v_add_f32_e32 v52, 1.0, v52
	v_add_f32_e32 v53, 1.0, v53
	v_add_f32_e32 v54, 1.0, v54
	v_rcp_f32_e32 v56, v44
	v_add_f32_e32 v44, 1.0, v46
	v_mul_f32_e32 v40, 0xbfb8aa3b, v40
	v_mul_f32_e32 v41, s48, v41
	v_rcp_f32_e32 v13, v13
	v_rcp_f32_e32 v52, v52
	v_rcp_f32_e32 v53, v53
	v_rcp_f32_e32 v54, v54
	v_rcp_f32_e32 v57, v44
	v_exp_f32_e32 v40, v40
	v_mul_f32_e32 v41, 0xbfb8aa3b, v41
	v_exp_f32_e32 v41, v41
	v_lshl_add_u64 v[14:15], v[14:15], 0, v[4:5]
	v_cvt_pk_bf16_f32 v44, v13, v52
	v_cvt_pk_bf16_f32 v45, v53, v54
	v_cvt_pk_bf16_f32 v46, v55, v47
	v_cvt_pk_bf16_f32 v47, v56, v57
	v_add_f32_e32 v40, 1.0, v40
	global_store_dwordx4 v[14:15], v[44:47], off sc1
	v_mul_f32_e32 v13, s48, v48
	v_mul_f32_e32 v48, s48, v49
	v_rcp_f32_e32 v47, v40
	v_add_f32_e32 v40, 1.0, v41
	v_mul_f32_e32 v41, s48, v42
	v_mul_f32_e32 v45, s48, v50
	v_mul_f32_e32 v46, s48, v51
	v_mul_f32_e32 v41, 0xbfb8aa3b, v41
	v_mul_f32_e32 v42, s48, v43
	v_mul_f32_e32 v13, 0xbfb8aa3b, v13
	v_mul_f32_e32 v48, 0xbfb8aa3b, v48
	v_mul_f32_e32 v45, 0xbfb8aa3b, v45
	v_mul_f32_e32 v46, 0xbfb8aa3b, v46
	v_exp_f32_e32 v41, v41
	v_mul_f32_e32 v42, 0xbfb8aa3b, v42
	v_exp_f32_e32 v13, v13
	v_exp_f32_e32 v48, v48
	v_exp_f32_e32 v45, v45
	v_exp_f32_e32 v46, v46
	v_exp_f32_e32 v42, v42
	v_rcp_f32_e32 v43, v40
	v_add_f32_e32 v40, 1.0, v41
	v_add_f32_e32 v13, 1.0, v13
	v_add_f32_e32 v44, 1.0, v48
	v_add_f32_e32 v45, 1.0, v45
	v_add_f32_e32 v46, 1.0, v46
	v_rcp_f32_e32 v48, v40
	v_add_f32_e32 v40, 1.0, v42
	v_rcp_f32_e32 v13, v13
	v_rcp_f32_e32 v44, v44
	v_rcp_f32_e32 v45, v45
	v_rcp_f32_e32 v46, v46
	v_rcp_f32_e32 v49, v40
	v_cvt_pk_bf16_f32 v40, v13, v44
	v_cvt_pk_bf16_f32 v42, v47, v43
	v_cvt_pk_bf16_f32 v41, v45, v46
	v_cvt_pk_bf16_f32 v43, v48, v49
	global_store_dwordx4 v[14:15], v[40:43], off offset:256 sc1
	v_mul_f32_e32 v32, s48, v32
	v_mul_f32_e32 v32, 0xbfb8aa3b, v32
	v_mul_f32_e32 v33, s48, v33
	v_exp_f32_e32 v32, v32
	v_mul_f32_e32 v33, 0xbfb8aa3b, v33
	v_add_u32_e32 v13, 0xa0, v12
	v_exp_f32_e32 v33, v33
	v_mad_u64_u32 v[14:15], s[4:5], v13, s21, v[6:7]
	v_mul_f32_e32 v13, s48, v36
	v_mul_f32_e32 v36, s48, v37
	v_mul_f32_e32 v13, 0xbfb8aa3b, v13
	v_mul_f32_e32 v36, 0xbfb8aa3b, v36
	v_exp_f32_e32 v13, v13
	v_exp_f32_e32 v36, v36
	v_add_f32_e32 v32, 1.0, v32
	v_mul_f32_e32 v37, s48, v38
	v_mul_f32_e32 v38, s48, v39
	v_rcp_f32_e32 v39, v32
	v_add_f32_e32 v32, 1.0, v33
	v_mul_f32_e32 v33, s48, v34
	v_mul_f32_e32 v33, 0xbfb8aa3b, v33
	v_mul_f32_e32 v34, s48, v35
	v_mul_f32_e32 v20, s48, v20
	v_exp_f32_e32 v33, v33
	v_mul_f32_e32 v34, 0xbfb8aa3b, v34
	v_mul_f32_e32 v20, 0xbfb8aa3b, v20
	v_mul_f32_e32 v21, s48, v21
	v_add_f32_e32 v13, 1.0, v13
	v_add_f32_e32 v36, 1.0, v36
	v_exp_f32_e32 v34, v34
	v_exp_f32_e32 v20, v20
	v_mul_f32_e32 v21, 0xbfb8aa3b, v21
	v_rcp_f32_e32 v13, v13
	v_mul_f32_e32 v37, 0xbfb8aa3b, v37
	v_mul_f32_e32 v38, 0xbfb8aa3b, v38
	v_rcp_f32_e32 v36, v36
	v_exp_f32_e32 v21, v21
	v_exp_f32_e32 v37, v37
	v_exp_f32_e32 v38, v38
	v_rcp_f32_e32 v35, v32
	v_add_f32_e32 v32, 1.0, v33
	v_rcp_f32_e32 v40, v32
	v_add_f32_e32 v32, 1.0, v34
	v_add_f32_e32 v20, 1.0, v20
	v_rcp_f32_e32 v41, v32
	v_cvt_pk_bf16_f32 v32, v13, v36
	v_mul_f32_e32 v13, s48, v28
	v_mul_f32_e32 v28, s48, v29
	v_mul_f32_e32 v29, s48, v30
	v_mul_f32_e32 v30, s48, v31
	v_rcp_f32_e32 v31, v20
	v_add_f32_e32 v20, 1.0, v21
	v_mul_f32_e32 v21, s48, v22
	v_add_f32_e32 v37, 1.0, v37
	v_add_f32_e32 v38, 1.0, v38
	v_mul_f32_e32 v21, 0xbfb8aa3b, v21
	v_mul_f32_e32 v22, s48, v23
	v_rcp_f32_e32 v37, v37
	v_rcp_f32_e32 v38, v38
	v_mul_f32_e32 v13, 0xbfb8aa3b, v13
	v_mul_f32_e32 v28, 0xbfb8aa3b, v28
	v_mul_f32_e32 v29, 0xbfb8aa3b, v29
	v_mul_f32_e32 v30, 0xbfb8aa3b, v30
	v_exp_f32_e32 v21, v21
	v_mul_f32_e32 v22, 0xbfb8aa3b, v22
	v_exp_f32_e32 v13, v13
	v_exp_f32_e32 v28, v28
	v_exp_f32_e32 v29, v29
	v_exp_f32_e32 v30, v30
	v_exp_f32_e32 v22, v22
	v_lshl_add_u64 v[14:15], v[14:15], 0, v[4:5]
	v_cvt_pk_bf16_f32 v33, v37, v38
	v_cvt_pk_bf16_f32 v34, v39, v35
	v_cvt_pk_bf16_f32 v35, v40, v41
	v_rcp_f32_e32 v23, v20
	v_add_f32_e32 v20, 1.0, v21
	global_store_dwordx4 v[14:15], v[32:35], off sc1
	v_add_f32_e32 v13, 1.0, v13
	v_add_f32_e32 v28, 1.0, v28
	v_add_f32_e32 v29, 1.0, v29
	v_add_f32_e32 v30, 1.0, v30
	v_rcp_f32_e32 v32, v20
	v_add_f32_e32 v20, 1.0, v22
	v_rcp_f32_e32 v13, v13
	v_rcp_f32_e32 v28, v28
	v_rcp_f32_e32 v29, v29
	v_rcp_f32_e32 v30, v30
	v_rcp_f32_e32 v33, v20
	v_cvt_pk_bf16_f32 v20, v13, v28
	v_cvt_pk_bf16_f32 v22, v31, v23
	v_cvt_pk_bf16_f32 v21, v29, v30
	v_cvt_pk_bf16_f32 v23, v32, v33
	global_store_dwordx4 v[14:15], v[20:23], off offset:256 sc1
	v_add_u32_e32 v12, 0xb0, v12
	v_mad_u64_u32 v[6:7], s[4:5], v12, s21, v[6:7]
	v_mul_f32_e32 v12, s48, v24
	v_mul_f32_e32 v12, 0xbfb8aa3b, v12
	v_exp_f32_e32 v14, v12
	v_mul_f32_e32 v12, s48, v25
	v_mul_f32_e32 v12, 0xbfb8aa3b, v12
	v_exp_f32_e32 v15, v12
	v_lshl_add_u64 v[12:13], v[6:7], 0, v[4:5]
	v_add_f32_e32 v4, 1.0, v14
	v_mul_f32_e32 v6, s48, v26
	v_add_f32_e32 v5, 1.0, v15
	v_mul_f32_e32 v7, s48, v27
	v_mul_f32_e32 v14, s48, v16
	v_mul_f32_e32 v15, s48, v17
	v_mul_f32_e32 v16, s48, v18
	v_mul_f32_e32 v17, s48, v19
	v_mul_f32_e32 v6, 0xbfb8aa3b, v6
	v_mul_f32_e32 v7, 0xbfb8aa3b, v7
	v_mul_f32_e32 v14, 0xbfb8aa3b, v14
	v_mul_f32_e32 v15, 0xbfb8aa3b, v15
	v_mul_f32_e32 v16, 0xbfb8aa3b, v16
	v_mul_f32_e32 v17, 0xbfb8aa3b, v17
	v_exp_f32_e32 v6, v6
	v_exp_f32_e32 v7, v7
	v_exp_f32_e32 v14, v14
	v_exp_f32_e32 v15, v15
	v_exp_f32_e32 v16, v16
	v_exp_f32_e32 v17, v17
	v_mul_f32_e32 v0, s48, v0
	v_add_f32_e32 v6, 1.0, v6
	v_add_f32_e32 v7, 1.0, v7
	v_add_f32_e32 v14, 1.0, v14
	v_add_f32_e32 v15, 1.0, v15
	v_add_f32_e32 v16, 1.0, v16
	v_add_f32_e32 v17, 1.0, v17
	v_mul_f32_e32 v8, s48, v8
	v_mul_f32_e32 v0, 0xbfb8aa3b, v0
	v_mul_f32_e32 v1, s48, v1
	v_rcp_f32_e32 v4, v4
	v_rcp_f32_e32 v5, v5
	v_rcp_f32_e32 v6, v6
	v_rcp_f32_e32 v7, v7
	v_rcp_f32_e32 v14, v14
	v_rcp_f32_e32 v15, v15
	v_rcp_f32_e32 v16, v16
	v_rcp_f32_e32 v17, v17
	v_mul_f32_e32 v8, 0xbfb8aa3b, v8
	v_exp_f32_e32 v0, v0
	v_mul_f32_e32 v1, 0xbfb8aa3b, v1
	v_exp_f32_e32 v8, v8
	v_exp_f32_e32 v1, v1
	v_cvt_pk_bf16_f32 v4, v4, v5
	v_cvt_pk_bf16_f32 v5, v6, v7
	v_cvt_pk_bf16_f32 v6, v14, v15
	v_cvt_pk_bf16_f32 v7, v16, v17
	v_add_f32_e32 v0, 1.0, v0
	global_store_dwordx4 v[12:13], v[4:7], off sc1
	v_mul_f32_e32 v9, s48, v9
	v_mul_f32_e32 v9, 0xbfb8aa3b, v9
	v_add_f32_e32 v4, 1.0, v8
	v_rcp_f32_e32 v8, v0
	v_add_f32_e32 v0, 1.0, v1
	v_mul_f32_e32 v1, s48, v2
	v_mul_f32_e32 v6, s48, v10
	v_mul_f32_e32 v7, s48, v11
	v_mul_f32_e32 v1, 0xbfb8aa3b, v1
	v_mul_f32_e32 v2, s48, v3
	v_mul_f32_e32 v6, 0xbfb8aa3b, v6
	v_mul_f32_e32 v7, 0xbfb8aa3b, v7
	v_exp_f32_e32 v1, v1
	v_mul_f32_e32 v2, 0xbfb8aa3b, v2
	v_exp_f32_e32 v9, v9
	v_exp_f32_e32 v6, v6
	v_exp_f32_e32 v7, v7
	v_exp_f32_e32 v2, v2
	v_rcp_f32_e32 v3, v0
	v_add_f32_e32 v0, 1.0, v1
	v_add_f32_e32 v5, 1.0, v9
	v_add_f32_e32 v6, 1.0, v6
	v_add_f32_e32 v7, 1.0, v7
	v_rcp_f32_e32 v9, v0
	v_add_f32_e32 v0, 1.0, v2
	v_rcp_f32_e32 v4, v4
	v_rcp_f32_e32 v5, v5
	v_rcp_f32_e32 v6, v6
	v_rcp_f32_e32 v7, v7
	v_rcp_f32_e32 v10, v0
	v_cvt_pk_bf16_f32 v0, v4, v5
	v_cvt_pk_bf16_f32 v2, v8, v3
	v_cvt_pk_bf16_f32 v1, v6, v7
	v_cvt_pk_bf16_f32 v3, v9, v10
	s_andn2_b64 vcc, exec, s[28:29]
	s_mov_b64 s[4:5], -1
	global_store_dwordx4 v[12:13], v[0:3], off offset:256 sc1
	s_cbranch_vccnz .LBB0_309
	s_andn2_b64 vcc, exec, s[16:17]
	s_cbranch_vccnz .LBB0_308
	s_barrier
	s_branch .LBB0_308

.LBB0_688:
	v_mbcnt_lo_u32_b32 v128, -1, 0
	v_mbcnt_hi_u32_b32 v128, -1, v128
	s_nop 0
	v_and_or_b32 v144, v128, 15, s3
	v_ashrrev_i32_e32 v128, 1, v128
	v_and_b32_e32 v128, -8, v128
	v_add_u32_e32 v128, s56, v128
	v_ashrrev_i32_e32 v129, 31, v128
	v_lshlrev_b64 v[128:129], 1, v[128:129]
	v_mov_b64_e32 v[132:133], s[36:37]
	v_mad_u64_u32 v[140:141], s[4:5], v144, s19, v[132:133]
	v_pk_mul_f32 v[122:123], s[0:1], v[122:123] op_sel_hi:[0,1]
	v_pk_mul_f32 v[120:121], s[0:1], v[120:121] op_sel_hi:[0,1]
	v_pk_mul_f32 v[142:143], s[0:1], v[114:115] op_sel_hi:[0,1]
	v_pk_mul_f32 v[114:115], s[0:1], v[112:113] op_sel_hi:[0,1]
	v_lshl_add_u64 v[140:141], v[140:141], 0, v[128:129]
	v_cvt_pk_bf16_f32 v112, v120, v121
	v_cvt_pk_bf16_f32 v113, v122, v123
	v_cvt_pk_bf16_f32 v114, v114, v115
	v_cvt_pk_bf16_f32 v115, v142, v143
	global_store_dwordx4 v[140:141], v[112:115], off sc1
	v_pk_mul_f32 v[118:119], s[0:1], v[118:119] op_sel_hi:[0,1]
	v_pk_mul_f32 v[116:117], s[0:1], v[116:117] op_sel_hi:[0,1]
	v_pk_mul_f32 v[114:115], s[0:1], v[126:127] op_sel_hi:[0,1]
	v_pk_mul_f32 v[112:113], s[0:1], v[124:125] op_sel_hi:[0,1]
	v_cvt_pk_bf16_f32 v112, v112, v113
	v_cvt_pk_bf16_f32 v113, v114, v115
	v_cvt_pk_bf16_f32 v114, v116, v117
	v_cvt_pk_bf16_f32 v115, v118, v119
	global_store_dwordx4 v[140:141], v[112:115], off offset:256 sc1
	s_nop 1
	v_or_b32_e32 v112, 16, v144
	v_mad_u64_u32 v[112:113], s[4:5], v112, s19, v[132:133]
	v_pk_mul_f32 v[106:107], s[0:1], v[106:107] op_sel_hi:[0,1]
	v_pk_mul_f32 v[104:105], s[0:1], v[104:105] op_sel_hi:[0,1]
	v_pk_mul_f32 v[114:115], s[0:1], v[98:99] op_sel_hi:[0,1]
	v_pk_mul_f32 v[98:99], s[0:1], v[96:97] op_sel_hi:[0,1]
	v_lshl_add_u64 v[112:113], v[112:113], 0, v[128:129]
	v_cvt_pk_bf16_f32 v96, v104, v105
	v_cvt_pk_bf16_f32 v97, v106, v107
	v_cvt_pk_bf16_f32 v98, v98, v99
	v_cvt_pk_bf16_f32 v99, v114, v115
	global_store_dwordx4 v[112:113], v[96:99], off sc1
	v_pk_mul_f32 v[102:103], s[0:1], v[102:103] op_sel_hi:[0,1]
	v_pk_mul_f32 v[100:101], s[0:1], v[100:101] op_sel_hi:[0,1]
	v_pk_mul_f32 v[98:99], s[0:1], v[110:111] op_sel_hi:[0,1]
	v_pk_mul_f32 v[96:97], s[0:1], v[108:109] op_sel_hi:[0,1]
	v_cvt_pk_bf16_f32 v96, v96, v97
	v_cvt_pk_bf16_f32 v97, v98, v99
	v_cvt_pk_bf16_f32 v98, v100, v101
	v_cvt_pk_bf16_f32 v99, v102, v103
	global_store_dwordx4 v[112:113], v[96:99], off offset:256 sc1
	s_nop 1
	v_or_b32_e32 v96, 32, v144
	v_mad_u64_u32 v[96:97], s[4:5], v96, s19, v[132:133]
	v_pk_mul_f32 v[74:75], s[0:1], v[74:75] op_sel_hi:[0,1]
	v_pk_mul_f32 v[72:73], s[0:1], v[72:73] op_sel_hi:[0,1]
	v_pk_mul_f32 v[98:99], s[0:1], v[66:67] op_sel_hi:[0,1]
	v_pk_mul_f32 v[66:67], s[0:1], v[64:65] op_sel_hi:[0,1]
	v_lshl_add_u64 v[96:97], v[96:97], 0, v[128:129]
	v_cvt_pk_bf16_f32 v64, v72, v73
	v_cvt_pk_bf16_f32 v65, v74, v75
	v_cvt_pk_bf16_f32 v66, v66, v67
	v_cvt_pk_bf16_f32 v67, v98, v99
	global_store_dwordx4 v[96:97], v[64:67], off sc1
	v_pk_mul_f32 v[70:71], s[0:1], v[70:71] op_sel_hi:[0,1]
	v_pk_mul_f32 v[68:69], s[0:1], v[68:69] op_sel_hi:[0,1]
	v_pk_mul_f32 v[66:67], s[0:1], v[78:79] op_sel_hi:[0,1]
	v_pk_mul_f32 v[64:65], s[0:1], v[76:77] op_sel_hi:[0,1]
	v_cvt_pk_bf16_f32 v64, v64, v65
	v_cvt_pk_bf16_f32 v65, v66, v67
	v_cvt_pk_bf16_f32 v66, v68, v69
	v_cvt_pk_bf16_f32 v67, v70, v71
	global_store_dwordx4 v[96:97], v[64:67], off offset:256 sc1
	s_nop 1
	v_or_b32_e32 v64, 48, v144
	v_mad_u64_u32 v[64:65], s[4:5], v64, s19, v[132:133]
	v_pk_mul_f32 v[42:43], s[0:1], v[42:43] op_sel_hi:[0,1]
	v_pk_mul_f32 v[40:41], s[0:1], v[40:41] op_sel_hi:[0,1]
	v_pk_mul_f32 v[66:67], s[0:1], v[34:35] op_sel_hi:[0,1]
	v_pk_mul_f32 v[34:35], s[0:1], v[32:33] op_sel_hi:[0,1]
	v_lshl_add_u64 v[64:65], v[64:65], 0, v[128:129]
	v_cvt_pk_bf16_f32 v32, v40, v41
	v_cvt_pk_bf16_f32 v33, v42, v43
	v_cvt_pk_bf16_f32 v34, v34, v35
	v_cvt_pk_bf16_f32 v35, v66, v67
	global_store_dwordx4 v[64:65], v[32:35], off sc1
	v_pk_mul_f32 v[38:39], s[0:1], v[38:39] op_sel_hi:[0,1]
	v_pk_mul_f32 v[36:37], s[0:1], v[36:37] op_sel_hi:[0,1]
	v_pk_mul_f32 v[34:35], s[0:1], v[46:47] op_sel_hi:[0,1]
	v_pk_mul_f32 v[32:33], s[0:1], v[44:45] op_sel_hi:[0,1]
	v_cvt_pk_bf16_f32 v32, v32, v33
	v_cvt_pk_bf16_f32 v33, v34, v35
	v_cvt_pk_bf16_f32 v34, v36, v37
	v_cvt_pk_bf16_f32 v35, v38, v39
	global_store_dwordx4 v[64:65], v[32:35], off offset:256 sc1
	s_nop 1
	v_add_u32_e32 v32, 0x80, v144
	v_mad_u64_u32 v[32:33], s[4:5], v32, s19, v[132:133]
	v_lshl_add_u64 v[36:37], v[32:33], 0, v[128:129]
	v_pk_mul_f32 v[34:35], s[0:1], v[90:91] op_sel_hi:[0,1]
	v_pk_mul_f32 v[32:33], s[0:1], v[88:89] op_sel_hi:[0,1]
	v_pk_mul_f32 v[38:39], s[0:1], v[82:83] op_sel_hi:[0,1]
	v_pk_mul_f32 v[40:41], s[0:1], v[80:81] op_sel_hi:[0,1]
	v_cvt_pk_bf16_f32 v32, v32, v33
	v_cvt_pk_bf16_f32 v33, v34, v35
	v_cvt_pk_bf16_f32 v34, v40, v41
	v_cvt_pk_bf16_f32 v35, v38, v39
	global_store_dwordx4 v[36:37], v[32:35], off sc1
	v_pk_mul_f32 v[38:39], s[0:1], v[86:87] op_sel_hi:[0,1]
	v_pk_mul_f32 v[40:41], s[0:1], v[84:85] op_sel_hi:[0,1]
	v_pk_mul_f32 v[34:35], s[0:1], v[94:95] op_sel_hi:[0,1]
	v_pk_mul_f32 v[32:33], s[0:1], v[92:93] op_sel_hi:[0,1]
	v_cvt_pk_bf16_f32 v32, v32, v33
	v_cvt_pk_bf16_f32 v33, v34, v35
	v_cvt_pk_bf16_f32 v34, v40, v41
	v_cvt_pk_bf16_f32 v35, v38, v39
	global_store_dwordx4 v[36:37], v[32:35], off offset:256 sc1
	s_nop 1
	v_add_u32_e32 v32, 0x90, v144
	v_mad_u64_u32 v[32:33], s[4:5], v32, s19, v[132:133]
	v_lshl_add_u64 v[36:37], v[32:33], 0, v[128:129]
	v_pk_mul_f32 v[34:35], s[0:1], v[58:59] op_sel_hi:[0,1]
	v_pk_mul_f32 v[32:33], s[0:1], v[56:57] op_sel_hi:[0,1]
	v_pk_mul_f32 v[38:39], s[0:1], v[50:51] op_sel_hi:[0,1]
	v_pk_mul_f32 v[40:41], s[0:1], v[48:49] op_sel_hi:[0,1]
	v_cvt_pk_bf16_f32 v32, v32, v33
	v_cvt_pk_bf16_f32 v33, v34, v35
	v_cvt_pk_bf16_f32 v34, v40, v41
	v_cvt_pk_bf16_f32 v35, v38, v39
	global_store_dwordx4 v[36:37], v[32:35], off sc1
	v_pk_mul_f32 v[38:39], s[0:1], v[54:55] op_sel_hi:[0,1]
	v_pk_mul_f32 v[40:41], s[0:1], v[52:53] op_sel_hi:[0,1]
	v_pk_mul_f32 v[34:35], s[0:1], v[62:63] op_sel_hi:[0,1]
	v_pk_mul_f32 v[32:33], s[0:1], v[60:61] op_sel_hi:[0,1]
	v_cvt_pk_bf16_f32 v32, v32, v33
	v_cvt_pk_bf16_f32 v33, v34, v35
	v_cvt_pk_bf16_f32 v34, v40, v41
	v_cvt_pk_bf16_f32 v35, v38, v39
	global_store_dwordx4 v[36:37], v[32:35], off offset:256 sc1
	s_nop 1
	v_add_u32_e32 v32, 0xa0, v144
	v_mad_u64_u32 v[32:33], s[4:5], v32, s19, v[132:133]
	v_pk_mul_f32 v[26:27], s[0:1], v[26:27] op_sel_hi:[0,1]
	v_pk_mul_f32 v[24:25], s[0:1], v[24:25] op_sel_hi:[0,1]
	v_pk_mul_f32 v[34:35], s[0:1], v[18:19] op_sel_hi:[0,1]
	v_pk_mul_f32 v[18:19], s[0:1], v[16:17] op_sel_hi:[0,1]
	v_lshl_add_u64 v[32:33], v[32:33], 0, v[128:129]
	v_cvt_pk_bf16_f32 v16, v24, v25
	v_cvt_pk_bf16_f32 v17, v26, v27
	v_cvt_pk_bf16_f32 v18, v18, v19
	v_cvt_pk_bf16_f32 v19, v34, v35
	global_store_dwordx4 v[32:33], v[16:19], off sc1
	v_pk_mul_f32 v[22:23], s[0:1], v[22:23] op_sel_hi:[0,1]
	v_pk_mul_f32 v[20:21], s[0:1], v[20:21] op_sel_hi:[0,1]
	v_pk_mul_f32 v[18:19], s[0:1], v[30:31] op_sel_hi:[0,1]
	v_pk_mul_f32 v[16:17], s[0:1], v[28:29] op_sel_hi:[0,1]
	v_cvt_pk_bf16_f32 v16, v16, v17
	v_cvt_pk_bf16_f32 v17, v18, v19
	v_cvt_pk_bf16_f32 v18, v20, v21
	v_cvt_pk_bf16_f32 v19, v22, v23
	global_store_dwordx4 v[32:33], v[16:19], off offset:256 sc1
	s_nop 1
	v_add_u32_e32 v16, 0xb0, v144
	v_mad_u64_u32 v[16:17], s[4:5], v16, s19, v[132:133]
	v_pk_mul_f32 v[10:11], s[0:1], v[10:11] op_sel_hi:[0,1]
	v_pk_mul_f32 v[8:9], s[0:1], v[8:9] op_sel_hi:[0,1]
	v_pk_mul_f32 v[18:19], s[0:1], v[2:3] op_sel_hi:[0,1]
	v_pk_mul_f32 v[2:3], s[0:1], v[0:1] op_sel_hi:[0,1]
	v_lshl_add_u64 v[16:17], v[16:17], 0, v[128:129]
	v_cvt_pk_bf16_f32 v0, v8, v9
	v_cvt_pk_bf16_f32 v1, v10, v11
	v_cvt_pk_bf16_f32 v2, v2, v3
	v_cvt_pk_bf16_f32 v3, v18, v19
	global_store_dwordx4 v[16:17], v[0:3], off sc1
	v_pk_mul_f32 v[6:7], s[0:1], v[6:7] op_sel_hi:[0,1]
	v_pk_mul_f32 v[4:5], s[0:1], v[4:5] op_sel_hi:[0,1]
	v_pk_mul_f32 v[2:3], s[0:1], v[14:15] op_sel_hi:[0,1]
	v_pk_mul_f32 v[0:1], s[0:1], v[12:13] op_sel_hi:[0,1]
	v_cvt_pk_bf16_f32 v0, v0, v1
	v_cvt_pk_bf16_f32 v1, v2, v3
	v_cvt_pk_bf16_f32 v2, v4, v5
	v_cvt_pk_bf16_f32 v3, v6, v7
	s_andn2_b64 vcc, exec, s[34:35]
	s_mov_b64 s[4:5], -1
	global_store_dwordx4 v[16:17], v[0:3], off offset:256 sc1
	s_cbranch_vccnz .LBB0_678
	s_andn2_b64 vcc, exec, s[20:21]
	s_cbranch_vccnz .LBB0_677
	s_barrier
	s_branch .LBB0_677

.LBB0_707:
	s_bitcmp1_b32 s2, 0
	s_cselect_b64 s[4:5], -1, 0
	s_and_b64 vcc, exec, s[4:5]
	s_cbranch_vccz .LBB0_710
	v_mbcnt_lo_u32_b32 v1, -1, 0
	v_mbcnt_hi_u32_b32 v1, -1, v1
	s_nop 0
	v_and_or_b32 v151, v1, 15, s3
	v_ashrrev_i32_e32 v1, 1, v1
	v_and_b32_e32 v1, -8, v1
	v_add_u32_e32 v10, s56, v1
	v_ashrrev_i32_e32 v11, 31, v10
	v_lshlrev_b64 v[10:11], 1, v[10:11]
	v_lshl_add_u64 v[18:19], s[42:43], 0, v[10:11]
	v_mad_u64_u32 v[16:17], s[4:5], v151, s45, v[18:19]
	global_load_dwordx4 v[24:27], v[16:17], off
	global_load_dwordx4 v[140:143], v[16:17], off offset:256
	v_or_b32_e32 v1, 16, v151
	v_mad_u64_u32 v[16:17], s[4:5], v1, s45, v[18:19]
	global_load_dwordx4 v[152:155], v[16:17], off
	global_load_dwordx4 v[156:159], v[16:17], off offset:256
	v_or_b32_e32 v196, 32, v151
	v_mad_u64_u32 v[146:147], s[4:5], v196, s45, v[18:19]
	global_load_dwordx4 v[160:163], v[146:147], off
	v_or_b32_e32 v197, 48, v151
	v_mad_u64_u32 v[172:173], s[4:5], v197, s45, v[18:19]
	global_load_dwordx4 v[164:167], v[146:147], off offset:256
	global_load_dwordx4 v[168:171], v[172:173], off
	s_nop 0
	global_load_dwordx4 v[172:175], v[172:173], off offset:256
	v_mov_b64_e32 v[16:17], s[8:9]
	v_mad_u64_u32 v[176:177], s[4:5], v151, s44, v[16:17]
	v_mad_u64_u32 v[178:179], s[4:5], v1, s44, v[16:17]
	v_lshl_add_u64 v[146:147], v[176:177], 0, v[10:11]
	v_lshl_add_u64 v[176:177], v[178:179], 0, v[10:11]
	s_waitcnt vmcnt(7)
	v_lshlrev_b32_e32 v178, 16, v24
	v_and_b32_e32 v179, 0xffff0000, v24
	v_lshlrev_b32_e32 v24, 16, v25
	v_and_b32_e32 v25, 0xffff0000, v25
	v_lshlrev_b32_e32 v180, 16, v26
	v_and_b32_e32 v181, 0xffff0000, v26
	v_lshlrev_b32_e32 v26, 16, v27
	v_and_b32_e32 v27, 0xffff0000, v27
	s_waitcnt vmcnt(6)
	v_lshlrev_b32_e32 v182, 16, v140
	v_and_b32_e32 v183, 0xffff0000, v140
	v_lshlrev_b32_e32 v140, 16, v141
	v_and_b32_e32 v141, 0xffff0000, v141
	v_lshlrev_b32_e32 v184, 16, v142
	v_and_b32_e32 v185, 0xffff0000, v142
	v_lshlrev_b32_e32 v142, 16, v143
	v_and_b32_e32 v143, 0xffff0000, v143
	s_waitcnt vmcnt(5)
	v_lshlrev_b32_e32 v186, 16, v152
	v_and_b32_e32 v187, 0xffff0000, v152
	v_lshlrev_b32_e32 v152, 16, v153
	v_and_b32_e32 v153, 0xffff0000, v153
	v_lshlrev_b32_e32 v188, 16, v154
	v_and_b32_e32 v189, 0xffff0000, v154
	v_lshlrev_b32_e32 v154, 16, v155
	v_and_b32_e32 v155, 0xffff0000, v155
	v_pk_mul_f32 v[194:195], v[4:5], v[24:25]
	v_pk_mul_f32 v[24:25], v[2:3], v[178:179]
	v_pk_mul_f32 v[178:179], v[8:9], v[26:27]
	v_pk_mul_f32 v[26:27], v[6:7], v[180:181]
	v_pk_mul_f32 v[180:181], v[82:83], v[140:141]
	v_pk_mul_f32 v[140:141], v[80:81], v[182:183]
	v_pk_mul_f32 v[182:183], v[90:91], v[142:143]
	v_pk_mul_f32 v[142:143], v[88:89], v[184:185]
	s_waitcnt vmcnt(4)
	v_lshlrev_b32_e32 v190, 16, v156
	v_and_b32_e32 v191, 0xffff0000, v156
	v_lshlrev_b32_e32 v156, 16, v157
	v_and_b32_e32 v157, 0xffff0000, v157
	v_lshlrev_b32_e32 v192, 16, v158
	v_and_b32_e32 v193, 0xffff0000, v158
	v_lshlrev_b32_e32 v158, 16, v159
	v_and_b32_e32 v159, 0xffff0000, v159
	v_pk_mul_f32 v[184:185], v[30:31], v[152:153]
	v_pk_mul_f32 v[152:153], v[28:29], v[186:187]
	v_pk_mul_f32 v[186:187], v[34:35], v[154:155]
	v_pk_mul_f32 v[154:155], v[32:33], v[188:189]
	v_cvt_pk_bf16_f32 v24, v24, v25
	v_cvt_pk_bf16_f32 v25, v194, v195
	v_cvt_pk_bf16_f32 v26, v26, v27
	v_cvt_pk_bf16_f32 v27, v178, v179
	v_cvt_pk_bf16_f32 v140, v140, v141
	v_cvt_pk_bf16_f32 v141, v180, v181
	v_cvt_pk_bf16_f32 v142, v142, v143
	v_cvt_pk_bf16_f32 v143, v182, v183
	v_cvt_pk_bf16_f32 v152, v152, v153
	v_cvt_pk_bf16_f32 v153, v184, v185
	v_cvt_pk_bf16_f32 v154, v154, v155
	v_cvt_pk_bf16_f32 v155, v186, v187
	global_store_dwordx4 v[146:147], v[24:27], off sc1
	global_store_dwordx4 v[146:147], v[140:143], off offset:256 sc1
	global_store_dwordx4 v[176:177], v[152:155], off sc1
	v_pk_mul_f32 v[26:27], v[46:47], v[156:157]
	v_pk_mul_f32 v[24:25], v[44:45], v[190:191]
	v_pk_mul_f32 v[140:141], v[50:51], v[158:159]
	v_pk_mul_f32 v[142:143], v[48:49], v[192:193]
	v_cvt_pk_bf16_f32 v24, v24, v25
	v_cvt_pk_bf16_f32 v25, v26, v27
	v_cvt_pk_bf16_f32 v26, v142, v143
	v_cvt_pk_bf16_f32 v27, v140, v141
	global_store_dwordx4 v[176:177], v[24:27], off offset:256 sc1
	s_waitcnt vmcnt(7)
	v_lshlrev_b32_e32 v142, 16, v162
	v_and_b32_e32 v143, 0xffff0000, v162
	v_mad_u64_u32 v[24:25], s[4:5], v196, s44, v[16:17]
	v_lshl_add_u64 v[140:141], v[24:25], 0, v[10:11]
	v_lshlrev_b32_e32 v24, 16, v160
	v_and_b32_e32 v25, 0xffff0000, v160
	v_lshlrev_b32_e32 v26, 16, v161
	v_and_b32_e32 v27, 0xffff0000, v161
	v_lshlrev_b32_e32 v146, 16, v163
	v_and_b32_e32 v147, 0xffff0000, v163
	v_pk_mul_f32 v[26:27], v[70:71], v[26:27]
	v_pk_mul_f32 v[24:25], v[68:69], v[24:25]
	v_pk_mul_f32 v[146:147], v[74:75], v[146:147]
	v_pk_mul_f32 v[142:143], v[72:73], v[142:143]
	v_cvt_pk_bf16_f32 v24, v24, v25
	v_cvt_pk_bf16_f32 v25, v26, v27
	v_cvt_pk_bf16_f32 v26, v142, v143
	v_cvt_pk_bf16_f32 v27, v146, v147
	global_store_dwordx4 v[140:141], v[24:27], off sc1
	s_waitcnt vmcnt(7)
	v_lshlrev_b32_e32 v142, 16, v166
	v_and_b32_e32 v143, 0xffff0000, v166
	v_lshlrev_b32_e32 v24, 16, v164
	v_and_b32_e32 v25, 0xffff0000, v164
	v_lshlrev_b32_e32 v26, 16, v165
	v_and_b32_e32 v27, 0xffff0000, v165
	v_lshlrev_b32_e32 v146, 16, v167
	v_and_b32_e32 v147, 0xffff0000, v167
	v_pk_mul_f32 v[26:27], v[134:135], v[26:27]
	v_pk_mul_f32 v[24:25], v[132:133], v[24:25]
	v_pk_mul_f32 v[146:147], v[138:139], v[146:147]
	v_pk_mul_f32 v[142:143], v[136:137], v[142:143]
	v_cvt_pk_bf16_f32 v24, v24, v25
	v_cvt_pk_bf16_f32 v25, v26, v27
	v_cvt_pk_bf16_f32 v26, v142, v143
	v_cvt_pk_bf16_f32 v27, v146, v147
	global_store_dwordx4 v[140:141], v[24:27], off offset:256 sc1
	s_waitcnt vmcnt(7)
	v_lshlrev_b32_e32 v142, 16, v170
	v_and_b32_e32 v143, 0xffff0000, v170
	v_mad_u64_u32 v[24:25], s[4:5], v197, s44, v[16:17]
	v_lshl_add_u64 v[140:141], v[24:25], 0, v[10:11]
	v_lshlrev_b32_e32 v24, 16, v168
	v_and_b32_e32 v25, 0xffff0000, v168
	v_lshlrev_b32_e32 v26, 16, v169
	v_and_b32_e32 v27, 0xffff0000, v169
	v_lshlrev_b32_e32 v146, 16, v171
	v_and_b32_e32 v147, 0xffff0000, v171
	v_pk_mul_f32 v[26:27], v[94:95], v[26:27]
	v_pk_mul_f32 v[24:25], v[92:93], v[24:25]
	v_pk_mul_f32 v[146:147], v[98:99], v[146:147]
	v_pk_mul_f32 v[142:143], v[96:97], v[142:143]
	v_cvt_pk_bf16_f32 v24, v24, v25
	v_cvt_pk_bf16_f32 v25, v26, v27
	v_cvt_pk_bf16_f32 v26, v142, v143
	v_cvt_pk_bf16_f32 v27, v146, v147
	global_store_dwordx4 v[140:141], v[24:27], off sc1
	s_waitcnt vmcnt(7)
	v_lshlrev_b32_e32 v142, 16, v174
	v_and_b32_e32 v143, 0xffff0000, v174
	v_lshlrev_b32_e32 v24, 16, v172
	v_and_b32_e32 v25, 0xffff0000, v172
	v_lshlrev_b32_e32 v26, 16, v173
	v_and_b32_e32 v27, 0xffff0000, v173
	v_lshlrev_b32_e32 v146, 16, v175
	v_and_b32_e32 v147, 0xffff0000, v175
	v_pk_mul_f32 v[26:27], v[110:111], v[26:27]
	v_pk_mul_f32 v[24:25], v[108:109], v[24:25]
	v_pk_mul_f32 v[146:147], v[114:115], v[146:147]
	v_pk_mul_f32 v[142:143], v[112:113], v[142:143]
	v_cvt_pk_bf16_f32 v24, v24, v25
	v_cvt_pk_bf16_f32 v25, v26, v27
	v_cvt_pk_bf16_f32 v26, v142, v143
	v_cvt_pk_bf16_f32 v27, v146, v147
	global_store_dwordx4 v[140:141], v[24:27], off offset:256 sc1
	v_add_u32_e32 v1, 0x80, v151
	v_mad_u64_u32 v[140:141], s[4:5], v1, s45, v[18:19]
	global_load_dwordx4 v[24:27], v[140:141], off
	s_nop 0
	global_load_dwordx4 v[140:143], v[140:141], off offset:256
	v_add_u32_e32 v164, 0x90, v151
	v_mad_u64_u32 v[146:147], s[4:5], v164, s45, v[18:19]
	global_load_dwordx4 v[152:155], v[146:147], off
	global_load_dwordx4 v[156:159], v[146:147], off offset:256
	v_add_u32_e32 v194, 0xa0, v151
	v_mad_u64_u32 v[146:147], s[4:5], v194, s45, v[18:19]
	global_load_dwordx4 v[160:163], v[146:147], off
	v_add_u32_e32 v151, 0xb0, v151
	v_mad_u64_u32 v[18:19], s[4:5], v151, s45, v[18:19]
	v_mad_u64_u32 v[178:179], s[4:5], v164, s44, v[16:17]
	global_load_dwordx4 v[164:167], v[146:147], off offset:256
	global_load_dwordx4 v[168:171], v[18:19], off
	global_load_dwordx4 v[172:175], v[18:19], off offset:256
	v_mad_u64_u32 v[176:177], s[4:5], v1, s44, v[16:17]
	v_lshl_add_u64 v[18:19], v[176:177], 0, v[10:11]
	v_lshl_add_u64 v[146:147], v[178:179], 0, v[10:11]
	s_waitcnt vmcnt(7)
	v_lshlrev_b32_e32 v176, 16, v24
	v_and_b32_e32 v177, 0xffff0000, v24
	v_lshlrev_b32_e32 v24, 16, v25
	v_and_b32_e32 v25, 0xffff0000, v25
	v_lshlrev_b32_e32 v178, 16, v26
	v_and_b32_e32 v179, 0xffff0000, v26
	v_lshlrev_b32_e32 v26, 16, v27
	v_and_b32_e32 v27, 0xffff0000, v27
	s_waitcnt vmcnt(6)
	v_lshlrev_b32_e32 v180, 16, v140
	v_and_b32_e32 v181, 0xffff0000, v140
	v_lshlrev_b32_e32 v140, 16, v141
	v_and_b32_e32 v141, 0xffff0000, v141
	v_lshlrev_b32_e32 v182, 16, v142
	v_and_b32_e32 v183, 0xffff0000, v142
	v_lshlrev_b32_e32 v142, 16, v143
	v_and_b32_e32 v143, 0xffff0000, v143
	s_waitcnt vmcnt(5)
	v_lshlrev_b32_e32 v184, 16, v152
	v_and_b32_e32 v185, 0xffff0000, v152
	v_lshlrev_b32_e32 v152, 16, v153
	v_and_b32_e32 v153, 0xffff0000, v153
	v_lshlrev_b32_e32 v186, 16, v154
	v_and_b32_e32 v187, 0xffff0000, v154
	v_lshlrev_b32_e32 v154, 16, v155
	v_and_b32_e32 v155, 0xffff0000, v155
	v_pk_mul_f32 v[192:193], v[118:119], v[24:25]
	v_pk_mul_f32 v[24:25], v[116:117], v[176:177]
	v_pk_mul_f32 v[176:177], v[122:123], v[26:27]
	v_pk_mul_f32 v[26:27], v[120:121], v[178:179]
	v_pk_mul_f32 v[178:179], v[126:127], v[140:141]
	v_pk_mul_f32 v[140:141], v[124:125], v[180:181]
	s_waitcnt vmcnt(4)
	v_lshlrev_b32_e32 v188, 16, v156
	v_and_b32_e32 v189, 0xffff0000, v156
	v_lshlrev_b32_e32 v156, 16, v157
	v_and_b32_e32 v157, 0xffff0000, v157
	v_lshlrev_b32_e32 v190, 16, v158
	v_and_b32_e32 v191, 0xffff0000, v158
	v_lshlrev_b32_e32 v158, 16, v159
	v_and_b32_e32 v159, 0xffff0000, v159
	v_pk_mul_f32 v[180:181], v[130:131], v[142:143]
	v_pk_mul_f32 v[142:143], v[128:129], v[182:183]
	v_pk_mul_f32 v[182:183], v[106:107], v[152:153]
	v_pk_mul_f32 v[152:153], v[104:105], v[184:185]
	v_pk_mul_f32 v[184:185], v[102:103], v[154:155]
	v_pk_mul_f32 v[154:155], v[100:101], v[186:187]
	v_cvt_pk_bf16_f32 v24, v24, v25
	v_cvt_pk_bf16_f32 v25, v192, v193
	v_cvt_pk_bf16_f32 v26, v26, v27
	v_cvt_pk_bf16_f32 v27, v176, v177
	v_cvt_pk_bf16_f32 v140, v140, v141
	v_cvt_pk_bf16_f32 v141, v178, v179
	v_pk_mul_f32 v[156:157], v[86:87], v[156:157]
	v_cvt_pk_bf16_f32 v142, v142, v143
	v_cvt_pk_bf16_f32 v143, v180, v181
	v_cvt_pk_bf16_f32 v152, v152, v153
	v_cvt_pk_bf16_f32 v153, v182, v183
	v_cvt_pk_bf16_f32 v154, v154, v155
	v_cvt_pk_bf16_f32 v155, v184, v185
	global_store_dwordx4 v[18:19], v[24:27], off sc1
	global_store_dwordx4 v[18:19], v[140:143], off offset:256 sc1
	global_store_dwordx4 v[146:147], v[152:155], off sc1
	v_pk_mul_f32 v[18:19], v[84:85], v[188:189]
	v_pk_mul_f32 v[140:141], v[78:79], v[158:159]
	v_pk_mul_f32 v[26:27], v[76:77], v[190:191]
	v_cvt_pk_bf16_f32 v24, v18, v19
	v_cvt_pk_bf16_f32 v25, v156, v157
	v_cvt_pk_bf16_f32 v26, v26, v27
	v_cvt_pk_bf16_f32 v27, v140, v141
	global_store_dwordx4 v[146:147], v[24:27], off offset:256 sc1
	s_waitcnt vmcnt(7)
	v_lshlrev_b32_e32 v140, 16, v162
	v_and_b32_e32 v141, 0xffff0000, v162
	v_lshlrev_b32_e32 v24, 16, v160
	v_and_b32_e32 v25, 0xffff0000, v160
	v_lshlrev_b32_e32 v26, 16, v161
	v_and_b32_e32 v27, 0xffff0000, v161
	v_lshlrev_b32_e32 v142, 16, v163
	v_and_b32_e32 v143, 0xffff0000, v163
	v_mad_u64_u32 v[18:19], s[4:5], v194, s44, v[16:17]
	v_pk_mul_f32 v[26:27], v[54:55], v[26:27]
	v_pk_mul_f32 v[24:25], v[52:53], v[24:25]
	v_pk_mul_f32 v[142:143], v[58:59], v[142:143]
	v_pk_mul_f32 v[140:141], v[56:57], v[140:141]
	v_lshl_add_u64 v[18:19], v[18:19], 0, v[10:11]
	v_cvt_pk_bf16_f32 v24, v24, v25
	v_cvt_pk_bf16_f32 v25, v26, v27
	v_cvt_pk_bf16_f32 v26, v140, v141
	v_cvt_pk_bf16_f32 v27, v142, v143
	global_store_dwordx4 v[18:19], v[24:27], off sc1
	s_waitcnt vmcnt(7)
	v_lshlrev_b32_e32 v140, 16, v166
	v_and_b32_e32 v141, 0xffff0000, v166
	v_lshlrev_b32_e32 v24, 16, v164
	v_and_b32_e32 v25, 0xffff0000, v164
	v_lshlrev_b32_e32 v26, 16, v165
	v_and_b32_e32 v27, 0xffff0000, v165
	v_lshlrev_b32_e32 v142, 16, v167
	v_and_b32_e32 v143, 0xffff0000, v167
	v_pk_mul_f32 v[26:27], v[62:63], v[26:27]
	v_pk_mul_f32 v[24:25], v[60:61], v[24:25]
	v_pk_mul_f32 v[142:143], v[66:67], v[142:143]
	v_pk_mul_f32 v[140:141], v[64:65], v[140:141]
	v_cvt_pk_bf16_f32 v24, v24, v25
	v_cvt_pk_bf16_f32 v25, v26, v27
	v_cvt_pk_bf16_f32 v26, v140, v141
	v_cvt_pk_bf16_f32 v27, v142, v143
	v_mad_u64_u32 v[16:17], s[4:5], v151, s44, v[16:17]
	global_store_dwordx4 v[18:19], v[24:27], off offset:256 sc1
	v_lshl_add_u64 v[10:11], v[16:17], 0, v[10:11]
	s_waitcnt vmcnt(7)
	v_lshlrev_b32_e32 v16, 16, v168
	v_and_b32_e32 v17, 0xffff0000, v168
	v_lshlrev_b32_e32 v18, 16, v169
	v_and_b32_e32 v19, 0xffff0000, v169
	v_lshlrev_b32_e32 v24, 16, v170
	v_and_b32_e32 v25, 0xffff0000, v170
	v_lshlrev_b32_e32 v26, 16, v171
	v_and_b32_e32 v27, 0xffff0000, v171
	v_pk_mul_f32 v[18:19], v[42:43], v[18:19]
	v_pk_mul_f32 v[16:17], v[40:41], v[16:17]
	v_pk_mul_f32 v[26:27], v[38:39], v[26:27]
	v_pk_mul_f32 v[24:25], v[36:37], v[24:25]
	v_cvt_pk_bf16_f32 v16, v16, v17
	v_cvt_pk_bf16_f32 v17, v18, v19
	v_cvt_pk_bf16_f32 v18, v24, v25
	v_cvt_pk_bf16_f32 v19, v26, v27
	global_store_dwordx4 v[10:11], v[16:19], off sc1
	s_waitcnt vmcnt(7)
	v_lshlrev_b32_e32 v24, 16, v174
	v_and_b32_e32 v25, 0xffff0000, v174
	v_lshlrev_b32_e32 v16, 16, v172
	v_and_b32_e32 v17, 0xffff0000, v172
	v_lshlrev_b32_e32 v18, 16, v173
	v_and_b32_e32 v19, 0xffff0000, v173
	v_lshlrev_b32_e32 v26, 16, v175
	v_and_b32_e32 v27, 0xffff0000, v175
	v_pk_mul_f32 v[18:19], v[22:23], v[18:19]
	v_pk_mul_f32 v[16:17], v[20:21], v[16:17]
	v_pk_mul_f32 v[26:27], v[14:15], v[26:27]
	v_pk_mul_f32 v[24:25], v[12:13], v[24:25]
	v_cvt_pk_bf16_f32 v16, v16, v17
	v_cvt_pk_bf16_f32 v17, v18, v19
	v_cvt_pk_bf16_f32 v18, v24, v25
	v_cvt_pk_bf16_f32 v19, v26, v27
	global_store_dwordx4 v[10:11], v[16:19], off offset:256 sc1
	s_mov_b64 s[4:5], s[40:41]
	s_cbranch_execz .LBB0_711
	v_mov_b32_e32 v2, v0
	v_mov_b32_e32 v3, v0
	v_mov_b32_e32 v1, v0
	v_mov_b64_e32 v[26:27], v[2:3]
	v_mov_b64_e32 v[18:19], v[2:3]
	v_mov_b64_e32 v[30:31], v[2:3]
	v_mov_b64_e32 v[34:35], v[2:3]
	v_mov_b64_e32 v[90:91], v[2:3]
	v_mov_b64_e32 v[82:83], v[2:3]
	v_mov_b64_e32 v[94:95], v[2:3]
	v_mov_b64_e32 v[98:99], v[2:3]
	v_mov_b64_e32 v[10:11], v[2:3]
	v_mov_b64_e32 v[6:7], v[2:3]
	v_mov_b64_e32 v[46:47], v[2:3]
	v_mov_b64_e32 v[50:51], v[2:3]
	v_mov_b64_e32 v[74:75], v[2:3]
	v_mov_b64_e32 v[70:71], v[2:3]
	v_mov_b64_e32 v[110:111], v[2:3]
	v_mov_b64_e32 v[114:115], v[2:3]
	v_mov_b64_e32 v[138:139], v[2:3]
	v_mov_b64_e32 v[134:135], v[2:3]
	v_mov_b64_e32 v[106:107], v[2:3]
	v_mov_b64_e32 v[102:103], v[2:3]
	v_mov_b64_e32 v[130:131], v[2:3]
	v_mov_b64_e32 v[126:127], v[2:3]
	v_mov_b64_e32 v[42:43], v[2:3]
	v_mov_b64_e32 v[38:39], v[2:3]
	v_mov_b64_e32 v[122:123], v[2:3]
	v_mov_b64_e32 v[118:119], v[2:3]
	v_mov_b64_e32 v[86:87], v[2:3]
	v_mov_b64_e32 v[78:79], v[2:3]
	v_mov_b64_e32 v[58:59], v[2:3]
	v_mov_b64_e32 v[54:55], v[2:3]
	v_mov_b64_e32 v[22:23], v[2:3]
	v_mov_b64_e32 v[14:15], v[2:3]
	v_mov_b64_e32 v[24:25], v[0:1]
	v_mov_b64_e32 v[16:17], v[0:1]
	v_mov_b64_e32 v[28:29], v[0:1]
	v_mov_b64_e32 v[32:33], v[0:1]
	v_mov_b64_e32 v[88:89], v[0:1]
	v_mov_b64_e32 v[80:81], v[0:1]
	v_mov_b64_e32 v[92:93], v[0:1]
	v_mov_b64_e32 v[96:97], v[0:1]
	v_mov_b64_e32 v[8:9], v[0:1]
	v_mov_b64_e32 v[4:5], v[0:1]
	v_mov_b64_e32 v[44:45], v[0:1]
	v_mov_b64_e32 v[48:49], v[0:1]
	v_mov_b64_e32 v[72:73], v[0:1]
	v_mov_b64_e32 v[68:69], v[0:1]
	v_mov_b64_e32 v[108:109], v[0:1]
	v_mov_b64_e32 v[112:113], v[0:1]
	v_mov_b64_e32 v[136:137], v[0:1]
	v_mov_b64_e32 v[132:133], v[0:1]
	v_mov_b64_e32 v[104:105], v[0:1]
	v_mov_b64_e32 v[100:101], v[0:1]
	v_mov_b64_e32 v[128:129], v[0:1]
	v_mov_b64_e32 v[124:125], v[0:1]
	v_mov_b64_e32 v[40:41], v[0:1]
	v_mov_b64_e32 v[36:37], v[0:1]
	v_mov_b64_e32 v[120:121], v[0:1]
	v_mov_b64_e32 v[116:117], v[0:1]
	v_mov_b64_e32 v[84:85], v[0:1]
	v_mov_b64_e32 v[76:77], v[0:1]
	v_mov_b64_e32 v[56:57], v[0:1]
	v_mov_b64_e32 v[52:53], v[0:1]
	v_mov_b64_e32 v[20:21], v[0:1]
	v_mov_b64_e32 v[12:13], v[0:1]
	s_andn2_b64 vcc, exec, s[4:5]
	s_mov_b64 s[4:5], -1
	s_cbranch_vccnz .LBB0_697
	s_branch .LBB0_712

.LBB0_788:
	v_mbcnt_lo_u32_b32 v128, -1, 0
	v_mbcnt_hi_u32_b32 v128, -1, v128
	s_nop 0
	v_and_or_b32 v178, v128, 15, s65
	v_ashrrev_i32_e32 v128, 1, v128
	v_and_b32_e32 v128, -8, v128
	v_add_u32_e32 v132, s66, v128
	v_ashrrev_i32_e32 v133, 31, v132
	v_lshlrev_b64 v[128:129], 1, v[132:133]
	v_lshl_add_u64 v[134:135], v[132:133], 2, s[10:11]
	v_mad_u64_u32 v[132:133], s[4:5], v178, s39, v[134:135]
	v_or_b32_e32 v176, 16, v178
	global_load_dwordx4 v[142:145], v[132:133], off nt
	global_load_dwordx4 v[146:149], v[132:133], off offset:16 nt
	global_load_dwordx4 v[150:153], v[132:133], off offset:528 nt
	global_load_dwordx4 v[154:157], v[132:133], off offset:512 nt
	v_mad_u64_u32 v[132:133], s[4:5], v176, s39, v[134:135]
	global_load_dwordx4 v[158:161], v[132:133], off nt
	global_load_dwordx4 v[162:165], v[132:133], off offset:16 nt
	global_load_dwordx4 v[166:169], v[132:133], off offset:512 nt
	global_load_dwordx4 v[170:173], v[132:133], off offset:528 nt
	v_mov_b64_e32 v[132:133], s[8:9]
	v_mad_u64_u32 v[174:175], s[4:5], v178, s38, v[132:133]
	v_mad_u64_u32 v[176:177], s[4:5], v176, s38, v[132:133]
	v_lshl_add_u64 v[174:175], v[174:175], 0, v[128:129]
	v_lshl_add_u64 v[176:177], v[176:177], 0, v[128:129]
	s_waitcnt vmcnt(7)
	v_pk_fma_f32 v[114:115], s[26:27], v[144:145], v[114:115] op_sel_hi:[0,1,1]
	v_pk_fma_f32 v[112:113], s[26:27], v[142:143], v[112:113] op_sel_hi:[0,1,1]
	s_waitcnt vmcnt(6)
	v_pk_fma_f32 v[118:119], s[26:27], v[148:149], v[118:119] op_sel_hi:[0,1,1]
	v_pk_fma_f32 v[116:117], s[26:27], v[146:147], v[116:117] op_sel_hi:[0,1,1]
	s_waitcnt vmcnt(4)
	v_pk_fma_f32 v[122:123], s[26:27], v[156:157], v[122:123] op_sel_hi:[0,1,1]
	v_pk_fma_f32 v[120:121], s[26:27], v[154:155], v[120:121] op_sel_hi:[0,1,1]
	v_pk_fma_f32 v[126:127], s[26:27], v[152:153], v[126:127] op_sel_hi:[0,1,1]
	v_pk_fma_f32 v[124:125], s[26:27], v[150:151], v[124:125] op_sel_hi:[0,1,1]
	s_waitcnt vmcnt(3)
	v_pk_fma_f32 v[110:111], s[26:27], v[160:161], v[110:111] op_sel_hi:[0,1,1]
	v_pk_fma_f32 v[108:109], s[26:27], v[158:159], v[108:109] op_sel_hi:[0,1,1]
	s_waitcnt vmcnt(2)
	v_pk_fma_f32 v[142:143], s[26:27], v[164:165], v[102:103] op_sel_hi:[0,1,1]
	v_pk_fma_f32 v[144:145], s[26:27], v[162:163], v[100:101] op_sel_hi:[0,1,1]
	s_waitcnt vmcnt(1)
	v_pk_fma_f32 v[146:147], s[26:27], v[168:169], v[106:107] op_sel_hi:[0,1,1]
	v_pk_fma_f32 v[148:149], s[26:27], v[166:167], v[104:105] op_sel_hi:[0,1,1]
	s_waitcnt vmcnt(0)
	v_pk_fma_f32 v[150:151], s[26:27], v[172:173], v[98:99] op_sel_hi:[0,1,1]
	v_pk_fma_f32 v[152:153], s[26:27], v[170:171], v[96:97] op_sel_hi:[0,1,1]
	v_cvt_pk_bf16_f32 v96, v112, v113
	v_cvt_pk_bf16_f32 v97, v114, v115
	v_cvt_pk_bf16_f32 v98, v116, v117
	v_cvt_pk_bf16_f32 v99, v118, v119
	v_cvt_pk_bf16_f32 v100, v120, v121
	v_cvt_pk_bf16_f32 v101, v122, v123
	v_cvt_pk_bf16_f32 v102, v124, v125
	v_cvt_pk_bf16_f32 v103, v126, v127
	v_cvt_pk_bf16_f32 v104, v108, v109
	v_cvt_pk_bf16_f32 v105, v110, v111
	v_cvt_pk_bf16_f32 v106, v144, v145
	v_cvt_pk_bf16_f32 v107, v142, v143
	v_cvt_pk_bf16_f32 v108, v148, v149
	v_cvt_pk_bf16_f32 v109, v146, v147
	v_cvt_pk_bf16_f32 v110, v152, v153
	v_cvt_pk_bf16_f32 v111, v150, v151
	global_store_dwordx4 v[174:175], v[96:99], off sc1
	global_store_dwordx4 v[174:175], v[100:103], off offset:256 sc1
	global_store_dwordx4 v[176:177], v[104:107], off sc1
	global_store_dwordx4 v[176:177], v[108:111], off offset:256 sc1
	v_or_b32_e32 v142, 32, v178
	v_or_b32_e32 v144, 48, v178
	v_mad_u64_u32 v[108:109], s[4:5], v142, s39, v[134:135]
	v_mad_u64_u32 v[124:125], s[4:5], v144, s39, v[134:135]
	global_load_dwordx4 v[96:99], v[108:109], off nt
	global_load_dwordx4 v[100:103], v[108:109], off offset:16 nt
	global_load_dwordx4 v[104:107], v[108:109], off offset:528 nt
	s_nop 0
	global_load_dwordx4 v[108:111], v[108:109], off offset:512 nt
	s_nop 0
	global_load_dwordx4 v[112:115], v[124:125], off nt
	global_load_dwordx4 v[116:119], v[124:125], off offset:16 nt
	global_load_dwordx4 v[120:123], v[124:125], off offset:512 nt
	s_nop 0
	global_load_dwordx4 v[124:127], v[124:125], off offset:528 nt
	v_mad_u64_u32 v[142:143], s[4:5], v142, s38, v[132:133]
	v_mad_u64_u32 v[144:145], s[4:5], v144, s38, v[132:133]
	v_lshl_add_u64 v[142:143], v[142:143], 0, v[128:129]
	v_lshl_add_u64 v[144:145], v[144:145], 0, v[128:129]
	s_waitcnt vmcnt(7)
	v_pk_fma_f32 v[82:83], s[26:27], v[98:99], v[82:83] op_sel_hi:[0,1,1]
	v_pk_fma_f32 v[80:81], s[26:27], v[96:97], v[80:81] op_sel_hi:[0,1,1]
	s_waitcnt vmcnt(6)
	v_pk_fma_f32 v[86:87], s[26:27], v[102:103], v[86:87] op_sel_hi:[0,1,1]
	v_pk_fma_f32 v[84:85], s[26:27], v[100:101], v[84:85] op_sel_hi:[0,1,1]
	s_waitcnt vmcnt(4)
	v_pk_fma_f32 v[90:91], s[26:27], v[110:111], v[90:91] op_sel_hi:[0,1,1]
	v_pk_fma_f32 v[88:89], s[26:27], v[108:109], v[88:89] op_sel_hi:[0,1,1]
	v_pk_fma_f32 v[94:95], s[26:27], v[106:107], v[94:95] op_sel_hi:[0,1,1]
	v_pk_fma_f32 v[92:93], s[26:27], v[104:105], v[92:93] op_sel_hi:[0,1,1]
	s_waitcnt vmcnt(3)
	v_pk_fma_f32 v[78:79], s[26:27], v[114:115], v[78:79] op_sel_hi:[0,1,1]
	v_pk_fma_f32 v[76:77], s[26:27], v[112:113], v[76:77] op_sel_hi:[0,1,1]
	s_waitcnt vmcnt(2)
	v_pk_fma_f32 v[96:97], s[26:27], v[118:119], v[70:71] op_sel_hi:[0,1,1]
	v_pk_fma_f32 v[98:99], s[26:27], v[116:117], v[68:69] op_sel_hi:[0,1,1]
	s_waitcnt vmcnt(1)
	v_pk_fma_f32 v[100:101], s[26:27], v[122:123], v[74:75] op_sel_hi:[0,1,1]
	v_pk_fma_f32 v[102:103], s[26:27], v[120:121], v[72:73] op_sel_hi:[0,1,1]
	s_waitcnt vmcnt(0)
	v_pk_fma_f32 v[104:105], s[26:27], v[126:127], v[66:67] op_sel_hi:[0,1,1]
	v_pk_fma_f32 v[106:107], s[26:27], v[124:125], v[64:65] op_sel_hi:[0,1,1]
	v_cvt_pk_bf16_f32 v64, v80, v81
	v_cvt_pk_bf16_f32 v65, v82, v83
	v_cvt_pk_bf16_f32 v66, v84, v85
	v_cvt_pk_bf16_f32 v67, v86, v87
	v_cvt_pk_bf16_f32 v68, v88, v89
	v_cvt_pk_bf16_f32 v69, v90, v91
	v_cvt_pk_bf16_f32 v70, v92, v93
	v_cvt_pk_bf16_f32 v71, v94, v95
	v_cvt_pk_bf16_f32 v72, v76, v77
	v_cvt_pk_bf16_f32 v73, v78, v79
	v_cvt_pk_bf16_f32 v74, v98, v99
	v_cvt_pk_bf16_f32 v75, v96, v97
	v_cvt_pk_bf16_f32 v76, v102, v103
	v_cvt_pk_bf16_f32 v77, v100, v101
	v_cvt_pk_bf16_f32 v78, v106, v107
	v_cvt_pk_bf16_f32 v79, v104, v105
	global_store_dwordx4 v[142:143], v[64:67], off sc1
	global_store_dwordx4 v[142:143], v[68:71], off offset:256 sc1
	global_store_dwordx4 v[144:145], v[72:75], off sc1
	global_store_dwordx4 v[144:145], v[76:79], off offset:256 sc1
	v_add_u32_e32 v96, 0x80, v178
	v_add_u32_e32 v98, 0x90, v178
	v_mad_u64_u32 v[76:77], s[4:5], v96, s39, v[134:135]
	v_mad_u64_u32 v[92:93], s[4:5], v98, s39, v[134:135]
	global_load_dwordx4 v[64:67], v[76:77], off nt
	global_load_dwordx4 v[68:71], v[76:77], off offset:16 nt
	global_load_dwordx4 v[72:75], v[76:77], off offset:512 nt
	s_nop 0
	global_load_dwordx4 v[76:79], v[76:77], off offset:528 nt
	s_nop 0
	global_load_dwordx4 v[80:83], v[92:93], off nt
	global_load_dwordx4 v[84:87], v[92:93], off offset:16 nt
	global_load_dwordx4 v[88:91], v[92:93], off offset:512 nt
	s_nop 0
	global_load_dwordx4 v[92:95], v[92:93], off offset:528 nt
	v_mad_u64_u32 v[96:97], s[4:5], v96, s38, v[132:133]
	v_mad_u64_u32 v[98:99], s[4:5], v98, s38, v[132:133]
	v_lshl_add_u64 v[96:97], v[96:97], 0, v[128:129]
	v_lshl_add_u64 v[98:99], v[98:99], 0, v[128:129]
	s_waitcnt vmcnt(7)
	v_pk_fma_f32 v[50:51], s[26:27], v[66:67], v[50:51] op_sel_hi:[0,1,1]
	v_pk_fma_f32 v[48:49], s[26:27], v[64:65], v[48:49] op_sel_hi:[0,1,1]
	s_waitcnt vmcnt(6)
	v_pk_fma_f32 v[54:55], s[26:27], v[70:71], v[54:55] op_sel_hi:[0,1,1]
	v_pk_fma_f32 v[52:53], s[26:27], v[68:69], v[52:53] op_sel_hi:[0,1,1]
	s_waitcnt vmcnt(5)
	v_pk_fma_f32 v[58:59], s[26:27], v[74:75], v[58:59] op_sel_hi:[0,1,1]
	v_pk_fma_f32 v[56:57], s[26:27], v[72:73], v[56:57] op_sel_hi:[0,1,1]
	s_waitcnt vmcnt(3)
	v_pk_fma_f32 v[46:47], s[26:27], v[82:83], v[46:47] op_sel_hi:[0,1,1]
	v_pk_fma_f32 v[44:45], s[26:27], v[80:81], v[44:45] op_sel_hi:[0,1,1]
	s_waitcnt vmcnt(2)
	v_pk_fma_f32 v[38:39], s[26:27], v[86:87], v[38:39] op_sel_hi:[0,1,1]
	v_pk_fma_f32 v[36:37], s[26:27], v[84:85], v[36:37] op_sel_hi:[0,1,1]
	v_pk_fma_f32 v[62:63], s[26:27], v[78:79], v[62:63] op_sel_hi:[0,1,1]
	v_pk_fma_f32 v[60:61], s[26:27], v[76:77], v[60:61] op_sel_hi:[0,1,1]
	v_cvt_pk_bf16_f32 v48, v48, v49
	v_cvt_pk_bf16_f32 v49, v50, v51
	v_cvt_pk_bf16_f32 v50, v52, v53
	v_cvt_pk_bf16_f32 v51, v54, v55
	v_cvt_pk_bf16_f32 v52, v56, v57
	v_cvt_pk_bf16_f32 v53, v58, v59
	s_waitcnt vmcnt(1)
	v_pk_fma_f32 v[42:43], s[26:27], v[90:91], v[42:43] op_sel_hi:[0,1,1]
	v_pk_fma_f32 v[40:41], s[26:27], v[88:89], v[40:41] op_sel_hi:[0,1,1]
	s_waitcnt vmcnt(0)
	v_pk_fma_f32 v[56:57], s[26:27], v[94:95], v[34:35] op_sel_hi:[0,1,1]
	v_pk_fma_f32 v[58:59], s[26:27], v[92:93], v[32:33] op_sel_hi:[0,1,1]
	v_cvt_pk_bf16_f32 v32, v44, v45
	v_cvt_pk_bf16_f32 v33, v46, v47
	v_cvt_pk_bf16_f32 v34, v36, v37
	v_cvt_pk_bf16_f32 v35, v38, v39
	v_cvt_pk_bf16_f32 v54, v60, v61
	v_cvt_pk_bf16_f32 v55, v62, v63
	global_store_dwordx4 v[96:97], v[48:51], off sc1
	global_store_dwordx4 v[96:97], v[52:55], off offset:256 sc1
	v_cvt_pk_bf16_f32 v36, v40, v41
	v_cvt_pk_bf16_f32 v37, v42, v43
	v_cvt_pk_bf16_f32 v38, v58, v59
	v_cvt_pk_bf16_f32 v39, v56, v57
	global_store_dwordx4 v[98:99], v[32:35], off sc1
	global_store_dwordx4 v[98:99], v[36:39], off offset:256 sc1
	v_add_u32_e32 v64, 0xa0, v178
	v_add_u32_e32 v66, 0xb0, v178
	v_mad_u64_u32 v[44:45], s[4:5], v64, s39, v[134:135]
	v_mad_u64_u32 v[60:61], s[4:5], v66, s39, v[134:135]
	global_load_dwordx4 v[32:35], v[44:45], off nt
	global_load_dwordx4 v[36:39], v[44:45], off offset:16 nt
	global_load_dwordx4 v[40:43], v[44:45], off offset:528 nt
	s_nop 0
	global_load_dwordx4 v[44:47], v[44:45], off offset:512 nt
	s_nop 0
	global_load_dwordx4 v[48:51], v[60:61], off nt
	global_load_dwordx4 v[52:55], v[60:61], off offset:16 nt
	global_load_dwordx4 v[56:59], v[60:61], off offset:512 nt
	s_nop 0
	global_load_dwordx4 v[60:63], v[60:61], off offset:528 nt
	v_mad_u64_u32 v[64:65], s[4:5], v64, s38, v[132:133]
	v_mad_u64_u32 v[66:67], s[4:5], v66, s38, v[132:133]
	v_lshl_add_u64 v[64:65], v[64:65], 0, v[128:129]
	s_andn2_b64 vcc, exec, s[44:45]
	s_mov_b64 s[4:5], -1
	v_lshl_add_u64 v[66:67], v[66:67], 0, v[128:129]
	s_waitcnt vmcnt(7)
	v_pk_fma_f32 v[10:11], s[26:27], v[34:35], v[10:11] op_sel_hi:[0,1,1]
	v_pk_fma_f32 v[8:9], s[26:27], v[32:33], v[8:9] op_sel_hi:[0,1,1]
	s_waitcnt vmcnt(6)
	v_pk_fma_f32 v[14:15], s[26:27], v[38:39], v[14:15] op_sel_hi:[0,1,1]
	v_pk_fma_f32 v[12:13], s[26:27], v[36:37], v[12:13] op_sel_hi:[0,1,1]
	s_waitcnt vmcnt(4)
	v_pk_fma_f32 v[26:27], s[26:27], v[46:47], v[26:27] op_sel_hi:[0,1,1]
	v_pk_fma_f32 v[24:25], s[26:27], v[44:45], v[24:25] op_sel_hi:[0,1,1]
	v_pk_fma_f32 v[30:31], s[26:27], v[42:43], v[30:31] op_sel_hi:[0,1,1]
	v_pk_fma_f32 v[28:29], s[26:27], v[40:41], v[28:29] op_sel_hi:[0,1,1]
	s_waitcnt vmcnt(3)
	v_pk_fma_f32 v[32:33], s[26:27], v[50:51], v[2:3] op_sel_hi:[0,1,1]
	v_pk_fma_f32 v[34:35], s[26:27], v[48:49], v[0:1] op_sel_hi:[0,1,1]
	s_waitcnt vmcnt(2)
	v_pk_fma_f32 v[36:37], s[26:27], v[54:55], v[6:7] op_sel_hi:[0,1,1]
	v_pk_fma_f32 v[38:39], s[26:27], v[52:53], v[4:5] op_sel_hi:[0,1,1]
	s_waitcnt vmcnt(1)
	v_pk_fma_f32 v[18:19], s[26:27], v[58:59], v[18:19] op_sel_hi:[0,1,1]
	v_pk_fma_f32 v[16:17], s[26:27], v[56:57], v[16:17] op_sel_hi:[0,1,1]
	s_waitcnt vmcnt(0)
	v_pk_fma_f32 v[22:23], s[26:27], v[62:63], v[22:23] op_sel_hi:[0,1,1]
	v_pk_fma_f32 v[20:21], s[26:27], v[60:61], v[20:21] op_sel_hi:[0,1,1]
	v_cvt_pk_bf16_f32 v0, v8, v9
	v_cvt_pk_bf16_f32 v1, v10, v11
	v_cvt_pk_bf16_f32 v2, v12, v13
	v_cvt_pk_bf16_f32 v3, v14, v15
	v_cvt_pk_bf16_f32 v4, v24, v25
	v_cvt_pk_bf16_f32 v5, v26, v27
	v_cvt_pk_bf16_f32 v6, v28, v29
	v_cvt_pk_bf16_f32 v7, v30, v31
	v_cvt_pk_bf16_f32 v8, v34, v35
	v_cvt_pk_bf16_f32 v9, v32, v33
	v_cvt_pk_bf16_f32 v10, v38, v39
	v_cvt_pk_bf16_f32 v11, v36, v37
	v_cvt_pk_bf16_f32 v12, v16, v17
	v_cvt_pk_bf16_f32 v13, v18, v19
	v_cvt_pk_bf16_f32 v14, v20, v21
	v_cvt_pk_bf16_f32 v15, v22, v23
	global_store_dwordx4 v[64:65], v[0:3], off sc1
	global_store_dwordx4 v[64:65], v[4:7], off offset:256 sc1
	global_store_dwordx4 v[66:67], v[8:11], off sc1
	global_store_dwordx4 v[66:67], v[12:15], off offset:256 sc1
	s_cbranch_vccnz .LBB0_778
	s_andn2_b64 vcc, exec, s[28:29]
	s_cbranch_vccnz .LBB0_777
	s_barrier
	s_branch .LBB0_777

.LBB0_928:
	v_mbcnt_lo_u32_b32 v128, -1, 0
	v_mbcnt_hi_u32_b32 v128, -1, v128
	s_nop 0
	v_and_or_b32 v138, v128, 15, s3
	v_ashrrev_i32_e32 v128, 1, v128
	v_and_b32_e32 v128, -8, v128
	v_add_u32_e32 v128, s54, v128
	v_ashrrev_i32_e32 v129, 31, v128
	v_lshl_add_u64 v[128:129], v[128:129], 1, s[30:31]
	v_mul_f32_e32 v139, 0xbfb8aa3b, v116
	v_mul_f32_e32 v140, 0xbfb8aa3b, v112
	v_exp_f32_e32 v139, v139
	v_exp_f32_e32 v141, v140
	v_mul_f32_e32 v140, 0xbfb8aa3b, v117
	v_exp_f32_e32 v142, v140
	v_add_f32_e32 v139, 1.0, v139
	v_rcp_f32_e32 v140, v139
	v_add_f32_e32 v139, 1.0, v141
	v_add_f32_e32 v141, 1.0, v142
	v_rcp_f32_e32 v141, v141
	v_mul_f32_e32 v142, 0xbfb8aa3b, v113
	v_exp_f32_e32 v143, v142
	v_rcp_f32_e32 v142, v139
	v_pk_mul_f32 v[116:117], v[116:117], v[140:141]
	v_mul_f32_e32 v139, 0xbfb8aa3b, v119
	v_pk_mul_f32 v[116:117], v[116:117], v[124:125]
	v_add_f32_e32 v124, 1.0, v143
	v_mul_f32_e32 v125, 0xbfb8aa3b, v114
	v_rcp_f32_e32 v143, v124
	v_mul_f32_e32 v124, 0xbfb8aa3b, v118
	v_exp_f32_e32 v125, v125
	v_exp_f32_e32 v124, v124
	v_exp_f32_e32 v139, v139
	v_mul_f32_e32 v140, 0xbfb8aa3b, v115
	v_exp_f32_e32 v141, v140
	v_add_f32_e32 v125, 1.0, v125
	v_add_f32_e32 v124, 1.0, v124
	v_rcp_f32_e32 v140, v125
	v_add_f32_e32 v125, 1.0, v139
	v_rcp_f32_e32 v124, v124
	v_rcp_f32_e32 v125, v125
	v_add_f32_e32 v139, 1.0, v141
	v_rcp_f32_e32 v141, v139
	v_pk_mul_f32 v[112:113], v[112:113], v[142:143]
	s_nop 0
	v_pk_mul_f32 v[120:121], v[112:113], v[120:121]
	v_pk_mul_f32 v[112:113], v[118:119], v[124:125]
	v_mad_u64_u32 v[124:125], s[4:5], v138, s1, v[128:129]
	v_pk_mul_f32 v[118:119], v[112:113], v[126:127]
	v_pk_mul_f32 v[112:113], v[114:115], v[140:141]
	v_cvt_pk_bf16_f32 v114, v120, v121
	v_pk_mul_f32 v[122:123], v[112:113], v[122:123]
	v_cvt_pk_bf16_f32 v112, v116, v117
	v_cvt_pk_bf16_f32 v113, v118, v119
	v_cvt_pk_bf16_f32 v115, v122, v123
	global_store_dwordx4 v[124:125], v[112:115], off sc1
	s_nop 1
	v_mul_f32_e32 v112, 0xbfb8aa3b, v100
	v_mul_f32_e32 v113, 0xbfb8aa3b, v96
	v_mul_f32_e32 v114, 0xbfb8aa3b, v101
	v_exp_f32_e32 v112, v112
	v_exp_f32_e32 v113, v113
	v_exp_f32_e32 v114, v114
	v_or_b32_e32 v116, 16, v138
	v_add_f32_e32 v112, 1.0, v112
	v_add_f32_e32 v115, 1.0, v113
	v_add_f32_e32 v113, 1.0, v114
	v_rcp_f32_e32 v112, v112
	v_rcp_f32_e32 v113, v113
	v_mul_f32_e32 v114, 0xbfb8aa3b, v97
	v_exp_f32_e32 v117, v114
	v_rcp_f32_e32 v114, v115
	v_pk_mul_f32 v[100:101], v[100:101], v[112:113]
	v_mul_f32_e32 v112, 0xbfb8aa3b, v103
	v_pk_mul_f32 v[100:101], v[100:101], v[108:109]
	v_add_f32_e32 v108, 1.0, v117
	v_rcp_f32_e32 v115, v108
	v_mul_f32_e32 v109, 0xbfb8aa3b, v98
	v_mul_f32_e32 v108, 0xbfb8aa3b, v102
	v_exp_f32_e32 v109, v109
	v_exp_f32_e32 v108, v108
	v_exp_f32_e32 v113, v112
	v_mul_f32_e32 v112, 0xbfb8aa3b, v99
	v_pk_mul_f32 v[96:97], v[96:97], v[114:115]
	v_exp_f32_e32 v114, v112
	v_add_f32_e32 v109, 1.0, v109
	v_add_f32_e32 v108, 1.0, v108
	v_rcp_f32_e32 v112, v109
	v_add_f32_e32 v109, 1.0, v113
	v_rcp_f32_e32 v108, v108
	v_rcp_f32_e32 v109, v109
	v_add_f32_e32 v113, 1.0, v114
	v_rcp_f32_e32 v113, v113
	v_pk_mul_f32 v[104:105], v[96:97], v[104:105]
	v_pk_mul_f32 v[96:97], v[102:103], v[108:109]
	v_mad_u64_u32 v[108:109], s[4:5], v116, s1, v[128:129]
	v_pk_mul_f32 v[102:103], v[96:97], v[110:111]
	v_pk_mul_f32 v[96:97], v[98:99], v[112:113]
	v_cvt_pk_bf16_f32 v98, v104, v105
	v_pk_mul_f32 v[106:107], v[96:97], v[106:107]
	v_cvt_pk_bf16_f32 v96, v100, v101
	v_cvt_pk_bf16_f32 v97, v102, v103
	v_cvt_pk_bf16_f32 v99, v106, v107
	global_store_dwordx4 v[108:109], v[96:99], off sc1
	s_nop 1
	v_mul_f32_e32 v96, 0xbfb8aa3b, v84
	v_mul_f32_e32 v97, 0xbfb8aa3b, v80
	v_mul_f32_e32 v98, 0xbfb8aa3b, v85
	v_exp_f32_e32 v96, v96
	v_exp_f32_e32 v97, v97
	v_exp_f32_e32 v98, v98
	v_or_b32_e32 v100, 32, v138
	v_add_f32_e32 v96, 1.0, v96
	v_add_f32_e32 v99, 1.0, v97
	v_add_f32_e32 v97, 1.0, v98
	v_rcp_f32_e32 v96, v96
	v_rcp_f32_e32 v97, v97
	v_mul_f32_e32 v98, 0xbfb8aa3b, v81
	v_exp_f32_e32 v101, v98
	v_rcp_f32_e32 v98, v99
	v_pk_mul_f32 v[84:85], v[84:85], v[96:97]
	v_mul_f32_e32 v96, 0xbfb8aa3b, v87
	v_pk_mul_f32 v[84:85], v[84:85], v[92:93]
	v_add_f32_e32 v92, 1.0, v101
	v_rcp_f32_e32 v99, v92
	v_mul_f32_e32 v93, 0xbfb8aa3b, v82
	v_mul_f32_e32 v92, 0xbfb8aa3b, v86
	v_exp_f32_e32 v93, v93
	v_exp_f32_e32 v92, v92
	v_exp_f32_e32 v97, v96
	v_mul_f32_e32 v96, 0xbfb8aa3b, v83
	v_pk_mul_f32 v[80:81], v[80:81], v[98:99]
	v_exp_f32_e32 v98, v96
	v_add_f32_e32 v93, 1.0, v93
	v_add_f32_e32 v92, 1.0, v92
	v_rcp_f32_e32 v96, v93
	v_add_f32_e32 v93, 1.0, v97
	v_rcp_f32_e32 v92, v92
	v_rcp_f32_e32 v93, v93
	v_add_f32_e32 v97, 1.0, v98
	v_rcp_f32_e32 v97, v97
	v_pk_mul_f32 v[88:89], v[80:81], v[88:89]
	v_pk_mul_f32 v[80:81], v[86:87], v[92:93]
	v_mad_u64_u32 v[92:93], s[4:5], v100, s1, v[128:129]
	v_pk_mul_f32 v[86:87], v[80:81], v[94:95]
	v_pk_mul_f32 v[80:81], v[82:83], v[96:97]
	v_cvt_pk_bf16_f32 v82, v88, v89
	v_pk_mul_f32 v[90:91], v[80:81], v[90:91]
	v_cvt_pk_bf16_f32 v80, v84, v85
	v_cvt_pk_bf16_f32 v81, v86, v87
	v_cvt_pk_bf16_f32 v83, v90, v91
	global_store_dwordx4 v[92:93], v[80:83], off sc1
	s_nop 1
	v_mul_f32_e32 v80, 0xbfb8aa3b, v60
	v_mul_f32_e32 v81, 0xbfb8aa3b, v52
	v_mul_f32_e32 v82, 0xbfb8aa3b, v61
	v_exp_f32_e32 v80, v80
	v_exp_f32_e32 v81, v81
	v_exp_f32_e32 v82, v82
	v_or_b32_e32 v84, 48, v138
	v_add_f32_e32 v80, 1.0, v80
	v_add_f32_e32 v83, 1.0, v81
	v_add_f32_e32 v81, 1.0, v82
	v_rcp_f32_e32 v80, v80
	v_rcp_f32_e32 v81, v81
	v_mul_f32_e32 v82, 0xbfb8aa3b, v53
	v_exp_f32_e32 v85, v82
	v_rcp_f32_e32 v82, v83
	v_pk_mul_f32 v[60:61], v[60:61], v[80:81]
	v_mul_f32_e32 v80, 0xbfb8aa3b, v63
	v_pk_mul_f32 v[60:61], v[60:61], v[76:77]
	v_add_f32_e32 v76, 1.0, v85
	v_rcp_f32_e32 v83, v76
	v_mul_f32_e32 v77, 0xbfb8aa3b, v54
	v_mul_f32_e32 v76, 0xbfb8aa3b, v62
	v_exp_f32_e32 v77, v77
	v_exp_f32_e32 v76, v76
	v_exp_f32_e32 v81, v80
	v_mul_f32_e32 v80, 0xbfb8aa3b, v55
	v_pk_mul_f32 v[52:53], v[52:53], v[82:83]
	v_exp_f32_e32 v82, v80
	v_add_f32_e32 v77, 1.0, v77
	v_add_f32_e32 v76, 1.0, v76
	v_rcp_f32_e32 v80, v77
	v_add_f32_e32 v77, 1.0, v81
	v_rcp_f32_e32 v76, v76
	v_rcp_f32_e32 v77, v77
	v_add_f32_e32 v81, 1.0, v82
	v_rcp_f32_e32 v81, v81
	v_pk_mul_f32 v[68:69], v[52:53], v[68:69]
	v_pk_mul_f32 v[52:53], v[62:63], v[76:77]
	v_mad_u64_u32 v[76:77], s[4:5], v84, s1, v[128:129]
	v_pk_mul_f32 v[62:63], v[52:53], v[78:79]
	v_pk_mul_f32 v[52:53], v[54:55], v[80:81]
	v_cvt_pk_bf16_f32 v54, v68, v69
	v_pk_mul_f32 v[70:71], v[52:53], v[70:71]
	v_cvt_pk_bf16_f32 v52, v60, v61
	v_cvt_pk_bf16_f32 v53, v62, v63
	v_cvt_pk_bf16_f32 v55, v70, v71
	global_store_dwordx4 v[76:77], v[52:55], off sc1
	v_add_u32_e32 v62, 0x80, v138
	s_nop 0
	v_mul_f32_e32 v52, 0xbfb8aa3b, v56
	v_mul_f32_e32 v53, 0xbfb8aa3b, v48
	v_mul_f32_e32 v54, 0xbfb8aa3b, v57
	v_exp_f32_e32 v52, v52
	v_exp_f32_e32 v53, v53
	v_exp_f32_e32 v54, v54
	v_add_f32_e32 v52, 1.0, v52
	v_add_f32_e32 v55, 1.0, v53
	v_add_f32_e32 v53, 1.0, v54
	v_mul_f32_e32 v54, 0xbfb8aa3b, v49
	v_rcp_f32_e32 v52, v52
	v_rcp_f32_e32 v53, v53
	v_exp_f32_e32 v60, v54
	v_rcp_f32_e32 v54, v55
	v_pk_mul_f32 v[52:53], v[56:57], v[52:53]
	v_add_f32_e32 v55, 1.0, v60
	v_mul_f32_e32 v56, 0xbfb8aa3b, v58
	v_rcp_f32_e32 v55, v55
	v_exp_f32_e32 v56, v56
	v_mul_f32_e32 v57, 0xbfb8aa3b, v50
	v_exp_f32_e32 v57, v57
	v_pk_mul_f32 v[48:49], v[48:49], v[54:55]
	v_add_f32_e32 v54, 1.0, v56
	v_mul_f32_e32 v56, 0xbfb8aa3b, v59
	v_add_f32_e32 v55, 1.0, v57
	v_exp_f32_e32 v57, v56
	v_mul_f32_e32 v56, 0xbfb8aa3b, v51
	v_exp_f32_e32 v60, v56
	v_rcp_f32_e32 v56, v55
	v_add_f32_e32 v55, 1.0, v57
	v_rcp_f32_e32 v54, v54
	v_rcp_f32_e32 v55, v55
	v_add_f32_e32 v57, 1.0, v60
	v_rcp_f32_e32 v57, v57
	v_pk_mul_f32 v[60:61], v[48:49], v[64:65]
	v_pk_mul_f32 v[48:49], v[58:59], v[54:55]
	v_pk_mul_f32 v[52:53], v[52:53], v[72:73]
	v_pk_mul_f32 v[54:55], v[48:49], v[74:75]
	v_pk_mul_f32 v[48:49], v[50:51], v[56:57]
	v_mad_u64_u32 v[58:59], s[4:5], v62, s1, v[128:129]
	v_pk_mul_f32 v[56:57], v[48:49], v[66:67]
	v_cvt_pk_bf16_f32 v48, v52, v53
	v_cvt_pk_bf16_f32 v49, v54, v55
	v_cvt_pk_bf16_f32 v50, v60, v61
	v_cvt_pk_bf16_f32 v51, v56, v57
	global_store_dwordx4 v[58:59], v[48:51], off sc1
	s_nop 1
	v_mul_f32_e32 v48, 0xbfb8aa3b, v36
	v_mul_f32_e32 v49, 0xbfb8aa3b, v32
	v_mul_f32_e32 v50, 0xbfb8aa3b, v37
	v_exp_f32_e32 v48, v48
	v_exp_f32_e32 v49, v49
	v_exp_f32_e32 v50, v50
	v_add_u32_e32 v52, 0x90, v138
	v_add_f32_e32 v48, 1.0, v48
	v_add_f32_e32 v51, 1.0, v49
	v_add_f32_e32 v49, 1.0, v50
	v_rcp_f32_e32 v48, v48
	v_rcp_f32_e32 v49, v49
	v_mul_f32_e32 v50, 0xbfb8aa3b, v33
	v_exp_f32_e32 v53, v50
	v_rcp_f32_e32 v50, v51
	v_pk_mul_f32 v[36:37], v[36:37], v[48:49]
	v_mul_f32_e32 v48, 0xbfb8aa3b, v39
	v_pk_mul_f32 v[36:37], v[36:37], v[44:45]
	v_add_f32_e32 v44, 1.0, v53
	v_rcp_f32_e32 v51, v44
	v_mul_f32_e32 v45, 0xbfb8aa3b, v34
	v_mul_f32_e32 v44, 0xbfb8aa3b, v38
	v_exp_f32_e32 v45, v45
	v_exp_f32_e32 v44, v44
	v_exp_f32_e32 v49, v48
	v_mul_f32_e32 v48, 0xbfb8aa3b, v35
	v_pk_mul_f32 v[32:33], v[32:33], v[50:51]
	v_exp_f32_e32 v50, v48
	v_add_f32_e32 v45, 1.0, v45
	v_add_f32_e32 v44, 1.0, v44
	v_rcp_f32_e32 v48, v45
	v_add_f32_e32 v45, 1.0, v49
	v_rcp_f32_e32 v44, v44
	v_rcp_f32_e32 v45, v45
	v_add_f32_e32 v49, 1.0, v50
	v_rcp_f32_e32 v49, v49
	v_pk_mul_f32 v[40:41], v[32:33], v[40:41]
	v_pk_mul_f32 v[32:33], v[38:39], v[44:45]
	v_mad_u64_u32 v[44:45], s[4:5], v52, s1, v[128:129]
	v_pk_mul_f32 v[38:39], v[32:33], v[46:47]
	v_pk_mul_f32 v[32:33], v[34:35], v[48:49]
	v_cvt_pk_bf16_f32 v34, v40, v41
	v_pk_mul_f32 v[42:43], v[32:33], v[42:43]
	v_cvt_pk_bf16_f32 v32, v36, v37
	v_cvt_pk_bf16_f32 v33, v38, v39
	v_cvt_pk_bf16_f32 v35, v42, v43
	global_store_dwordx4 v[44:45], v[32:35], off sc1
	s_nop 1
	v_mul_f32_e32 v32, 0xbfb8aa3b, v20
	v_mul_f32_e32 v33, 0xbfb8aa3b, v16
	v_mul_f32_e32 v34, 0xbfb8aa3b, v21
	v_exp_f32_e32 v32, v32
	v_exp_f32_e32 v33, v33
	v_exp_f32_e32 v34, v34
	v_add_u32_e32 v36, 0xa0, v138
	v_add_f32_e32 v32, 1.0, v32
	v_add_f32_e32 v35, 1.0, v33
	v_add_f32_e32 v33, 1.0, v34
	v_rcp_f32_e32 v32, v32
	v_rcp_f32_e32 v33, v33
	v_mul_f32_e32 v34, 0xbfb8aa3b, v17
	v_exp_f32_e32 v37, v34
	v_rcp_f32_e32 v34, v35
	v_pk_mul_f32 v[20:21], v[20:21], v[32:33]
	v_mul_f32_e32 v32, 0xbfb8aa3b, v23
	v_pk_mul_f32 v[20:21], v[20:21], v[28:29]
	v_add_f32_e32 v28, 1.0, v37
	v_rcp_f32_e32 v35, v28
	v_mul_f32_e32 v29, 0xbfb8aa3b, v18
	v_mul_f32_e32 v28, 0xbfb8aa3b, v22
	v_exp_f32_e32 v29, v29
	v_exp_f32_e32 v28, v28
	v_exp_f32_e32 v33, v32
	v_mul_f32_e32 v32, 0xbfb8aa3b, v19
	v_pk_mul_f32 v[16:17], v[16:17], v[34:35]
	v_exp_f32_e32 v34, v32
	v_add_f32_e32 v29, 1.0, v29
	v_add_f32_e32 v28, 1.0, v28
	v_rcp_f32_e32 v32, v29
	v_add_f32_e32 v29, 1.0, v33
	v_rcp_f32_e32 v28, v28
	v_rcp_f32_e32 v29, v29
	v_add_f32_e32 v33, 1.0, v34
	v_rcp_f32_e32 v33, v33
	v_pk_mul_f32 v[24:25], v[16:17], v[24:25]
	v_pk_mul_f32 v[16:17], v[22:23], v[28:29]
	v_mad_u64_u32 v[28:29], s[4:5], v36, s1, v[128:129]
	v_pk_mul_f32 v[22:23], v[16:17], v[30:31]
	v_pk_mul_f32 v[16:17], v[18:19], v[32:33]
	v_cvt_pk_bf16_f32 v18, v24, v25
	v_pk_mul_f32 v[26:27], v[16:17], v[26:27]
	v_cvt_pk_bf16_f32 v16, v20, v21
	v_cvt_pk_bf16_f32 v17, v22, v23
	v_cvt_pk_bf16_f32 v19, v26, v27
	global_store_dwordx4 v[28:29], v[16:19], off sc1
	s_nop 1
	v_mul_f32_e32 v16, 0xbfb8aa3b, v4
	v_mul_f32_e32 v17, 0xbfb8aa3b, v0
	v_mul_f32_e32 v18, 0xbfb8aa3b, v5
	v_exp_f32_e32 v16, v16
	v_exp_f32_e32 v17, v17
	v_exp_f32_e32 v18, v18
	v_add_u32_e32 v20, 0xb0, v138
	v_add_f32_e32 v16, 1.0, v16
	v_add_f32_e32 v19, 1.0, v17
	v_add_f32_e32 v17, 1.0, v18
	v_rcp_f32_e32 v16, v16
	v_rcp_f32_e32 v17, v17
	v_mul_f32_e32 v18, 0xbfb8aa3b, v1
	v_exp_f32_e32 v21, v18
	v_rcp_f32_e32 v18, v19
	v_pk_mul_f32 v[4:5], v[4:5], v[16:17]
	v_mul_f32_e32 v16, 0xbfb8aa3b, v7
	v_pk_mul_f32 v[4:5], v[4:5], v[12:13]
	v_add_f32_e32 v12, 1.0, v21
	v_rcp_f32_e32 v19, v12
	v_mul_f32_e32 v13, 0xbfb8aa3b, v2
	v_mul_f32_e32 v12, 0xbfb8aa3b, v6
	v_exp_f32_e32 v13, v13
	v_exp_f32_e32 v12, v12
	v_exp_f32_e32 v17, v16
	v_mul_f32_e32 v16, 0xbfb8aa3b, v3
	v_pk_mul_f32 v[0:1], v[0:1], v[18:19]
	v_exp_f32_e32 v18, v16
	v_add_f32_e32 v13, 1.0, v13
	v_add_f32_e32 v12, 1.0, v12
	v_rcp_f32_e32 v16, v13
	v_add_f32_e32 v13, 1.0, v17
	v_rcp_f32_e32 v12, v12
	v_rcp_f32_e32 v13, v13
	v_add_f32_e32 v17, 1.0, v18
	v_rcp_f32_e32 v17, v17
	v_pk_mul_f32 v[8:9], v[0:1], v[8:9]
	v_pk_mul_f32 v[0:1], v[6:7], v[12:13]
	v_mad_u64_u32 v[12:13], s[0:1], v20, s1, v[128:129]
	v_pk_mul_f32 v[6:7], v[0:1], v[14:15]
	v_pk_mul_f32 v[0:1], v[2:3], v[16:17]
	v_cvt_pk_bf16_f32 v2, v8, v9
	v_pk_mul_f32 v[10:11], v[0:1], v[10:11]
	v_cvt_pk_bf16_f32 v0, v4, v5
	v_cvt_pk_bf16_f32 v1, v6, v7
	v_cvt_pk_bf16_f32 v3, v10, v11
	s_andn2_b64 vcc, exec, s[28:29]
	s_mov_b64 s[0:1], -1
	global_store_dwordx4 v[12:13], v[0:3], off sc1
	s_cbranch_vccnz .LBB0_918
	s_andn2_b64 vcc, exec, s[18:19]
	s_cbranch_vccnz .LBB0_917
	s_barrier
	s_branch .LBB0_917

.LBB0_947:
	v_mbcnt_lo_u32_b32 v4, -1, 0
	v_mbcnt_hi_u32_b32 v4, -1, v4
	s_nop 0
	v_and_or_b32 v68, v4, 15, s3
	v_ashrrev_i32_e32 v4, 1, v4
	v_and_b32_e32 v4, -8, v4
	v_add_u32_e32 v4, s54, v4
	v_ashrrev_i32_e32 v5, 31, v4
	v_lshlrev_b64 v[136:137], 1, v[4:5]
	v_lshl_add_u64 v[140:141], s[10:11], 0, v[136:137]
	v_mad_u64_u32 v[4:5], s[4:5], v68, s43, v[140:141]
	global_load_dwordx4 v[70:73], v[4:5], off
	global_load_dwordx4 v[74:77], v[4:5], off offset:256
	v_or_b32_e32 v163, 16, v68
	v_or_b32_e32 v164, 32, v68
	v_or_b32_e32 v69, 48, v68
	v_mul_f32_e32 v12, 0xbfb8aa3b, v128
	v_mul_f32_e32 v13, 0xbfb8aa3b, v129
	v_mul_f32_e32 v14, 0xbfb8aa3b, v130
	v_mul_f32_e32 v15, 0xbfb8aa3b, v131
	v_mul_f32_e32 v78, 0xbfb8aa3b, v120
	v_mul_f32_e32 v79, 0xbfb8aa3b, v121
	v_mul_f32_e32 v80, 0xbfb8aa3b, v122
	v_mul_f32_e32 v81, 0xbfb8aa3b, v123
	v_mul_f32_e32 v120, 0xbfb8aa3b, v132
	v_mul_f32_e32 v121, 0xbfb8aa3b, v133
	v_mul_f32_e32 v122, 0xbfb8aa3b, v134
	v_mad_u64_u32 v[4:5], s[4:5], v163, s43, v[140:141]
	v_mad_u64_u32 v[6:7], s[4:5], v164, s43, v[140:141]
	v_mul_f32_e32 v165, 0xbfb8aa3b, v135
	v_mad_u64_u32 v[82:83], s[4:5], v69, s43, v[140:141]
	v_exp_f32_e32 v144, v12
	v_exp_f32_e32 v145, v13
	v_exp_f32_e32 v146, v14
	v_exp_f32_e32 v147, v15
	v_exp_f32_e32 v148, v78
	v_exp_f32_e32 v149, v79
	v_exp_f32_e32 v150, v80
	v_exp_f32_e32 v151, v81
	v_exp_f32_e32 v152, v120
	v_exp_f32_e32 v153, v121
	v_exp_f32_e32 v166, v122
	global_load_dwordx4 v[78:81], v[4:5], off
	global_load_dwordx4 v[132:135], v[4:5], off offset:256
	global_load_dwordx4 v[128:131], v[6:7], off
	global_load_dwordx4 v[120:123], v[6:7], off offset:256
	global_load_dwordx4 v[12:15], v[82:83], off
	s_nop 0
	global_load_dwordx4 v[4:7], v[82:83], off offset:256
	v_mov_b64_e32 v[138:139], s[8:9]
	v_mad_u64_u32 v[142:143], s[4:5], v68, s42, v[138:139]
	v_lshl_add_u64 v[82:83], v[142:143], 0, v[136:137]
	v_add_f32_e32 v142, 1.0, v144
	v_add_f32_e32 v143, 1.0, v145
	v_add_f32_e32 v144, 1.0, v146
	v_add_f32_e32 v145, 1.0, v147
	v_add_f32_e32 v146, 1.0, v148
	v_add_f32_e32 v147, 1.0, v149
	v_add_f32_e32 v148, 1.0, v150
	v_add_f32_e32 v149, 1.0, v151
	v_rcp_f32_e32 v142, v142
	v_rcp_f32_e32 v143, v143
	v_rcp_f32_e32 v144, v144
	v_rcp_f32_e32 v145, v145
	v_rcp_f32_e32 v146, v146
	v_rcp_f32_e32 v147, v147
	v_rcp_f32_e32 v148, v148
	v_rcp_f32_e32 v149, v149
	v_add_f32_e32 v150, 1.0, v152
	v_add_f32_e32 v151, 1.0, v153
	v_mul_f32_e32 v125, 0xbfb8aa3b, v125
	v_exp_f32_e32 v125, v125
	v_mul_f32_e32 v124, 0xbfb8aa3b, v124
	v_exp_f32_e32 v124, v124
	v_rcp_f32_e32 v150, v150
	v_rcp_f32_e32 v151, v151
	s_waitcnt vmcnt(7)
	v_lshlrev_b32_e32 v152, 16, v70
	v_and_b32_e32 v153, 0xffff0000, v70
	v_lshlrev_b32_e32 v70, 16, v71
	v_and_b32_e32 v71, 0xffff0000, v71
	v_lshlrev_b32_e32 v154, 16, v72
	v_and_b32_e32 v155, 0xffff0000, v72
	v_lshlrev_b32_e32 v72, 16, v73
	v_and_b32_e32 v73, 0xffff0000, v73
	v_pk_mul_f32 v[142:143], v[142:143], v[152:153]
	v_pk_mul_f32 v[144:145], v[144:145], v[70:71]
	v_pk_mul_f32 v[146:147], v[146:147], v[154:155]
	v_pk_mul_f32 v[148:149], v[148:149], v[72:73]
	v_cvt_pk_bf16_f32 v70, v142, v143
	v_cvt_pk_bf16_f32 v71, v144, v145
	v_cvt_pk_bf16_f32 v72, v146, v147
	v_cvt_pk_bf16_f32 v73, v148, v149
	global_store_dwordx4 v[82:83], v[70:73], off sc1
	s_waitcnt vmcnt(7)
	v_lshlrev_b32_e32 v160, 16, v74
	v_and_b32_e32 v161, 0xffff0000, v74
	v_exp_f32_e32 v73, v165
	v_add_f32_e32 v72, 1.0, v166
	v_rcp_f32_e32 v72, v72
	v_lshlrev_b32_e32 v74, 16, v75
	v_add_f32_e32 v73, 1.0, v73
	v_rcp_f32_e32 v73, v73
	v_and_b32_e32 v75, 0xffff0000, v75
	v_pk_mul_f32 v[70:71], v[150:151], v[160:161]
	v_pk_mul_f32 v[72:73], v[72:73], v[74:75]
	v_add_f32_e32 v75, 1.0, v125
	v_mul_f32_e32 v125, 0xbfb8aa3b, v126
	v_exp_f32_e32 v126, v125
	v_mul_f32_e32 v125, 0xbfb8aa3b, v127
	v_exp_f32_e32 v127, v125
	v_add_f32_e32 v74, 1.0, v124
	v_lshlrev_b32_e32 v124, 16, v76
	v_and_b32_e32 v125, 0xffff0000, v76
	v_add_f32_e32 v76, 1.0, v126
	v_rcp_f32_e32 v126, v76
	v_add_f32_e32 v76, 1.0, v127
	v_rcp_f32_e32 v74, v74
	v_rcp_f32_e32 v75, v75
	v_rcp_f32_e32 v127, v76
	v_lshlrev_b32_e32 v76, 16, v77
	v_and_b32_e32 v77, 0xffff0000, v77
	v_pk_mul_f32 v[74:75], v[74:75], v[124:125]
	v_pk_mul_f32 v[76:77], v[126:127], v[76:77]
	v_cvt_pk_bf16_f32 v70, v70, v71
	v_cvt_pk_bf16_f32 v71, v72, v73
	v_cvt_pk_bf16_f32 v72, v74, v75
	v_cvt_pk_bf16_f32 v73, v76, v77
	global_store_dwordx4 v[82:83], v[70:73], off offset:256 sc1
	v_mul_f32_e32 v76, 0xbfb8aa3b, v118
	v_mul_f32_e32 v77, 0xbfb8aa3b, v119
	v_mul_f32_e32 v72, 0xbfb8aa3b, v116
	v_mul_f32_e32 v73, 0xbfb8aa3b, v117
	v_exp_f32_e32 v72, v72
	v_exp_f32_e32 v73, v73
	v_mad_u64_u32 v[70:71], s[4:5], v163, s42, v[138:139]
	v_lshl_add_u64 v[74:75], v[70:71], 0, v[136:137]
	v_add_f32_e32 v70, 1.0, v72
	v_add_f32_e32 v71, 1.0, v73
	v_rcp_f32_e32 v70, v70
	v_rcp_f32_e32 v71, v71
	v_exp_f32_e32 v76, v76
	v_exp_f32_e32 v77, v77
	s_waitcnt vmcnt(7)
	v_lshlrev_b32_e32 v72, 16, v78
	v_and_b32_e32 v73, 0xffff0000, v78
	v_pk_mul_f32 v[70:71], v[70:71], v[72:73]
	v_add_f32_e32 v72, 1.0, v76
	v_add_f32_e32 v73, 1.0, v77
	v_lshlrev_b32_e32 v76, 16, v79
	v_and_b32_e32 v77, 0xffff0000, v79
	v_mul_f32_e32 v79, 0xbfb8aa3b, v109
	v_rcp_f32_e32 v72, v72
	v_rcp_f32_e32 v73, v73
	v_exp_f32_e32 v79, v79
	v_mul_f32_e32 v78, 0xbfb8aa3b, v108
	v_exp_f32_e32 v78, v78
	v_pk_mul_f32 v[72:73], v[72:73], v[76:77]
	v_add_f32_e32 v77, 1.0, v79
	v_mul_f32_e32 v79, 0xbfb8aa3b, v110
	v_exp_f32_e32 v82, v79
	v_mul_f32_e32 v79, 0xbfb8aa3b, v111
	v_add_f32_e32 v76, 1.0, v78
	v_exp_f32_e32 v83, v79
	v_rcp_f32_e32 v76, v76
	v_rcp_f32_e32 v77, v77
	v_lshlrev_b32_e32 v78, 16, v80
	v_and_b32_e32 v79, 0xffff0000, v80
	v_add_f32_e32 v80, 1.0, v82
	v_rcp_f32_e32 v82, v80
	v_add_f32_e32 v80, 1.0, v83
	v_rcp_f32_e32 v83, v80
	v_pk_mul_f32 v[76:77], v[76:77], v[78:79]
	v_cvt_pk_bf16_f32 v70, v70, v71
	v_cvt_pk_bf16_f32 v71, v72, v73
	v_cvt_pk_bf16_f32 v72, v76, v77
	v_mul_f32_e32 v76, 0xbfb8aa3b, v112
	v_mul_f32_e32 v77, 0xbfb8aa3b, v113
	v_exp_f32_e32 v76, v76
	v_exp_f32_e32 v77, v77
	v_lshlrev_b32_e32 v78, 16, v81
	v_and_b32_e32 v79, 0xffff0000, v81
	v_pk_mul_f32 v[78:79], v[82:83], v[78:79]
	s_nop 0
	v_cvt_pk_bf16_f32 v73, v78, v79
	global_store_dwordx4 v[74:75], v[70:73], off sc1
	v_mul_f32_e32 v79, 0xbfb8aa3b, v105
	v_exp_f32_e32 v79, v79
	v_add_f32_e32 v70, 1.0, v76
	v_add_f32_e32 v71, 1.0, v77
	v_mul_f32_e32 v76, 0xbfb8aa3b, v114
	v_mul_f32_e32 v77, 0xbfb8aa3b, v115
	v_rcp_f32_e32 v70, v70
	v_rcp_f32_e32 v71, v71
	v_exp_f32_e32 v76, v76
	v_exp_f32_e32 v77, v77
	s_waitcnt vmcnt(7)
	v_lshlrev_b32_e32 v72, 16, v132
	v_and_b32_e32 v73, 0xffff0000, v132
	v_pk_mul_f32 v[70:71], v[70:71], v[72:73]
	v_add_f32_e32 v72, 1.0, v76
	v_add_f32_e32 v73, 1.0, v77
	v_rcp_f32_e32 v72, v72
	v_rcp_f32_e32 v73, v73
	v_lshlrev_b32_e32 v76, 16, v133
	v_and_b32_e32 v77, 0xffff0000, v133
	v_mul_f32_e32 v78, 0xbfb8aa3b, v104
	v_pk_mul_f32 v[72:73], v[72:73], v[76:77]
	v_add_f32_e32 v77, 1.0, v79
	v_mul_f32_e32 v79, 0xbfb8aa3b, v106
	v_exp_f32_e32 v78, v78
	v_exp_f32_e32 v80, v79
	v_mul_f32_e32 v79, 0xbfb8aa3b, v107
	v_exp_f32_e32 v81, v79
	v_add_f32_e32 v76, 1.0, v78
	v_rcp_f32_e32 v76, v76
	v_rcp_f32_e32 v77, v77
	v_add_f32_e32 v80, 1.0, v80
	v_add_f32_e32 v81, 1.0, v81
	v_rcp_f32_e32 v80, v80
	v_rcp_f32_e32 v81, v81
	v_lshlrev_b32_e32 v78, 16, v134
	v_and_b32_e32 v79, 0xffff0000, v134
	v_pk_mul_f32 v[76:77], v[76:77], v[78:79]
	v_lshlrev_b32_e32 v78, 16, v135
	v_and_b32_e32 v79, 0xffff0000, v135
	v_pk_mul_f32 v[78:79], v[80:81], v[78:79]
	v_cvt_pk_bf16_f32 v70, v70, v71
	v_cvt_pk_bf16_f32 v71, v72, v73
	v_cvt_pk_bf16_f32 v72, v76, v77
	v_cvt_pk_bf16_f32 v73, v78, v79
	global_store_dwordx4 v[74:75], v[70:73], off offset:256 sc1
	v_mul_f32_e32 v76, 0xbfb8aa3b, v102
	v_mul_f32_e32 v77, 0xbfb8aa3b, v103
	v_mul_f32_e32 v72, 0xbfb8aa3b, v100
	v_mul_f32_e32 v73, 0xbfb8aa3b, v101
	v_exp_f32_e32 v72, v72
	v_exp_f32_e32 v73, v73
	v_mad_u64_u32 v[70:71], s[4:5], v164, s42, v[138:139]
	v_lshl_add_u64 v[74:75], v[70:71], 0, v[136:137]
	v_add_f32_e32 v70, 1.0, v72
	v_add_f32_e32 v71, 1.0, v73
	v_rcp_f32_e32 v70, v70
	v_rcp_f32_e32 v71, v71
	v_exp_f32_e32 v76, v76
	v_exp_f32_e32 v77, v77
	s_waitcnt vmcnt(7)
	v_lshlrev_b32_e32 v72, 16, v128
	v_and_b32_e32 v73, 0xffff0000, v128
	v_pk_mul_f32 v[70:71], v[70:71], v[72:73]
	v_add_f32_e32 v72, 1.0, v76
	v_add_f32_e32 v73, 1.0, v77
	v_mul_f32_e32 v79, 0xbfb8aa3b, v93
	v_rcp_f32_e32 v72, v72
	v_rcp_f32_e32 v73, v73
	v_exp_f32_e32 v79, v79
	v_mul_f32_e32 v78, 0xbfb8aa3b, v92
	v_exp_f32_e32 v78, v78
	v_lshlrev_b32_e32 v76, 16, v129
	v_and_b32_e32 v77, 0xffff0000, v129
	v_pk_mul_f32 v[72:73], v[72:73], v[76:77]
	v_add_f32_e32 v77, 1.0, v79
	v_mul_f32_e32 v79, 0xbfb8aa3b, v94
	v_exp_f32_e32 v80, v79
	v_mul_f32_e32 v79, 0xbfb8aa3b, v95
	v_add_f32_e32 v76, 1.0, v78
	v_exp_f32_e32 v81, v79
	v_rcp_f32_e32 v76, v76
	v_rcp_f32_e32 v77, v77
	v_lshlrev_b32_e32 v78, 16, v130
	v_and_b32_e32 v79, 0xffff0000, v130
	v_add_f32_e32 v80, 1.0, v80
	v_add_f32_e32 v81, 1.0, v81
	v_rcp_f32_e32 v80, v80
	v_rcp_f32_e32 v81, v81
	v_pk_mul_f32 v[76:77], v[76:77], v[78:79]
	v_cvt_pk_bf16_f32 v70, v70, v71
	v_cvt_pk_bf16_f32 v71, v72, v73
	v_cvt_pk_bf16_f32 v72, v76, v77
	v_mul_f32_e32 v76, 0xbfb8aa3b, v96
	v_mul_f32_e32 v77, 0xbfb8aa3b, v97
	v_exp_f32_e32 v76, v76
	v_exp_f32_e32 v77, v77
	v_lshlrev_b32_e32 v78, 16, v131
	v_and_b32_e32 v79, 0xffff0000, v131
	v_pk_mul_f32 v[78:79], v[80:81], v[78:79]
	s_nop 0
	v_cvt_pk_bf16_f32 v73, v78, v79
	global_store_dwordx4 v[74:75], v[70:73], off sc1
	v_mul_f32_e32 v79, 0xbfb8aa3b, v89
	v_exp_f32_e32 v79, v79
	v_add_f32_e32 v70, 1.0, v76
	v_add_f32_e32 v71, 1.0, v77
	v_mul_f32_e32 v76, 0xbfb8aa3b, v98
	v_mul_f32_e32 v77, 0xbfb8aa3b, v99
	v_rcp_f32_e32 v70, v70
	v_rcp_f32_e32 v71, v71
	v_exp_f32_e32 v76, v76
	v_exp_f32_e32 v77, v77
	s_waitcnt vmcnt(7)
	v_lshlrev_b32_e32 v72, 16, v120
	v_and_b32_e32 v73, 0xffff0000, v120
	v_pk_mul_f32 v[70:71], v[70:71], v[72:73]
	v_add_f32_e32 v72, 1.0, v76
	v_add_f32_e32 v73, 1.0, v77
	v_rcp_f32_e32 v72, v72
	v_rcp_f32_e32 v73, v73
	v_lshlrev_b32_e32 v76, 16, v121
	v_and_b32_e32 v77, 0xffff0000, v121
	v_mul_f32_e32 v78, 0xbfb8aa3b, v88
	v_pk_mul_f32 v[72:73], v[72:73], v[76:77]
	v_add_f32_e32 v77, 1.0, v79
	v_mul_f32_e32 v79, 0xbfb8aa3b, v90
	v_exp_f32_e32 v78, v78
	v_exp_f32_e32 v80, v79
	v_mul_f32_e32 v79, 0xbfb8aa3b, v91
	v_exp_f32_e32 v81, v79
	v_add_f32_e32 v76, 1.0, v78
	v_rcp_f32_e32 v76, v76
	v_rcp_f32_e32 v77, v77
	v_add_f32_e32 v80, 1.0, v80
	v_add_f32_e32 v81, 1.0, v81
	v_rcp_f32_e32 v80, v80
	v_rcp_f32_e32 v81, v81
	v_lshlrev_b32_e32 v78, 16, v122
	v_and_b32_e32 v79, 0xffff0000, v122
	v_pk_mul_f32 v[76:77], v[76:77], v[78:79]
	v_lshlrev_b32_e32 v78, 16, v123
	v_and_b32_e32 v79, 0xffff0000, v123
	v_pk_mul_f32 v[78:79], v[80:81], v[78:79]
	v_cvt_pk_bf16_f32 v70, v70, v71
	v_cvt_pk_bf16_f32 v71, v72, v73
	v_cvt_pk_bf16_f32 v72, v76, v77
	v_cvt_pk_bf16_f32 v73, v78, v79
	global_store_dwordx4 v[74:75], v[70:73], off offset:256 sc1
	s_waitcnt vmcnt(7)
	v_lshlrev_b32_e32 v74, 16, v12
	v_and_b32_e32 v75, 0xffff0000, v12
	v_mad_u64_u32 v[70:71], s[4:5], v69, s42, v[138:139]
	v_mul_f32_e32 v69, 0xbfb8aa3b, v84
	v_exp_f32_e32 v69, v69
	v_mul_f32_e32 v72, 0xbfb8aa3b, v85
	v_exp_f32_e32 v73, v72
	v_mul_f32_e32 v12, 0xbfb8aa3b, v86
	v_add_f32_e32 v69, 1.0, v69
	v_rcp_f32_e32 v72, v69
	v_add_f32_e32 v69, 1.0, v73
	v_rcp_f32_e32 v73, v69
	v_exp_f32_e32 v12, v12
	v_mul_f32_e32 v69, 0xbfb8aa3b, v87
	v_exp_f32_e32 v69, v69
	v_pk_mul_f32 v[72:73], v[72:73], v[74:75]
	v_add_f32_e32 v12, 1.0, v12
	v_rcp_f32_e32 v74, v12
	v_add_f32_e32 v12, 1.0, v69
	v_mul_f32_e32 v69, 0xbfb8aa3b, v200
	v_rcp_f32_e32 v75, v12
	v_exp_f32_e32 v69, v69
	v_lshlrev_b32_e32 v12, 16, v13
	v_and_b32_e32 v13, 0xffff0000, v13
	v_mul_f32_e32 v76, 0xbfb8aa3b, v201
	v_pk_mul_f32 v[74:75], v[74:75], v[12:13]
	v_add_f32_e32 v12, 1.0, v69
	v_mul_f32_e32 v69, 0xbfb8aa3b, v202
	v_exp_f32_e32 v76, v76
	v_exp_f32_e32 v69, v69
	v_mul_f32_e32 v77, 0xbfb8aa3b, v203
	v_exp_f32_e32 v79, v77
	v_add_f32_e32 v13, 1.0, v76
	v_lshlrev_b32_e32 v76, 16, v14
	v_and_b32_e32 v77, 0xffff0000, v14
	v_add_f32_e32 v14, 1.0, v69
	v_rcp_f32_e32 v12, v12
	v_rcp_f32_e32 v13, v13
	v_rcp_f32_e32 v78, v14
	v_add_f32_e32 v14, 1.0, v79
	v_rcp_f32_e32 v79, v14
	v_pk_mul_f32 v[76:77], v[12:13], v[76:77]
	v_lshlrev_b32_e32 v12, 16, v15
	v_and_b32_e32 v13, 0xffff0000, v15
	v_pk_mul_f32 v[78:79], v[78:79], v[12:13]
	v_cvt_pk_bf16_f32 v12, v72, v73
	v_mul_f32_e32 v69, 0xbfb8aa3b, v196
	v_mul_f32_e32 v72, 0xbfb8aa3b, v197
	v_exp_f32_e32 v69, v69
	v_exp_f32_e32 v72, v72
	v_lshl_add_u64 v[70:71], v[70:71], 0, v[136:137]
	v_cvt_pk_bf16_f32 v13, v74, v75
	v_cvt_pk_bf16_f32 v14, v76, v77
	v_cvt_pk_bf16_f32 v15, v78, v79
	global_store_dwordx4 v[70:71], v[12:15], off sc1
	v_mul_f32_e32 v73, 0xbfb8aa3b, v195
	v_exp_f32_e32 v75, v73
	s_waitcnt vmcnt(7)
	v_lshlrev_b32_e32 v14, 16, v4
	v_and_b32_e32 v15, 0xffff0000, v4
	v_mul_f32_e32 v4, 0xbfb8aa3b, v198
	v_add_f32_e32 v12, 1.0, v69
	v_add_f32_e32 v13, 1.0, v72
	v_exp_f32_e32 v4, v4
	v_mul_f32_e32 v69, 0xbfb8aa3b, v199
	v_rcp_f32_e32 v12, v12
	v_rcp_f32_e32 v13, v13
	v_exp_f32_e32 v69, v69
	v_add_f32_e32 v4, 1.0, v4
	v_mul_f32_e32 v72, 0xbfb8aa3b, v193
	v_pk_mul_f32 v[12:13], v[12:13], v[14:15]
	v_rcp_f32_e32 v14, v4
	v_add_f32_e32 v4, 1.0, v69
	v_mul_f32_e32 v69, 0xbfb8aa3b, v192
	v_rcp_f32_e32 v15, v4
	v_exp_f32_e32 v69, v69
	v_lshlrev_b32_e32 v4, 16, v5
	v_and_b32_e32 v5, 0xffff0000, v5
	v_pk_mul_f32 v[14:15], v[14:15], v[4:5]
	v_add_f32_e32 v4, 1.0, v69
	v_mul_f32_e32 v69, 0xbfb8aa3b, v194
	v_exp_f32_e32 v72, v72
	v_exp_f32_e32 v69, v69
	v_and_b32_e32 v73, 0xffff0000, v6
	v_rcp_f32_e32 v4, v4
	v_add_f32_e32 v5, 1.0, v72
	v_lshlrev_b32_e32 v72, 16, v6
	v_add_f32_e32 v6, 1.0, v69
	v_rcp_f32_e32 v5, v5
	v_rcp_f32_e32 v74, v6
	v_add_f32_e32 v6, 1.0, v75
	v_rcp_f32_e32 v75, v6
	v_pk_mul_f32 v[72:73], v[4:5], v[72:73]
	v_lshlrev_b32_e32 v4, 16, v7
	v_and_b32_e32 v5, 0xffff0000, v7
	v_pk_mul_f32 v[74:75], v[74:75], v[4:5]
	v_cvt_pk_bf16_f32 v4, v12, v13
	v_cvt_pk_bf16_f32 v5, v14, v15
	v_cvt_pk_bf16_f32 v6, v72, v73
	v_cvt_pk_bf16_f32 v7, v74, v75
	global_store_dwordx4 v[70:71], v[4:7], off offset:256 sc1
	v_add_u32_e32 v12, 0x80, v68
	s_nop 0
	v_mad_u64_u32 v[4:5], s[4:5], v12, s43, v[140:141]
	global_load_dwordx4 v[72:75], v[4:5], off
	global_load_dwordx4 v[78:81], v[4:5], off offset:256
	v_add_u32_e32 v77, 0x90, v68
	v_add_u32_e32 v104, 0xa0, v68
	v_add_u32_e32 v76, 0xb0, v68
	v_mul_f32_e32 v13, 0xbfb8aa3b, v156
	v_mul_f32_e32 v14, 0xbfb8aa3b, v157
	v_mul_f32_e32 v15, 0xbfb8aa3b, v158
	v_mul_f32_e32 v68, 0xbfb8aa3b, v159
	v_mul_f32_e32 v60, 0xbfb8aa3b, v60
	v_mul_f32_e32 v61, 0xbfb8aa3b, v61
	v_mul_f32_e32 v62, 0xbfb8aa3b, v62
	v_mul_f32_e32 v63, 0xbfb8aa3b, v63
	v_mul_f32_e32 v64, 0xbfb8aa3b, v64
	v_mul_f32_e32 v65, 0xbfb8aa3b, v65
	v_mul_f32_e32 v66, 0xbfb8aa3b, v66
	v_mul_f32_e32 v67, 0xbfb8aa3b, v67
	v_mad_u64_u32 v[4:5], s[4:5], v77, s43, v[140:141]
	v_mad_u64_u32 v[6:7], s[4:5], v104, s43, v[140:141]
	v_mad_u64_u32 v[86:87], s[4:5], v76, s43, v[140:141]
	v_mad_u64_u32 v[88:89], s[4:5], v12, s42, v[138:139]
	v_exp_f32_e32 v90, v13
	v_exp_f32_e32 v91, v14
	v_exp_f32_e32 v92, v15
	v_exp_f32_e32 v93, v68
	v_exp_f32_e32 v94, v60
	v_exp_f32_e32 v95, v61
	v_exp_f32_e32 v96, v62
	v_exp_f32_e32 v97, v63
	v_exp_f32_e32 v98, v64
	v_exp_f32_e32 v99, v65
	v_exp_f32_e32 v105, v66
	v_exp_f32_e32 v106, v67
	global_load_dwordx4 v[82:85], v[4:5], off
	global_load_dwordx4 v[68:71], v[4:5], off offset:256
	global_load_dwordx4 v[64:67], v[6:7], off
	global_load_dwordx4 v[60:63], v[6:7], off offset:256
	global_load_dwordx4 v[12:15], v[86:87], off
	s_nop 0
	global_load_dwordx4 v[4:7], v[86:87], off offset:256
	v_lshl_add_u64 v[86:87], v[88:89], 0, v[136:137]
	v_add_f32_e32 v88, 1.0, v90
	v_add_f32_e32 v89, 1.0, v91
	v_add_f32_e32 v90, 1.0, v92
	v_add_f32_e32 v91, 1.0, v93
	v_add_f32_e32 v92, 1.0, v94
	v_add_f32_e32 v93, 1.0, v95
	v_add_f32_e32 v94, 1.0, v96
	v_add_f32_e32 v95, 1.0, v97
	v_rcp_f32_e32 v88, v88
	v_rcp_f32_e32 v89, v89
	v_rcp_f32_e32 v90, v90
	v_rcp_f32_e32 v91, v91
	v_rcp_f32_e32 v92, v92
	v_rcp_f32_e32 v93, v93
	v_rcp_f32_e32 v94, v94
	v_rcp_f32_e32 v95, v95
	v_mul_f32_e32 v56, 0xbfb8aa3b, v56
	v_mul_f32_e32 v57, 0xbfb8aa3b, v57
	v_add_f32_e32 v96, 1.0, v98
	v_add_f32_e32 v97, 1.0, v99
	v_exp_f32_e32 v56, v56
	v_exp_f32_e32 v57, v57
	v_mul_f32_e32 v58, 0xbfb8aa3b, v58
	v_mul_f32_e32 v59, 0xbfb8aa3b, v59
	v_exp_f32_e32 v58, v58
	v_exp_f32_e32 v59, v59
	v_add_f32_e32 v56, 1.0, v56
	v_add_f32_e32 v57, 1.0, v57
	v_rcp_f32_e32 v56, v56
	v_rcp_f32_e32 v57, v57
	v_add_f32_e32 v58, 1.0, v58
	v_add_f32_e32 v59, 1.0, v59
	v_rcp_f32_e32 v96, v96
	v_rcp_f32_e32 v97, v97
	v_rcp_f32_e32 v58, v58
	v_rcp_f32_e32 v59, v59
	v_mul_f32_e32 v52, 0xbfb8aa3b, v52
	v_mul_f32_e32 v54, 0xbfb8aa3b, v54
	v_mul_f32_e32 v48, 0xbfb8aa3b, v48
	v_mul_f32_e32 v49, 0xbfb8aa3b, v49
	v_exp_f32_e32 v48, v48
	s_waitcnt vmcnt(7)
	v_lshlrev_b32_e32 v98, 16, v72
	v_and_b32_e32 v99, 0xffff0000, v72
	v_lshlrev_b32_e32 v72, 16, v73
	v_and_b32_e32 v73, 0xffff0000, v73
	v_lshlrev_b32_e32 v100, 16, v74
	v_and_b32_e32 v101, 0xffff0000, v74
	v_lshlrev_b32_e32 v74, 16, v75
	v_and_b32_e32 v75, 0xffff0000, v75
	v_pk_mul_f32 v[88:89], v[88:89], v[98:99]
	v_pk_mul_f32 v[90:91], v[90:91], v[72:73]
	v_pk_mul_f32 v[92:93], v[92:93], v[100:101]
	v_pk_mul_f32 v[94:95], v[94:95], v[74:75]
	v_cvt_pk_bf16_f32 v72, v88, v89
	v_cvt_pk_bf16_f32 v73, v90, v91
	v_cvt_pk_bf16_f32 v74, v92, v93
	v_cvt_pk_bf16_f32 v75, v94, v95
	global_store_dwordx4 v[86:87], v[72:75], off sc1
	s_waitcnt vmcnt(7)
	v_lshlrev_b32_e32 v102, 16, v78
	v_and_b32_e32 v103, 0xffff0000, v78
	v_add_f32_e32 v74, 1.0, v105
	v_add_f32_e32 v75, 1.0, v106
	v_rcp_f32_e32 v74, v74
	v_rcp_f32_e32 v75, v75
	v_lshlrev_b32_e32 v78, 16, v79
	v_and_b32_e32 v79, 0xffff0000, v79
	v_pk_mul_f32 v[72:73], v[96:97], v[102:103]
	v_pk_mul_f32 v[74:75], v[74:75], v[78:79]
	v_lshlrev_b32_e32 v78, 16, v80
	v_and_b32_e32 v79, 0xffff0000, v80
	v_pk_mul_f32 v[78:79], v[56:57], v[78:79]
	v_lshlrev_b32_e32 v56, 16, v81
	v_and_b32_e32 v57, 0xffff0000, v81
	v_pk_mul_f32 v[80:81], v[58:59], v[56:57]
	v_cvt_pk_bf16_f32 v56, v72, v73
	v_cvt_pk_bf16_f32 v57, v74, v75
	v_cvt_pk_bf16_f32 v58, v78, v79
	v_cvt_pk_bf16_f32 v59, v80, v81
	global_store_dwordx4 v[86:87], v[56:59], off offset:256 sc1
	v_exp_f32_e32 v72, v54
	v_mul_f32_e32 v54, 0xbfb8aa3b, v55
	v_exp_f32_e32 v58, v52
	v_mul_f32_e32 v52, 0xbfb8aa3b, v53
	v_exp_f32_e32 v59, v52
	v_mad_u64_u32 v[56:57], s[4:5], v77, s42, v[138:139]
	v_lshl_add_u64 v[52:53], v[56:57], 0, v[136:137]
	v_add_f32_e32 v56, 1.0, v58
	v_add_f32_e32 v57, 1.0, v59
	v_rcp_f32_e32 v56, v56
	v_rcp_f32_e32 v57, v57
	v_exp_f32_e32 v73, v54
	v_exp_f32_e32 v49, v49
	v_mul_f32_e32 v50, 0xbfb8aa3b, v50
	v_mul_f32_e32 v51, 0xbfb8aa3b, v51
	v_exp_f32_e32 v50, v50
	v_exp_f32_e32 v51, v51
	s_waitcnt vmcnt(7)
	v_lshlrev_b32_e32 v58, 16, v82
	v_and_b32_e32 v59, 0xffff0000, v82
	v_pk_mul_f32 v[54:55], v[56:57], v[58:59]
	v_add_f32_e32 v56, 1.0, v72
	v_add_f32_e32 v57, 1.0, v73
	v_mul_f32_e32 v44, 0xbfb8aa3b, v44
	v_mul_f32_e32 v45, 0xbfb8aa3b, v45
	v_rcp_f32_e32 v56, v56
	v_rcp_f32_e32 v57, v57
	v_add_f32_e32 v48, 1.0, v48
	v_add_f32_e32 v49, 1.0, v49
	v_exp_f32_e32 v44, v44
	v_exp_f32_e32 v45, v45
	v_mul_f32_e32 v46, 0xbfb8aa3b, v46
	v_mul_f32_e32 v47, 0xbfb8aa3b, v47
	v_rcp_f32_e32 v48, v48
	v_rcp_f32_e32 v49, v49
	v_add_f32_e32 v50, 1.0, v50
	v_add_f32_e32 v51, 1.0, v51
	v_exp_f32_e32 v46, v46
	v_exp_f32_e32 v47, v47
	v_mul_f32_e32 v40, 0xbfb8aa3b, v40
	v_mul_f32_e32 v41, 0xbfb8aa3b, v41
	v_rcp_f32_e32 v50, v50
	v_rcp_f32_e32 v51, v51
	v_exp_f32_e32 v40, v40
	v_exp_f32_e32 v41, v41
	v_mul_f32_e32 v42, 0xbfb8aa3b, v42
	v_mul_f32_e32 v43, 0xbfb8aa3b, v43
	v_lshlrev_b32_e32 v58, 16, v83
	v_and_b32_e32 v59, 0xffff0000, v83
	v_exp_f32_e32 v42, v42
	v_exp_f32_e32 v43, v43
	v_pk_mul_f32 v[56:57], v[56:57], v[58:59]
	v_lshlrev_b32_e32 v58, 16, v84
	v_and_b32_e32 v59, 0xffff0000, v84
	v_add_f32_e32 v44, 1.0, v44
	v_add_f32_e32 v45, 1.0, v45
	v_pk_mul_f32 v[58:59], v[48:49], v[58:59]
	v_lshlrev_b32_e32 v48, 16, v85
	v_and_b32_e32 v49, 0xffff0000, v85
	v_rcp_f32_e32 v44, v44
	v_rcp_f32_e32 v45, v45
	v_add_f32_e32 v46, 1.0, v46
	v_add_f32_e32 v47, 1.0, v47
	v_pk_mul_f32 v[72:73], v[50:51], v[48:49]
	v_rcp_f32_e32 v46, v46
	v_rcp_f32_e32 v47, v47
	v_add_f32_e32 v40, 1.0, v40
	v_add_f32_e32 v41, 1.0, v41
	v_cvt_pk_bf16_f32 v48, v54, v55
	v_cvt_pk_bf16_f32 v49, v56, v57
	v_cvt_pk_bf16_f32 v50, v58, v59
	v_cvt_pk_bf16_f32 v51, v72, v73
	v_rcp_f32_e32 v40, v40
	v_rcp_f32_e32 v41, v41
	v_add_f32_e32 v42, 1.0, v42
	v_add_f32_e32 v43, 1.0, v43
	global_store_dwordx4 v[52:53], v[48:51], off sc1
	v_rcp_f32_e32 v42, v42
	v_rcp_f32_e32 v43, v43
	s_waitcnt vmcnt(7)
	v_lshlrev_b32_e32 v48, 16, v68
	v_and_b32_e32 v49, 0xffff0000, v68
	v_pk_mul_f32 v[44:45], v[44:45], v[48:49]
	v_lshlrev_b32_e32 v48, 16, v69
	v_and_b32_e32 v49, 0xffff0000, v69
	v_pk_mul_f32 v[46:47], v[46:47], v[48:49]
	v_lshlrev_b32_e32 v48, 16, v70
	v_and_b32_e32 v49, 0xffff0000, v70
	v_pk_mul_f32 v[48:49], v[40:41], v[48:49]
	v_lshlrev_b32_e32 v40, 16, v71
	v_and_b32_e32 v41, 0xffff0000, v71
	v_pk_mul_f32 v[50:51], v[42:43], v[40:41]
	v_cvt_pk_bf16_f32 v40, v44, v45
	v_cvt_pk_bf16_f32 v41, v46, v47
	v_cvt_pk_bf16_f32 v42, v48, v49
	v_cvt_pk_bf16_f32 v43, v50, v51
	v_mul_f32_e32 v36, 0xbfb8aa3b, v36
	global_store_dwordx4 v[52:53], v[40:43], off offset:256 sc1
	v_mul_f32_e32 v38, 0xbfb8aa3b, v38
	v_exp_f32_e32 v44, v38
	v_exp_f32_e32 v42, v36
	v_mul_f32_e32 v36, 0xbfb8aa3b, v37
	v_exp_f32_e32 v43, v36
	v_mad_u64_u32 v[40:41], s[4:5], v104, s42, v[138:139]
	v_lshl_add_u64 v[36:37], v[40:41], 0, v[136:137]
	v_add_f32_e32 v40, 1.0, v42
	v_add_f32_e32 v41, 1.0, v43
	v_mul_f32_e32 v38, 0xbfb8aa3b, v39
	v_rcp_f32_e32 v40, v40
	v_rcp_f32_e32 v41, v41
	v_exp_f32_e32 v45, v38
	v_mul_f32_e32 v32, 0xbfb8aa3b, v32
	v_mul_f32_e32 v33, 0xbfb8aa3b, v33
	v_exp_f32_e32 v32, v32
	v_exp_f32_e32 v33, v33
	v_mul_f32_e32 v34, 0xbfb8aa3b, v34
	v_mul_f32_e32 v35, 0xbfb8aa3b, v35
	v_exp_f32_e32 v34, v34
	v_exp_f32_e32 v35, v35
	s_waitcnt vmcnt(7)
	v_lshlrev_b32_e32 v42, 16, v64
	v_and_b32_e32 v43, 0xffff0000, v64
	v_pk_mul_f32 v[38:39], v[40:41], v[42:43]
	v_add_f32_e32 v40, 1.0, v44
	v_add_f32_e32 v41, 1.0, v45
	v_mul_f32_e32 v28, 0xbfb8aa3b, v28
	v_mul_f32_e32 v29, 0xbfb8aa3b, v29
	v_rcp_f32_e32 v40, v40
	v_rcp_f32_e32 v41, v41
	v_add_f32_e32 v32, 1.0, v32
	v_add_f32_e32 v33, 1.0, v33
	v_exp_f32_e32 v28, v28
	v_exp_f32_e32 v29, v29
	v_mul_f32_e32 v30, 0xbfb8aa3b, v30
	v_mul_f32_e32 v31, 0xbfb8aa3b, v31
	v_rcp_f32_e32 v32, v32
	v_rcp_f32_e32 v33, v33
	v_add_f32_e32 v34, 1.0, v34
	v_add_f32_e32 v35, 1.0, v35
	v_exp_f32_e32 v30, v30
	v_exp_f32_e32 v31, v31
	v_mul_f32_e32 v20, 0xbfb8aa3b, v20
	v_mul_f32_e32 v21, 0xbfb8aa3b, v21
	v_rcp_f32_e32 v34, v34
	v_rcp_f32_e32 v35, v35
	v_exp_f32_e32 v20, v20
	v_exp_f32_e32 v21, v21
	v_mul_f32_e32 v22, 0xbfb8aa3b, v22
	v_mul_f32_e32 v23, 0xbfb8aa3b, v23
	v_lshlrev_b32_e32 v42, 16, v65
	v_and_b32_e32 v43, 0xffff0000, v65
	v_exp_f32_e32 v22, v22
	v_exp_f32_e32 v23, v23
	v_pk_mul_f32 v[40:41], v[40:41], v[42:43]
	v_lshlrev_b32_e32 v42, 16, v66
	v_and_b32_e32 v43, 0xffff0000, v66
	v_add_f32_e32 v28, 1.0, v28
	v_add_f32_e32 v29, 1.0, v29
	v_pk_mul_f32 v[42:43], v[32:33], v[42:43]
	v_lshlrev_b32_e32 v32, 16, v67
	v_and_b32_e32 v33, 0xffff0000, v67
	v_rcp_f32_e32 v28, v28
	v_rcp_f32_e32 v29, v29
	v_add_f32_e32 v30, 1.0, v30
	v_add_f32_e32 v31, 1.0, v31
	v_pk_mul_f32 v[44:45], v[34:35], v[32:33]
	v_rcp_f32_e32 v30, v30
	v_rcp_f32_e32 v31, v31
	v_add_f32_e32 v20, 1.0, v20
	v_add_f32_e32 v21, 1.0, v21
	v_cvt_pk_bf16_f32 v32, v38, v39
	v_cvt_pk_bf16_f32 v33, v40, v41
	v_cvt_pk_bf16_f32 v34, v42, v43
	v_cvt_pk_bf16_f32 v35, v44, v45
	v_rcp_f32_e32 v20, v20
	v_rcp_f32_e32 v21, v21
	v_add_f32_e32 v22, 1.0, v22
	v_add_f32_e32 v23, 1.0, v23
	global_store_dwordx4 v[36:37], v[32:35], off sc1
	v_rcp_f32_e32 v22, v22
	v_rcp_f32_e32 v23, v23
	s_waitcnt vmcnt(7)
	v_lshlrev_b32_e32 v32, 16, v60
	v_and_b32_e32 v33, 0xffff0000, v60
	v_pk_mul_f32 v[28:29], v[28:29], v[32:33]
	v_lshlrev_b32_e32 v32, 16, v61
	v_and_b32_e32 v33, 0xffff0000, v61
	v_pk_mul_f32 v[30:31], v[30:31], v[32:33]
	v_lshlrev_b32_e32 v32, 16, v62
	v_and_b32_e32 v33, 0xffff0000, v62
	v_pk_mul_f32 v[32:33], v[20:21], v[32:33]
	v_lshlrev_b32_e32 v20, 16, v63
	v_and_b32_e32 v21, 0xffff0000, v63
	v_pk_mul_f32 v[34:35], v[22:23], v[20:21]
	v_cvt_pk_bf16_f32 v20, v28, v29
	v_cvt_pk_bf16_f32 v21, v30, v31
	v_cvt_pk_bf16_f32 v22, v32, v33
	v_cvt_pk_bf16_f32 v23, v34, v35
	global_store_dwordx4 v[36:37], v[20:23], off offset:256 sc1
	v_mul_f32_e32 v16, 0xbfb8aa3b, v16
	v_mul_f32_e32 v18, 0xbfb8aa3b, v18
	v_mul_f32_e32 v22, 0xbfb8aa3b, v24
	v_mul_f32_e32 v23, 0xbfb8aa3b, v25
	v_exp_f32_e32 v22, v22
	v_exp_f32_e32 v23, v23
	s_waitcnt vmcnt(7)
	v_lshlrev_b32_e32 v24, 16, v12
	v_and_b32_e32 v25, 0xffff0000, v12
	v_mul_f32_e32 v12, 0xbfb8aa3b, v26
	v_add_f32_e32 v22, 1.0, v22
	v_add_f32_e32 v23, 1.0, v23
	v_exp_f32_e32 v12, v12
	v_mul_f32_e32 v26, 0xbfb8aa3b, v27
	v_rcp_f32_e32 v22, v22
	v_rcp_f32_e32 v23, v23
	v_exp_f32_e32 v26, v26
	v_add_f32_e32 v12, 1.0, v12
	v_exp_f32_e32 v18, v18
	v_pk_mul_f32 v[22:23], v[22:23], v[24:25]
	v_rcp_f32_e32 v24, v12
	v_add_f32_e32 v12, 1.0, v26
	v_exp_f32_e32 v26, v16
	v_mul_f32_e32 v16, 0xbfb8aa3b, v17
	v_rcp_f32_e32 v25, v12
	v_exp_f32_e32 v27, v16
	v_mul_f32_e32 v19, 0xbfb8aa3b, v19
	v_exp_f32_e32 v19, v19
	v_lshlrev_b32_e32 v12, 16, v13
	v_and_b32_e32 v13, 0xffff0000, v13
	v_pk_mul_f32 v[16:17], v[24:25], v[12:13]
	v_add_f32_e32 v12, 1.0, v26
	v_add_f32_e32 v13, 1.0, v27
	v_lshlrev_b32_e32 v24, 16, v14
	v_and_b32_e32 v25, 0xffff0000, v14
	v_add_f32_e32 v14, 1.0, v18
	v_rcp_f32_e32 v12, v12
	v_rcp_f32_e32 v13, v13
	v_rcp_f32_e32 v18, v14
	v_add_f32_e32 v14, 1.0, v19
	v_rcp_f32_e32 v19, v14
	v_pk_mul_f32 v[24:25], v[12:13], v[24:25]
	v_lshlrev_b32_e32 v12, 16, v15
	v_and_b32_e32 v13, 0xffff0000, v15
	v_mad_u64_u32 v[20:21], s[4:5], v76, s42, v[138:139]
	v_pk_mul_f32 v[18:19], v[18:19], v[12:13]
	v_lshl_add_u64 v[20:21], v[20:21], 0, v[136:137]
	v_cvt_pk_bf16_f32 v12, v22, v23
	v_cvt_pk_bf16_f32 v13, v16, v17
	v_cvt_pk_bf16_f32 v14, v24, v25
	v_cvt_pk_bf16_f32 v15, v18, v19
	global_store_dwordx4 v[20:21], v[12:15], off sc1
	v_mul_f32_e32 v0, 0xbfb8aa3b, v0
	v_mul_f32_e32 v1, 0xbfb8aa3b, v1
	s_waitcnt vmcnt(7)
	v_lshlrev_b32_e32 v12, 16, v4
	v_and_b32_e32 v13, 0xffff0000, v4
	v_mul_f32_e32 v4, 0xbfb8aa3b, v10
	v_exp_f32_e32 v4, v4
	v_mul_f32_e32 v10, 0xbfb8aa3b, v11
	v_exp_f32_e32 v11, v10
	v_mul_f32_e32 v8, 0xbfb8aa3b, v8
	v_mul_f32_e32 v9, 0xbfb8aa3b, v9
	v_exp_f32_e32 v0, v0
	v_exp_f32_e32 v1, v1
	v_mul_f32_e32 v2, 0xbfb8aa3b, v2
	v_mul_f32_e32 v3, 0xbfb8aa3b, v3
	v_exp_f32_e32 v8, v8
	v_exp_f32_e32 v9, v9
	v_exp_f32_e32 v2, v2
	v_exp_f32_e32 v3, v3
	v_add_f32_e32 v4, 1.0, v4
	v_rcp_f32_e32 v10, v4
	v_add_f32_e32 v4, 1.0, v11
	v_rcp_f32_e32 v11, v4
	v_add_f32_e32 v0, 1.0, v0
	v_add_f32_e32 v1, 1.0, v1
	v_add_f32_e32 v8, 1.0, v8
	v_add_f32_e32 v9, 1.0, v9
	v_rcp_f32_e32 v0, v0
	v_rcp_f32_e32 v1, v1
	v_add_f32_e32 v2, 1.0, v2
	v_add_f32_e32 v3, 1.0, v3
	v_rcp_f32_e32 v8, v8
	v_rcp_f32_e32 v9, v9
	v_rcp_f32_e32 v2, v2
	v_rcp_f32_e32 v3, v3
	v_lshlrev_b32_e32 v4, 16, v5
	v_and_b32_e32 v5, 0xffff0000, v5
	v_pk_mul_f32 v[4:5], v[10:11], v[4:5]
	v_lshlrev_b32_e32 v10, 16, v6
	v_and_b32_e32 v11, 0xffff0000, v6
	v_pk_mul_f32 v[10:11], v[0:1], v[10:11]
	v_lshlrev_b32_e32 v0, 16, v7
	v_and_b32_e32 v1, 0xffff0000, v7
	v_pk_mul_f32 v[8:9], v[8:9], v[12:13]
	v_pk_mul_f32 v[6:7], v[2:3], v[0:1]
	v_cvt_pk_bf16_f32 v0, v8, v9
	v_cvt_pk_bf16_f32 v1, v4, v5
	v_cvt_pk_bf16_f32 v2, v10, v11
	v_cvt_pk_bf16_f32 v3, v6, v7
	s_andn2_b64 vcc, exec, s[40:41]
	s_mov_b64 s[4:5], -1
	global_store_dwordx4 v[20:21], v[0:3], off offset:256 sc1
	s_cbranch_vccnz .LBB0_937
	v_readlane_b32 s4, v254, 55
	v_readlane_b32 s5, v254, 56
	s_andn2_b64 vcc, exec, s[4:5]
	s_cbranch_vccnz .LBB0_936
	s_barrier
	s_branch .LBB0_936

.LBB0_1024:
	v_mbcnt_lo_u32_b32 v160, -1, 0
	v_mbcnt_hi_u32_b32 v160, -1, v160
	s_ashr_i32 s25, s45, 31
	v_ashrrev_i32_e32 v12, 1, v160
	s_mov_b32 s24, s45
	v_and_b32_e32 v12, -8, v12
	s_ashr_i32 s5, s44, 31
	s_lshl_b64 s[24:25], s[24:25], 3
	v_add_u32_e32 v164, s23, v12
	s_add_u32 s24, s28, s24
	s_addc_u32 s25, s29, s25
	v_ashrrev_i32_e32 v165, 31, v164
	v_lshl_add_u64 v[12:13], v[164:165], 3, s[24:25]
	s_mov_b64 s[24:25], 0x20000
	s_mov_b32 s0, 0x20000
	v_lshl_add_u64 v[28:29], v[12:13], 0, s[24:25]
	v_add_co_u32_e32 v12, vcc, s0, v12
	s_mov_b32 s4, s44
	s_nop 0
	v_addc_co_u32_e32 v13, vcc, 0, v13, vcc
	global_load_dwordx4 v[32:35], v[28:29], off offset:32
	global_load_dwordx4 v[52:55], v[28:29], off offset:16
	global_load_dwordx4 v[60:63], v[12:13], off
	s_nop 0
	global_load_dwordx4 v[12:15], v[28:29], off offset:1072
	global_load_dwordx4 v[16:19], v[28:29], off offset:1056
	global_load_dwordx4 v[24:27], v[28:29], off offset:1040
	global_load_dwordx4 v[40:43], v[28:29], off offset:48
	s_nop 0
	global_load_dwordx4 v[28:31], v[28:29], off offset:1024
	s_lshl_b64 s[4:5], s[4:5], 3
	s_add_u32 s24, s28, s4
	v_and_or_b32 v160, v160, 15, s20
	s_addc_u32 s25, s29, s5
	v_lshlrev_b64 v[164:165], 1, v[164:165]
	v_mad_u64_u32 v[166:167], s[4:5], v160, s8, v[164:165]
	s_add_u32 s4, s30, 0xee000000
	s_addc_u32 s5, s31, -1
	v_lshl_add_u64 v[168:169], s[30:31], 0, v[166:167]
	v_lshl_add_u64 v[166:167], s[4:5], 0, v[166:167]
	v_lshl_add_u64 v[170:171], v[160:161], 3, s[24:25]
	global_load_dwordx4 v[178:181], v[168:169], off
	global_load_dwordx4 v[182:185], v[168:169], off offset:256
	global_load_dwordx4 v[186:189], v[166:167], off
	global_load_dwordx4 v[190:193], v[166:167], off offset:256
	global_load_dwordx2 v[210:211], v[170:171], off
	global_load_dwordx2 v[212:213], v[170:171], off offset:128
	v_or_b32_e32 v226, 16, v160
	s_waitcnt vmcnt(11)
	v_mov_b32_e32 v166, v60
	v_mov_b32_e32 v167, v62
	v_mov_b32_e32 v62, v61
	v_mov_b32_e32 v60, v52
	v_mov_b32_e32 v61, v54
	v_mov_b32_e32 v54, v53
	v_mov_b32_e32 v52, v32
	v_mov_b32_e32 v53, v34
	v_mov_b32_e32 v34, v33
	s_waitcnt vmcnt(7)
	v_mov_b32_e32 v32, v40
	v_mov_b32_e32 v33, v42
	v_mov_b32_e32 v42, v41
	s_waitcnt vmcnt(6)
	v_mov_b32_e32 v40, v28
	v_mov_b32_e32 v41, v30
	v_mov_b32_e32 v30, v29
	v_mad_u64_u32 v[28:29], s[24:25], v226, s8, v[164:165]
	v_lshl_add_u64 v[168:169], s[4:5], 0, v[28:29]
	v_lshl_add_u64 v[28:29], s[30:31], 0, v[28:29]
	global_load_dwordx4 v[194:197], v[168:169], off
	global_load_dwordx4 v[198:201], v[168:169], off offset:256
	global_load_dwordx4 v[202:205], v[28:29], off
	global_load_dwordx4 v[206:209], v[28:29], off offset:256
	s_add_u32 s24, s30, 0xf8000000
	s_addc_u32 s25, s31, -1
	v_mov_b64_e32 v[168:169], s[24:25]
	v_mad_u64_u32 v[28:29], s[24:25], v160, s8, v[168:169]
	v_lshl_add_u64 v[214:215], v[28:29], 0, v[164:165]
	s_waitcnt vmcnt(9)
	v_lshlrev_b32_e32 v28, 16, v178
	s_waitcnt vmcnt(7)
	v_lshlrev_b32_e32 v220, 16, v186
	v_and_b32_e32 v221, 0xffff0000, v186
	s_waitcnt vmcnt(5)
	v_pk_add_f32 v[220:221], v[220:221], v[210:211] op_sel_hi:[1,0] neg_lo:[0,1] neg_hi:[0,1]
	v_lshlrev_b32_e32 v186, 16, v187
	v_and_b32_e32 v187, 0xffff0000, v187
	v_lshlrev_b32_e32 v222, 16, v188
	v_and_b32_e32 v223, 0xffff0000, v188
	v_lshlrev_b32_e32 v188, 16, v189
	v_and_b32_e32 v189, 0xffff0000, v189
	v_lshlrev_b32_e32 v224, 16, v190
	v_and_b32_e32 v225, 0xffff0000, v190
	v_pk_mul_f32 v[220:221], v[210:211], v[220:221] op_sel:[1,0]
	v_and_b32_e32 v29, 0xffff0000, v178
	v_pk_add_f32 v[186:187], v[186:187], v[210:211] op_sel_hi:[1,0] neg_lo:[0,1] neg_hi:[0,1]
	v_pk_add_f32 v[222:223], v[222:223], v[210:211] op_sel_hi:[1,0] neg_lo:[0,1] neg_hi:[0,1]
	v_pk_add_f32 v[188:189], v[188:189], v[210:211] op_sel_hi:[1,0] neg_lo:[0,1] neg_hi:[0,1]
	v_pk_add_f32 v[224:225], v[224:225], v[210:211] op_sel_hi:[1,0] neg_lo:[0,1] neg_hi:[0,1]
	v_pk_fma_f32 v[220:221], v[166:167], v[220:221], v[62:63]
	v_pk_mul_f32 v[186:187], v[210:211], v[186:187] op_sel:[1,0]
	v_pk_mul_f32 v[222:223], v[210:211], v[222:223] op_sel:[1,0]
	v_pk_mul_f32 v[188:189], v[210:211], v[188:189] op_sel:[1,0]
	v_pk_mul_f32 v[224:225], v[210:211], v[224:225] op_sel:[1,0]
	v_pk_add_f32 v[28:29], v[220:221], v[28:29]
	v_lshlrev_b32_e32 v178, 16, v179
	v_and_b32_e32 v179, 0xffff0000, v179
	v_lshlrev_b32_e32 v216, 16, v180
	v_and_b32_e32 v217, 0xffff0000, v180
	v_lshlrev_b32_e32 v180, 16, v181
	v_and_b32_e32 v181, 0xffff0000, v181
	v_lshlrev_b32_e32 v218, 16, v182
	v_and_b32_e32 v219, 0xffff0000, v182
	v_pk_fma_f32 v[186:187], v[60:61], v[186:187], v[54:55]
	v_pk_fma_f32 v[222:223], v[52:53], v[222:223], v[34:35]
	v_pk_fma_f32 v[188:189], v[32:33], v[188:189], v[42:43]
	v_pk_fma_f32 v[224:225], v[40:41], v[224:225], v[30:31]
	v_pk_add_f32 v[28:29], v[152:153], v[28:29]
	v_pk_add_f32 v[178:179], v[186:187], v[178:179]
	v_pk_add_f32 v[186:187], v[222:223], v[216:217]
	v_pk_add_f32 v[180:181], v[188:189], v[180:181]
	v_cvt_pk_bf16_f32 v152, v28, v29
	v_pk_add_f32 v[28:29], v[224:225], v[218:219]
	v_pk_add_f32 v[154:155], v[154:155], v[178:179]
	v_pk_add_f32 v[156:157], v[156:157], v[186:187]
	v_pk_add_f32 v[158:159], v[158:159], v[180:181]
	v_pk_add_f32 v[148:149], v[148:149], v[28:29]
	v_lshlrev_b32_e32 v28, 16, v191
	v_and_b32_e32 v29, 0xffff0000, v191
	v_cvt_pk_bf16_f32 v153, v154, v155
	v_cvt_pk_bf16_f32 v154, v156, v157
	v_cvt_pk_bf16_f32 v155, v158, v159
	v_pk_add_f32 v[28:29], v[28:29], v[210:211] op_sel_hi:[1,0] neg_lo:[0,1] neg_hi:[0,1]
	global_store_dwordx4 v[214:215], v[152:155], off sc1
	s_nop 1
	v_pk_mul_f32 v[154:155], v[210:211], v[28:29] op_sel:[1,0]
	v_mov_b32_e32 v28, v24
	v_mov_b32_e32 v29, v26
	v_mov_b32_e32 v26, v25
	v_lshlrev_b32_e32 v152, 16, v183
	v_and_b32_e32 v153, 0xffff0000, v183
	v_pk_fma_f32 v[24:25], v[28:29], v[154:155], v[26:27]
	s_nop 0
	v_pk_add_f32 v[24:25], v[24:25], v[152:153]
	v_lshlrev_b32_e32 v152, 16, v184
	v_pk_add_f32 v[150:151], v[150:151], v[24:25]
	v_lshlrev_b32_e32 v24, 16, v192
	v_and_b32_e32 v25, 0xffff0000, v192
	v_pk_add_f32 v[24:25], v[24:25], v[210:211] op_sel_hi:[1,0] neg_lo:[0,1] neg_hi:[0,1]
	v_and_b32_e32 v153, 0xffff0000, v184
	v_pk_mul_f32 v[154:155], v[210:211], v[24:25] op_sel:[1,0]
	v_mov_b32_e32 v24, v16
	v_mov_b32_e32 v25, v18
	v_mov_b32_e32 v18, v17
	v_pk_fma_f32 v[16:17], v[24:25], v[154:155], v[18:19]
	s_nop 0
	v_pk_add_f32 v[16:17], v[16:17], v[152:153]
	s_nop 0
	v_pk_add_f32 v[152:153], v[144:145], v[16:17]
	v_lshlrev_b32_e32 v16, 16, v193
	v_and_b32_e32 v17, 0xffff0000, v193
	v_pk_add_f32 v[16:17], v[16:17], v[210:211] op_sel_hi:[1,0] neg_lo:[0,1] neg_hi:[0,1]
	v_lshlrev_b32_e32 v144, 16, v185
	v_pk_mul_f32 v[154:155], v[210:211], v[16:17] op_sel:[1,0]
	v_mov_b32_e32 v16, v12
	v_mov_b32_e32 v17, v14
	v_mov_b32_e32 v14, v13
	v_and_b32_e32 v145, 0xffff0000, v185
	v_pk_fma_f32 v[12:13], v[16:17], v[154:155], v[14:15]
	s_nop 0
	v_pk_add_f32 v[12:13], v[12:13], v[144:145]
	v_cvt_pk_bf16_f32 v144, v148, v149
	v_pk_add_f32 v[12:13], v[146:147], v[12:13]
	v_cvt_pk_bf16_f32 v145, v150, v151
	v_cvt_pk_bf16_f32 v146, v152, v153
	v_cvt_pk_bf16_f32 v147, v12, v13
	global_store_dwordx4 v[214:215], v[144:147], off offset:256 sc1
	v_mad_u64_u32 v[12:13], s[24:25], v226, s8, v[168:169]
	s_waitcnt vmcnt(5)
	v_lshlrev_b32_e32 v146, 16, v194
	v_and_b32_e32 v147, 0xffff0000, v194
	v_pk_add_f32 v[146:147], v[146:147], v[212:213] op_sel_hi:[1,0] neg_lo:[0,1] neg_hi:[0,1]
	s_waitcnt vmcnt(3)
	v_lshlrev_b32_e32 v144, 16, v202
	v_pk_mul_f32 v[146:147], v[212:213], v[146:147] op_sel:[1,0]
	v_and_b32_e32 v145, 0xffff0000, v202
	v_pk_fma_f32 v[146:147], v[166:167], v[146:147], v[62:63]
	v_lshl_add_u64 v[12:13], v[12:13], 0, v[164:165]
	v_pk_add_f32 v[144:145], v[146:147], v[144:145]
	v_lshlrev_b32_e32 v146, 16, v195
	v_and_b32_e32 v147, 0xffff0000, v195
	v_pk_add_f32 v[146:147], v[146:147], v[212:213] op_sel_hi:[1,0] neg_lo:[0,1] neg_hi:[0,1]
	v_pk_add_f32 v[140:141], v[140:141], v[144:145]
	v_pk_mul_f32 v[146:147], v[212:213], v[146:147] op_sel:[1,0]
	v_lshlrev_b32_e32 v144, 16, v203
	v_and_b32_e32 v145, 0xffff0000, v203
	v_pk_fma_f32 v[146:147], v[60:61], v[146:147], v[54:55]
	s_nop 0
	v_pk_add_f32 v[144:145], v[146:147], v[144:145]
	v_lshlrev_b32_e32 v146, 16, v196
	v_and_b32_e32 v147, 0xffff0000, v196
	v_pk_add_f32 v[146:147], v[146:147], v[212:213] op_sel_hi:[1,0] neg_lo:[0,1] neg_hi:[0,1]
	v_pk_add_f32 v[142:143], v[142:143], v[144:145]
	v_pk_mul_f32 v[146:147], v[212:213], v[146:147] op_sel:[1,0]
	v_lshlrev_b32_e32 v144, 16, v204
	v_and_b32_e32 v145, 0xffff0000, v204
	v_pk_fma_f32 v[146:147], v[52:53], v[146:147], v[34:35]
	s_nop 0
	v_pk_add_f32 v[144:145], v[146:147], v[144:145]
	v_lshlrev_b32_e32 v146, 16, v197
	v_and_b32_e32 v147, 0xffff0000, v197
	v_pk_add_f32 v[146:147], v[146:147], v[212:213] op_sel_hi:[1,0] neg_lo:[0,1] neg_hi:[0,1]
	v_pk_add_f32 v[144:145], v[136:137], v[144:145]
	v_pk_mul_f32 v[146:147], v[212:213], v[146:147] op_sel:[1,0]
	v_lshlrev_b32_e32 v136, 16, v205
	v_and_b32_e32 v137, 0xffff0000, v205
	v_pk_fma_f32 v[146:147], v[32:33], v[146:147], v[42:43]
	s_nop 0
	v_pk_add_f32 v[136:137], v[146:147], v[136:137]
	s_nop 0
	v_pk_add_f32 v[146:147], v[138:139], v[136:137]
	v_cvt_pk_bf16_f32 v136, v140, v141
	v_cvt_pk_bf16_f32 v137, v142, v143
	v_cvt_pk_bf16_f32 v138, v144, v145
	v_cvt_pk_bf16_f32 v139, v146, v147
	global_store_dwordx4 v[12:13], v[136:139], off sc1
	s_nop 1
	v_lshlrev_b32_e32 v138, 16, v198
	v_and_b32_e32 v139, 0xffff0000, v198
	v_pk_add_f32 v[138:139], v[138:139], v[212:213] op_sel_hi:[1,0] neg_lo:[0,1] neg_hi:[0,1]
	s_waitcnt vmcnt(3)
	v_lshlrev_b32_e32 v136, 16, v206
	v_pk_mul_f32 v[138:139], v[212:213], v[138:139] op_sel:[1,0]
	v_and_b32_e32 v137, 0xffff0000, v206
	v_pk_fma_f32 v[138:139], v[40:41], v[138:139], v[30:31]
	s_nop 0
	v_pk_add_f32 v[136:137], v[138:139], v[136:137]
	v_lshlrev_b32_e32 v138, 16, v199
	v_and_b32_e32 v139, 0xffff0000, v199
	v_pk_add_f32 v[138:139], v[138:139], v[212:213] op_sel_hi:[1,0] neg_lo:[0,1] neg_hi:[0,1]
	v_pk_add_f32 v[132:133], v[132:133], v[136:137]
	v_pk_mul_f32 v[138:139], v[212:213], v[138:139] op_sel:[1,0]
	v_lshlrev_b32_e32 v136, 16, v207
	v_and_b32_e32 v137, 0xffff0000, v207
	v_pk_fma_f32 v[138:139], v[28:29], v[138:139], v[26:27]
	s_nop 0
	v_pk_add_f32 v[136:137], v[138:139], v[136:137]
	v_lshlrev_b32_e32 v138, 16, v200
	v_and_b32_e32 v139, 0xffff0000, v200
	v_pk_add_f32 v[138:139], v[138:139], v[212:213] op_sel_hi:[1,0] neg_lo:[0,1] neg_hi:[0,1]
	v_pk_add_f32 v[134:135], v[134:135], v[136:137]
	v_pk_mul_f32 v[138:139], v[212:213], v[138:139] op_sel:[1,0]
	v_lshlrev_b32_e32 v136, 16, v208
	v_and_b32_e32 v137, 0xffff0000, v208
	v_pk_fma_f32 v[138:139], v[24:25], v[138:139], v[18:19]
	s_nop 0
	v_pk_add_f32 v[136:137], v[138:139], v[136:137]
	v_lshlrev_b32_e32 v138, 16, v201
	v_and_b32_e32 v139, 0xffff0000, v201
	v_pk_add_f32 v[138:139], v[138:139], v[212:213] op_sel_hi:[1,0] neg_lo:[0,1] neg_hi:[0,1]
	v_pk_add_f32 v[136:137], v[128:129], v[136:137]
	v_pk_mul_f32 v[138:139], v[212:213], v[138:139] op_sel:[1,0]
	v_lshlrev_b32_e32 v128, 16, v209
	v_and_b32_e32 v129, 0xffff0000, v209
	v_pk_fma_f32 v[138:139], v[16:17], v[138:139], v[14:15]
	s_nop 0
	v_pk_add_f32 v[128:129], v[138:139], v[128:129]
	s_nop 0
	v_pk_add_f32 v[138:139], v[130:131], v[128:129]
	v_cvt_pk_bf16_f32 v128, v132, v133
	v_cvt_pk_bf16_f32 v129, v134, v135
	v_cvt_pk_bf16_f32 v130, v136, v137
	v_cvt_pk_bf16_f32 v131, v138, v139
	global_store_dwordx4 v[12:13], v[128:131], off offset:256 sc1
	s_nop 1
	v_or_b32_e32 v130, 32, v160
	v_mad_u64_u32 v[12:13], s[24:25], v130, s8, v[164:165]
	v_lshl_add_u64 v[128:129], s[30:31], 0, v[12:13]
	v_lshl_add_u64 v[12:13], s[4:5], 0, v[12:13]
	global_load_dwordx4 v[136:139], v[128:129], off
	global_load_dwordx4 v[140:143], v[12:13], off
	global_load_dwordx4 v[144:147], v[128:129], off offset:256
	global_load_dwordx4 v[148:151], v[12:13], off offset:256
	global_load_dwordx2 v[178:179], v[170:171], off offset:256
	v_or_b32_e32 v198, 48, v160
	global_load_dwordx2 v[12:13], v[170:171], off offset:384
	v_mad_u64_u32 v[128:129], s[24:25], v198, s8, v[164:165]
	v_mad_u64_u32 v[130:131], s[24:25], v130, s8, v[168:169]
	v_lshl_add_u64 v[132:133], s[4:5], 0, v[128:129]
	v_lshl_add_u64 v[134:135], s[30:31], 0, v[128:129]
	v_lshl_add_u64 v[180:181], v[130:131], 0, v[164:165]
	global_load_dwordx4 v[152:155], v[132:133], off
	global_load_dwordx4 v[128:131], v[132:133], off offset:256
	global_load_dwordx4 v[156:159], v[134:135], off
	s_nop 0
	global_load_dwordx4 v[132:135], v[134:135], off offset:256
	s_waitcnt vmcnt(8)
	v_lshlrev_b32_e32 v184, 16, v140
	v_and_b32_e32 v185, 0xffff0000, v140
	v_lshlrev_b32_e32 v140, 16, v141
	v_and_b32_e32 v141, 0xffff0000, v141
	v_lshlrev_b32_e32 v188, 16, v142
	v_and_b32_e32 v189, 0xffff0000, v142
	v_lshlrev_b32_e32 v142, 16, v143
	v_and_b32_e32 v143, 0xffff0000, v143
	s_waitcnt vmcnt(5)
	v_pk_add_f32 v[184:185], v[184:185], v[178:179] op_sel_hi:[1,0] neg_lo:[0,1] neg_hi:[0,1]
	v_pk_add_f32 v[140:141], v[140:141], v[178:179] op_sel_hi:[1,0] neg_lo:[0,1] neg_hi:[0,1]
	v_pk_add_f32 v[188:189], v[188:189], v[178:179] op_sel_hi:[1,0] neg_lo:[0,1] neg_hi:[0,1]
	v_pk_add_f32 v[142:143], v[142:143], v[178:179] op_sel_hi:[1,0] neg_lo:[0,1] neg_hi:[0,1]
	v_pk_mul_f32 v[184:185], v[178:179], v[184:185] op_sel:[1,0]
	v_pk_mul_f32 v[140:141], v[178:179], v[140:141] op_sel:[1,0]
	v_pk_mul_f32 v[188:189], v[178:179], v[188:189] op_sel:[1,0]
	v_pk_mul_f32 v[142:143], v[178:179], v[142:143] op_sel:[1,0]
	v_lshlrev_b32_e32 v182, 16, v136
	v_and_b32_e32 v183, 0xffff0000, v136
	v_lshlrev_b32_e32 v136, 16, v137
	v_and_b32_e32 v137, 0xffff0000, v137
	v_lshlrev_b32_e32 v186, 16, v138
	v_and_b32_e32 v187, 0xffff0000, v138
	v_lshlrev_b32_e32 v138, 16, v139
	v_and_b32_e32 v139, 0xffff0000, v139
	v_pk_fma_f32 v[184:185], v[166:167], v[184:185], v[62:63]
	v_pk_fma_f32 v[140:141], v[60:61], v[140:141], v[54:55]
	v_pk_fma_f32 v[188:189], v[52:53], v[188:189], v[34:35]
	v_pk_fma_f32 v[142:143], v[32:33], v[142:143], v[42:43]
	v_pk_add_f32 v[182:183], v[184:185], v[182:183]
	v_pk_add_f32 v[136:137], v[140:141], v[136:137]
	v_pk_add_f32 v[140:141], v[188:189], v[186:187]
	v_pk_add_f32 v[138:139], v[142:143], v[138:139]
	v_lshlrev_b32_e32 v192, 16, v148
	v_and_b32_e32 v193, 0xffff0000, v148
	v_lshlrev_b32_e32 v148, 16, v149
	v_and_b32_e32 v149, 0xffff0000, v149
	v_lshlrev_b32_e32 v196, 16, v150
	v_and_b32_e32 v197, 0xffff0000, v150
	v_pk_add_f32 v[116:117], v[116:117], v[182:183]
	v_pk_add_f32 v[118:119], v[118:119], v[136:137]
	v_pk_add_f32 v[120:121], v[120:121], v[140:141]
	v_pk_add_f32 v[122:123], v[122:123], v[138:139]
	v_pk_add_f32 v[148:149], v[148:149], v[178:179] op_sel_hi:[1,0] neg_lo:[0,1] neg_hi:[0,1]
	v_pk_add_f32 v[196:197], v[196:197], v[178:179] op_sel_hi:[1,0] neg_lo:[0,1] neg_hi:[0,1]
	v_cvt_pk_bf16_f32 v116, v116, v117
	v_cvt_pk_bf16_f32 v117, v118, v119
	v_cvt_pk_bf16_f32 v118, v120, v121
	v_cvt_pk_bf16_f32 v119, v122, v123
	v_pk_mul_f32 v[148:149], v[178:179], v[148:149] op_sel:[1,0]
	v_pk_mul_f32 v[196:197], v[178:179], v[196:197] op_sel:[1,0]
	global_store_dwordx4 v[180:181], v[116:119], off sc1
	v_lshlrev_b32_e32 v190, 16, v144
	v_and_b32_e32 v191, 0xffff0000, v144
	v_lshlrev_b32_e32 v116, 16, v151
	v_and_b32_e32 v117, 0xffff0000, v151
	v_lshlrev_b32_e32 v144, 16, v145
	v_and_b32_e32 v145, 0xffff0000, v145
	v_lshlrev_b32_e32 v194, 16, v146
	v_and_b32_e32 v195, 0xffff0000, v146
	v_pk_fma_f32 v[148:149], v[28:29], v[148:149], v[26:27]
	v_pk_fma_f32 v[196:197], v[24:25], v[196:197], v[18:19]
	v_pk_add_f32 v[116:117], v[116:117], v[178:179] op_sel_hi:[1,0] neg_lo:[0,1] neg_hi:[0,1]
	v_pk_add_f32 v[144:145], v[148:149], v[144:145]
	v_pk_add_f32 v[148:149], v[196:197], v[194:195]
	v_pk_mul_f32 v[116:117], v[178:179], v[116:117] op_sel:[1,0]
	v_pk_add_f32 v[192:193], v[192:193], v[178:179] op_sel_hi:[1,0] neg_lo:[0,1] neg_hi:[0,1]
	v_pk_add_f32 v[136:137], v[112:113], v[148:149]
	v_lshlrev_b32_e32 v112, 16, v147
	v_and_b32_e32 v113, 0xffff0000, v147
	v_pk_fma_f32 v[116:117], v[16:17], v[116:117], v[14:15]
	v_pk_mul_f32 v[192:193], v[178:179], v[192:193] op_sel:[1,0]
	v_pk_add_f32 v[112:113], v[116:117], v[112:113]
	v_pk_fma_f32 v[192:193], v[40:41], v[192:193], v[30:31]
	v_pk_add_f32 v[116:117], v[114:115], v[112:113]
	v_pk_add_f32 v[142:143], v[192:193], v[190:191]
	v_cvt_pk_bf16_f32 v115, v116, v117
	s_waitcnt vmcnt(4)
	v_lshlrev_b32_e32 v116, 16, v152
	v_and_b32_e32 v117, 0xffff0000, v152
	v_pk_add_f32 v[124:125], v[124:125], v[142:143]
	v_pk_add_f32 v[126:127], v[126:127], v[144:145]
	v_pk_add_f32 v[116:117], v[116:117], v[12:13] op_sel_hi:[1,0] neg_lo:[0,1] neg_hi:[0,1]
	v_cvt_pk_bf16_f32 v112, v124, v125
	v_cvt_pk_bf16_f32 v113, v126, v127
	v_cvt_pk_bf16_f32 v114, v136, v137
	v_pk_mul_f32 v[116:117], v[12:13], v[116:117] op_sel:[1,0]
	global_store_dwordx4 v[180:181], v[112:115], off offset:256 sc1
	v_pk_fma_f32 v[116:117], v[166:167], v[116:117], v[62:63]
	s_waitcnt vmcnt(3)
	v_lshlrev_b32_e32 v114, 16, v156
	v_and_b32_e32 v115, 0xffff0000, v156
	v_pk_add_f32 v[114:115], v[116:117], v[114:115]
	v_lshlrev_b32_e32 v116, 16, v153
	v_and_b32_e32 v117, 0xffff0000, v153
	v_pk_add_f32 v[116:117], v[116:117], v[12:13] op_sel_hi:[1,0] neg_lo:[0,1] neg_hi:[0,1]
	v_pk_add_f32 v[108:109], v[108:109], v[114:115]
	v_pk_mul_f32 v[116:117], v[12:13], v[116:117] op_sel:[1,0]
	v_lshlrev_b32_e32 v114, 16, v157
	v_and_b32_e32 v115, 0xffff0000, v157
	v_pk_fma_f32 v[116:117], v[60:61], v[116:117], v[54:55]
	v_mad_u64_u32 v[112:113], s[24:25], v198, s8, v[168:169]
	v_pk_add_f32 v[114:115], v[116:117], v[114:115]
	v_lshlrev_b32_e32 v116, 16, v154
	v_and_b32_e32 v117, 0xffff0000, v154
	v_pk_add_f32 v[116:117], v[116:117], v[12:13] op_sel_hi:[1,0] neg_lo:[0,1] neg_hi:[0,1]
	v_pk_add_f32 v[110:111], v[110:111], v[114:115]
	v_pk_mul_f32 v[116:117], v[12:13], v[116:117] op_sel:[1,0]
	v_lshlrev_b32_e32 v114, 16, v158
	v_and_b32_e32 v115, 0xffff0000, v158
	v_pk_fma_f32 v[116:117], v[52:53], v[116:117], v[34:35]
	v_lshl_add_u64 v[112:113], v[112:113], 0, v[164:165]
	v_pk_add_f32 v[114:115], v[116:117], v[114:115]
	v_lshlrev_b32_e32 v116, 16, v155
	v_and_b32_e32 v117, 0xffff0000, v155
	v_pk_add_f32 v[116:117], v[116:117], v[12:13] op_sel_hi:[1,0] neg_lo:[0,1] neg_hi:[0,1]
	v_pk_add_f32 v[114:115], v[104:105], v[114:115]
	v_pk_mul_f32 v[116:117], v[12:13], v[116:117] op_sel:[1,0]
	v_lshlrev_b32_e32 v104, 16, v159
	v_and_b32_e32 v105, 0xffff0000, v159
	v_pk_fma_f32 v[116:117], v[32:33], v[116:117], v[42:43]
	s_nop 0
	v_pk_add_f32 v[104:105], v[116:117], v[104:105]
	s_nop 0
	v_pk_add_f32 v[116:117], v[106:107], v[104:105]
	v_cvt_pk_bf16_f32 v104, v108, v109
	v_cvt_pk_bf16_f32 v105, v110, v111
	v_cvt_pk_bf16_f32 v106, v114, v115
	v_cvt_pk_bf16_f32 v107, v116, v117
	global_store_dwordx4 v[112:113], v[104:107], off sc1
	s_nop 1
	v_lshlrev_b32_e32 v106, 16, v128
	v_and_b32_e32 v107, 0xffff0000, v128
	v_pk_add_f32 v[106:107], v[106:107], v[12:13] op_sel_hi:[1,0] neg_lo:[0,1] neg_hi:[0,1]
	s_waitcnt vmcnt(3)
	v_lshlrev_b32_e32 v104, 16, v132
	v_pk_mul_f32 v[106:107], v[12:13], v[106:107] op_sel:[1,0]
	v_and_b32_e32 v105, 0xffff0000, v132
	v_pk_fma_f32 v[106:107], v[40:41], v[106:107], v[30:31]
	s_nop 0
	v_pk_add_f32 v[104:105], v[106:107], v[104:105]
	v_lshlrev_b32_e32 v106, 16, v129
	v_and_b32_e32 v107, 0xffff0000, v129
	v_pk_add_f32 v[106:107], v[106:107], v[12:13] op_sel_hi:[1,0] neg_lo:[0,1] neg_hi:[0,1]
	v_pk_add_f32 v[100:101], v[100:101], v[104:105]
	v_pk_mul_f32 v[106:107], v[12:13], v[106:107] op_sel:[1,0]
	v_lshlrev_b32_e32 v104, 16, v133
	v_and_b32_e32 v105, 0xffff0000, v133
	v_pk_fma_f32 v[106:107], v[28:29], v[106:107], v[26:27]
	s_nop 0
	v_pk_add_f32 v[104:105], v[106:107], v[104:105]
	v_lshlrev_b32_e32 v106, 16, v130
	v_and_b32_e32 v107, 0xffff0000, v130
	v_pk_add_f32 v[106:107], v[106:107], v[12:13] op_sel_hi:[1,0] neg_lo:[0,1] neg_hi:[0,1]
	v_pk_add_f32 v[102:103], v[102:103], v[104:105]
	v_pk_mul_f32 v[106:107], v[12:13], v[106:107] op_sel:[1,0]
	v_lshlrev_b32_e32 v104, 16, v134
	v_and_b32_e32 v105, 0xffff0000, v134
	v_pk_fma_f32 v[106:107], v[24:25], v[106:107], v[18:19]
	s_nop 0
	v_pk_add_f32 v[104:105], v[106:107], v[104:105]
	v_lshlrev_b32_e32 v106, 16, v131
	v_and_b32_e32 v107, 0xffff0000, v131
	v_pk_add_f32 v[106:107], v[106:107], v[12:13] op_sel_hi:[1,0] neg_lo:[0,1] neg_hi:[0,1]
	v_pk_add_f32 v[104:105], v[96:97], v[104:105]
	v_pk_mul_f32 v[12:13], v[12:13], v[106:107] op_sel:[1,0]
	v_lshlrev_b32_e32 v96, 16, v135
	v_and_b32_e32 v97, 0xffff0000, v135
	v_pk_fma_f32 v[12:13], v[16:17], v[12:13], v[14:15]
	s_nop 0
	v_pk_add_f32 v[12:13], v[12:13], v[96:97]
	v_cvt_pk_bf16_f32 v96, v100, v101
	v_pk_add_f32 v[12:13], v[98:99], v[12:13]
	v_cvt_pk_bf16_f32 v97, v102, v103
	v_cvt_pk_bf16_f32 v98, v104, v105
	v_cvt_pk_bf16_f32 v99, v12, v13
	global_store_dwordx4 v[112:113], v[96:99], off offset:256 sc1
	s_nop 1
	v_add_u32_e32 v98, 0x80, v160
	v_mad_u64_u32 v[12:13], s[24:25], v98, s8, v[164:165]
	v_lshl_add_u64 v[96:97], s[30:31], 0, v[12:13]
	v_lshl_add_u64 v[12:13], s[4:5], 0, v[12:13]
	global_load_dwordx4 v[104:107], v[96:97], off
	global_load_dwordx4 v[108:111], v[12:13], off
	global_load_dwordx4 v[112:115], v[96:97], off offset:256
	global_load_dwordx4 v[116:119], v[12:13], off offset:256
	global_load_dwordx2 v[128:129], v[170:171], off offset:1024
	v_add_u32_e32 v148, 0x90, v160
	global_load_dwordx2 v[12:13], v[170:171], off offset:1152
	v_mad_u64_u32 v[96:97], s[24:25], v98, s8, v[168:169]
	v_mad_u64_u32 v[98:99], s[24:25], v148, s8, v[164:165]
	v_lshl_add_u64 v[130:131], v[96:97], 0, v[164:165]
	v_lshl_add_u64 v[96:97], s[4:5], 0, v[98:99]
	v_lshl_add_u64 v[100:101], s[30:31], 0, v[98:99]
	global_load_dwordx4 v[120:123], v[96:97], off
	s_nop 0
	global_load_dwordx4 v[96:99], v[96:97], off offset:256
	s_nop 0
	global_load_dwordx4 v[124:127], v[100:101], off
	s_nop 0
	global_load_dwordx4 v[100:103], v[100:101], off offset:256
	s_waitcnt vmcnt(8)
	v_lshlrev_b32_e32 v134, 16, v108
	v_and_b32_e32 v135, 0xffff0000, v108
	v_lshlrev_b32_e32 v108, 16, v109
	v_and_b32_e32 v109, 0xffff0000, v109
	v_lshlrev_b32_e32 v138, 16, v110
	v_and_b32_e32 v139, 0xffff0000, v110
	v_lshlrev_b32_e32 v110, 16, v111
	v_and_b32_e32 v111, 0xffff0000, v111
	s_waitcnt vmcnt(5)
	v_pk_add_f32 v[134:135], v[134:135], v[128:129] op_sel_hi:[1,0] neg_lo:[0,1] neg_hi:[0,1]
	v_pk_add_f32 v[108:109], v[108:109], v[128:129] op_sel_hi:[1,0] neg_lo:[0,1] neg_hi:[0,1]
	v_pk_add_f32 v[138:139], v[138:139], v[128:129] op_sel_hi:[1,0] neg_lo:[0,1] neg_hi:[0,1]
	v_pk_add_f32 v[110:111], v[110:111], v[128:129] op_sel_hi:[1,0] neg_lo:[0,1] neg_hi:[0,1]
	v_pk_mul_f32 v[134:135], v[128:129], v[134:135] op_sel:[1,0]
	v_pk_mul_f32 v[108:109], v[128:129], v[108:109] op_sel:[1,0]
	v_pk_mul_f32 v[138:139], v[128:129], v[138:139] op_sel:[1,0]
	v_pk_mul_f32 v[110:111], v[128:129], v[110:111] op_sel:[1,0]
	v_lshlrev_b32_e32 v132, 16, v104
	v_and_b32_e32 v133, 0xffff0000, v104
	v_lshlrev_b32_e32 v104, 16, v105
	v_and_b32_e32 v105, 0xffff0000, v105
	v_lshlrev_b32_e32 v136, 16, v106
	v_and_b32_e32 v137, 0xffff0000, v106
	v_lshlrev_b32_e32 v106, 16, v107
	v_and_b32_e32 v107, 0xffff0000, v107
	v_pk_fma_f32 v[134:135], v[166:167], v[134:135], v[62:63]
	v_pk_fma_f32 v[108:109], v[60:61], v[108:109], v[54:55]
	v_pk_fma_f32 v[138:139], v[52:53], v[138:139], v[34:35]
	v_pk_fma_f32 v[110:111], v[32:33], v[110:111], v[42:43]
	v_pk_add_f32 v[132:133], v[134:135], v[132:133]
	v_pk_add_f32 v[104:105], v[108:109], v[104:105]
	v_pk_add_f32 v[108:109], v[138:139], v[136:137]
	v_pk_add_f32 v[106:107], v[110:111], v[106:107]
	v_lshlrev_b32_e32 v142, 16, v116
	v_and_b32_e32 v143, 0xffff0000, v116
	v_lshlrev_b32_e32 v116, 16, v117
	v_and_b32_e32 v117, 0xffff0000, v117
	v_lshlrev_b32_e32 v146, 16, v118
	v_and_b32_e32 v147, 0xffff0000, v118
	v_pk_add_f32 v[84:85], v[84:85], v[132:133]
	v_pk_add_f32 v[86:87], v[86:87], v[104:105]
	v_pk_add_f32 v[88:89], v[88:89], v[108:109]
	v_pk_add_f32 v[90:91], v[90:91], v[106:107]
	v_pk_add_f32 v[116:117], v[116:117], v[128:129] op_sel_hi:[1,0] neg_lo:[0,1] neg_hi:[0,1]
	v_pk_add_f32 v[146:147], v[146:147], v[128:129] op_sel_hi:[1,0] neg_lo:[0,1] neg_hi:[0,1]
	v_cvt_pk_bf16_f32 v84, v84, v85
	v_cvt_pk_bf16_f32 v85, v86, v87
	v_cvt_pk_bf16_f32 v86, v88, v89
	v_cvt_pk_bf16_f32 v87, v90, v91
	v_pk_mul_f32 v[116:117], v[128:129], v[116:117] op_sel:[1,0]
	v_pk_mul_f32 v[146:147], v[128:129], v[146:147] op_sel:[1,0]
	global_store_dwordx4 v[130:131], v[84:87], off sc1
	v_lshlrev_b32_e32 v140, 16, v112
	v_and_b32_e32 v141, 0xffff0000, v112
	v_lshlrev_b32_e32 v84, 16, v119
	v_and_b32_e32 v85, 0xffff0000, v119
	v_lshlrev_b32_e32 v112, 16, v113
	v_and_b32_e32 v113, 0xffff0000, v113
	v_lshlrev_b32_e32 v144, 16, v114
	v_and_b32_e32 v145, 0xffff0000, v114
	v_pk_fma_f32 v[116:117], v[28:29], v[116:117], v[26:27]
	v_pk_fma_f32 v[146:147], v[24:25], v[146:147], v[18:19]
	v_pk_add_f32 v[84:85], v[84:85], v[128:129] op_sel_hi:[1,0] neg_lo:[0,1] neg_hi:[0,1]
	v_pk_add_f32 v[112:113], v[116:117], v[112:113]
	v_pk_add_f32 v[116:117], v[146:147], v[144:145]
	v_pk_mul_f32 v[84:85], v[128:129], v[84:85] op_sel:[1,0]
	v_pk_add_f32 v[142:143], v[142:143], v[128:129] op_sel_hi:[1,0] neg_lo:[0,1] neg_hi:[0,1]
	v_pk_add_f32 v[104:105], v[80:81], v[116:117]
	v_lshlrev_b32_e32 v80, 16, v115
	v_and_b32_e32 v81, 0xffff0000, v115
	v_pk_fma_f32 v[84:85], v[16:17], v[84:85], v[14:15]
	v_pk_mul_f32 v[142:143], v[128:129], v[142:143] op_sel:[1,0]
	v_pk_add_f32 v[80:81], v[84:85], v[80:81]
	v_pk_fma_f32 v[142:143], v[40:41], v[142:143], v[30:31]
	v_pk_add_f32 v[84:85], v[82:83], v[80:81]
	v_pk_add_f32 v[110:111], v[142:143], v[140:141]
	v_cvt_pk_bf16_f32 v83, v84, v85
	s_waitcnt vmcnt(4)
	v_lshlrev_b32_e32 v84, 16, v120
	v_and_b32_e32 v85, 0xffff0000, v120
	v_pk_add_f32 v[92:93], v[92:93], v[110:111]
	v_pk_add_f32 v[94:95], v[94:95], v[112:113]
	v_pk_add_f32 v[84:85], v[84:85], v[12:13] op_sel_hi:[1,0] neg_lo:[0,1] neg_hi:[0,1]
	v_cvt_pk_bf16_f32 v80, v92, v93
	v_cvt_pk_bf16_f32 v81, v94, v95
	v_cvt_pk_bf16_f32 v82, v104, v105
	v_pk_mul_f32 v[84:85], v[12:13], v[84:85] op_sel:[1,0]
	global_store_dwordx4 v[130:131], v[80:83], off offset:256 sc1
	v_pk_fma_f32 v[84:85], v[166:167], v[84:85], v[62:63]
	s_waitcnt vmcnt(3)
	v_lshlrev_b32_e32 v82, 16, v124
	v_and_b32_e32 v83, 0xffff0000, v124
	v_pk_add_f32 v[82:83], v[84:85], v[82:83]
	v_lshlrev_b32_e32 v84, 16, v121
	v_and_b32_e32 v85, 0xffff0000, v121
	v_pk_add_f32 v[84:85], v[84:85], v[12:13] op_sel_hi:[1,0] neg_lo:[0,1] neg_hi:[0,1]
	v_pk_add_f32 v[76:77], v[76:77], v[82:83]
	v_pk_mul_f32 v[84:85], v[12:13], v[84:85] op_sel:[1,0]
	v_lshlrev_b32_e32 v82, 16, v125
	v_and_b32_e32 v83, 0xffff0000, v125
	v_pk_fma_f32 v[84:85], v[60:61], v[84:85], v[54:55]
	v_mad_u64_u32 v[80:81], s[24:25], v148, s8, v[168:169]
	v_pk_add_f32 v[82:83], v[84:85], v[82:83]
	v_lshlrev_b32_e32 v84, 16, v122
	v_and_b32_e32 v85, 0xffff0000, v122
	v_pk_add_f32 v[84:85], v[84:85], v[12:13] op_sel_hi:[1,0] neg_lo:[0,1] neg_hi:[0,1]
	v_pk_add_f32 v[78:79], v[78:79], v[82:83]
	v_pk_mul_f32 v[84:85], v[12:13], v[84:85] op_sel:[1,0]
	v_lshlrev_b32_e32 v82, 16, v126
	v_and_b32_e32 v83, 0xffff0000, v126
	v_pk_fma_f32 v[84:85], v[52:53], v[84:85], v[34:35]
	v_lshl_add_u64 v[80:81], v[80:81], 0, v[164:165]
	v_pk_add_f32 v[82:83], v[84:85], v[82:83]
	v_lshlrev_b32_e32 v84, 16, v123
	v_and_b32_e32 v85, 0xffff0000, v123
	v_pk_add_f32 v[84:85], v[84:85], v[12:13] op_sel_hi:[1,0] neg_lo:[0,1] neg_hi:[0,1]
	v_pk_add_f32 v[82:83], v[72:73], v[82:83]
	v_pk_mul_f32 v[84:85], v[12:13], v[84:85] op_sel:[1,0]
	v_lshlrev_b32_e32 v72, 16, v127
	v_and_b32_e32 v73, 0xffff0000, v127
	v_pk_fma_f32 v[84:85], v[32:33], v[84:85], v[42:43]
	s_nop 0
	v_pk_add_f32 v[72:73], v[84:85], v[72:73]
	s_nop 0
	v_pk_add_f32 v[84:85], v[74:75], v[72:73]
	v_cvt_pk_bf16_f32 v72, v76, v77
	v_cvt_pk_bf16_f32 v73, v78, v79
	v_cvt_pk_bf16_f32 v74, v82, v83
	v_cvt_pk_bf16_f32 v75, v84, v85
	global_store_dwordx4 v[80:81], v[72:75], off sc1
	s_nop 1
	v_lshlrev_b32_e32 v74, 16, v96
	v_and_b32_e32 v75, 0xffff0000, v96
	v_pk_add_f32 v[74:75], v[74:75], v[12:13] op_sel_hi:[1,0] neg_lo:[0,1] neg_hi:[0,1]
	s_waitcnt vmcnt(3)
	v_lshlrev_b32_e32 v72, 16, v100
	v_pk_mul_f32 v[74:75], v[12:13], v[74:75] op_sel:[1,0]
	v_and_b32_e32 v73, 0xffff0000, v100
	v_pk_fma_f32 v[74:75], v[40:41], v[74:75], v[30:31]
	s_nop 0
	v_pk_add_f32 v[72:73], v[74:75], v[72:73]
	v_lshlrev_b32_e32 v74, 16, v97
	v_and_b32_e32 v75, 0xffff0000, v97
	v_pk_add_f32 v[74:75], v[74:75], v[12:13] op_sel_hi:[1,0] neg_lo:[0,1] neg_hi:[0,1]
	v_pk_add_f32 v[68:69], v[68:69], v[72:73]
	v_pk_mul_f32 v[74:75], v[12:13], v[74:75] op_sel:[1,0]
	v_lshlrev_b32_e32 v72, 16, v101
	v_and_b32_e32 v73, 0xffff0000, v101
	v_pk_fma_f32 v[74:75], v[28:29], v[74:75], v[26:27]
	s_nop 0
	v_pk_add_f32 v[72:73], v[74:75], v[72:73]
	v_lshlrev_b32_e32 v74, 16, v98
	v_and_b32_e32 v75, 0xffff0000, v98
	v_pk_add_f32 v[74:75], v[74:75], v[12:13] op_sel_hi:[1,0] neg_lo:[0,1] neg_hi:[0,1]
	v_pk_add_f32 v[70:71], v[70:71], v[72:73]
	v_pk_mul_f32 v[74:75], v[12:13], v[74:75] op_sel:[1,0]
	v_lshlrev_b32_e32 v72, 16, v102
	v_and_b32_e32 v73, 0xffff0000, v102
	v_pk_fma_f32 v[74:75], v[24:25], v[74:75], v[18:19]
	s_nop 0
	v_pk_add_f32 v[72:73], v[74:75], v[72:73]
	v_lshlrev_b32_e32 v74, 16, v99
	v_and_b32_e32 v75, 0xffff0000, v99
	v_pk_add_f32 v[74:75], v[74:75], v[12:13] op_sel_hi:[1,0] neg_lo:[0,1] neg_hi:[0,1]
	v_pk_add_f32 v[72:73], v[64:65], v[72:73]
	v_pk_mul_f32 v[12:13], v[12:13], v[74:75] op_sel:[1,0]
	v_lshlrev_b32_e32 v64, 16, v103
	v_and_b32_e32 v65, 0xffff0000, v103
	v_pk_fma_f32 v[12:13], v[16:17], v[12:13], v[14:15]
	s_nop 0
	v_pk_add_f32 v[12:13], v[12:13], v[64:65]
	v_cvt_pk_bf16_f32 v64, v68, v69
	v_pk_add_f32 v[12:13], v[66:67], v[12:13]
	v_cvt_pk_bf16_f32 v65, v70, v71
	v_cvt_pk_bf16_f32 v66, v72, v73
	v_cvt_pk_bf16_f32 v67, v12, v13
	global_store_dwordx4 v[80:81], v[64:67], off offset:256 sc1
	s_nop 1
	v_add_u32_e32 v66, 0xa0, v160
	v_mad_u64_u32 v[12:13], s[24:25], v66, s8, v[164:165]
	v_lshl_add_u64 v[64:65], s[30:31], 0, v[12:13]
	v_lshl_add_u64 v[12:13], s[4:5], 0, v[12:13]
	global_load_dwordx4 v[72:75], v[64:65], off
	global_load_dwordx4 v[76:79], v[12:13], off
	global_load_dwordx4 v[80:83], v[64:65], off offset:256
	global_load_dwordx4 v[84:87], v[12:13], off offset:256
	global_load_dwordx2 v[96:97], v[170:171], off offset:1280
	v_add_u32_e32 v116, 0xb0, v160
	global_load_dwordx2 v[12:13], v[170:171], off offset:1408
	v_mad_u64_u32 v[64:65], s[24:25], v116, s8, v[164:165]
	v_mad_u64_u32 v[66:67], s[24:25], v66, s8, v[168:169]
	v_lshl_add_u64 v[68:69], s[4:5], 0, v[64:65]
	v_lshl_add_u64 v[70:71], s[30:31], 0, v[64:65]
	v_lshl_add_u64 v[98:99], v[66:67], 0, v[164:165]
	global_load_dwordx4 v[88:91], v[68:69], off
	global_load_dwordx4 v[64:67], v[68:69], off offset:256
	global_load_dwordx4 v[92:95], v[70:71], off
	s_nop 0
	global_load_dwordx4 v[68:71], v[70:71], off offset:256
	s_andn2_b64 vcc, exec, s[14:15]
	s_waitcnt vmcnt(8)
	v_lshlrev_b32_e32 v102, 16, v76
	v_and_b32_e32 v103, 0xffff0000, v76
	v_lshlrev_b32_e32 v76, 16, v77
	v_and_b32_e32 v77, 0xffff0000, v77
	v_lshlrev_b32_e32 v106, 16, v78
	v_and_b32_e32 v107, 0xffff0000, v78
	v_lshlrev_b32_e32 v78, 16, v79
	v_and_b32_e32 v79, 0xffff0000, v79
	s_waitcnt vmcnt(5)
	v_pk_add_f32 v[102:103], v[102:103], v[96:97] op_sel_hi:[1,0] neg_lo:[0,1] neg_hi:[0,1]
	v_pk_add_f32 v[76:77], v[76:77], v[96:97] op_sel_hi:[1,0] neg_lo:[0,1] neg_hi:[0,1]
	v_pk_add_f32 v[106:107], v[106:107], v[96:97] op_sel_hi:[1,0] neg_lo:[0,1] neg_hi:[0,1]
	v_pk_add_f32 v[78:79], v[78:79], v[96:97] op_sel_hi:[1,0] neg_lo:[0,1] neg_hi:[0,1]
	v_pk_mul_f32 v[102:103], v[96:97], v[102:103] op_sel:[1,0]
	v_pk_mul_f32 v[76:77], v[96:97], v[76:77] op_sel:[1,0]
	v_pk_mul_f32 v[106:107], v[96:97], v[106:107] op_sel:[1,0]
	v_pk_mul_f32 v[78:79], v[96:97], v[78:79] op_sel:[1,0]
	v_lshlrev_b32_e32 v100, 16, v72
	v_and_b32_e32 v101, 0xffff0000, v72
	v_lshlrev_b32_e32 v72, 16, v73
	v_and_b32_e32 v73, 0xffff0000, v73
	v_lshlrev_b32_e32 v104, 16, v74
	v_and_b32_e32 v105, 0xffff0000, v74
	v_lshlrev_b32_e32 v74, 16, v75
	v_and_b32_e32 v75, 0xffff0000, v75
	v_pk_fma_f32 v[102:103], v[166:167], v[102:103], v[62:63]
	v_pk_fma_f32 v[76:77], v[60:61], v[76:77], v[54:55]
	v_pk_fma_f32 v[106:107], v[52:53], v[106:107], v[34:35]
	v_pk_fma_f32 v[78:79], v[32:33], v[78:79], v[42:43]
	v_pk_add_f32 v[100:101], v[102:103], v[100:101]
	v_pk_add_f32 v[72:73], v[76:77], v[72:73]
	v_pk_add_f32 v[76:77], v[106:107], v[104:105]
	v_pk_add_f32 v[74:75], v[78:79], v[74:75]
	v_lshlrev_b32_e32 v110, 16, v84
	v_and_b32_e32 v111, 0xffff0000, v84
	v_lshlrev_b32_e32 v84, 16, v85
	v_and_b32_e32 v85, 0xffff0000, v85
	v_lshlrev_b32_e32 v114, 16, v86
	v_and_b32_e32 v115, 0xffff0000, v86
	v_pk_add_f32 v[44:45], v[44:45], v[100:101]
	v_pk_add_f32 v[46:47], v[46:47], v[72:73]
	v_pk_add_f32 v[48:49], v[48:49], v[76:77]
	v_pk_add_f32 v[50:51], v[50:51], v[74:75]
	v_pk_add_f32 v[84:85], v[84:85], v[96:97] op_sel_hi:[1,0] neg_lo:[0,1] neg_hi:[0,1]
	v_pk_add_f32 v[114:115], v[114:115], v[96:97] op_sel_hi:[1,0] neg_lo:[0,1] neg_hi:[0,1]
	v_cvt_pk_bf16_f32 v44, v44, v45
	v_cvt_pk_bf16_f32 v45, v46, v47
	v_cvt_pk_bf16_f32 v46, v48, v49
	v_cvt_pk_bf16_f32 v47, v50, v51
	v_pk_mul_f32 v[84:85], v[96:97], v[84:85] op_sel:[1,0]
	v_pk_mul_f32 v[114:115], v[96:97], v[114:115] op_sel:[1,0]
	global_store_dwordx4 v[98:99], v[44:47], off sc1
	v_lshlrev_b32_e32 v108, 16, v80
	v_and_b32_e32 v109, 0xffff0000, v80
	v_lshlrev_b32_e32 v44, 16, v87
	v_and_b32_e32 v45, 0xffff0000, v87
	v_lshlrev_b32_e32 v80, 16, v81
	v_and_b32_e32 v81, 0xffff0000, v81
	v_lshlrev_b32_e32 v112, 16, v82
	v_and_b32_e32 v113, 0xffff0000, v82
	v_pk_fma_f32 v[84:85], v[28:29], v[84:85], v[26:27]
	v_pk_fma_f32 v[114:115], v[24:25], v[114:115], v[18:19]
	v_pk_add_f32 v[44:45], v[44:45], v[96:97] op_sel_hi:[1,0] neg_lo:[0,1] neg_hi:[0,1]
	v_pk_add_f32 v[80:81], v[84:85], v[80:81]
	v_pk_add_f32 v[84:85], v[114:115], v[112:113]
	v_pk_mul_f32 v[44:45], v[96:97], v[44:45] op_sel:[1,0]
	v_pk_add_f32 v[110:111], v[110:111], v[96:97] op_sel_hi:[1,0] neg_lo:[0,1] neg_hi:[0,1]
	v_pk_add_f32 v[72:73], v[36:37], v[84:85]
	v_lshlrev_b32_e32 v36, 16, v83
	v_and_b32_e32 v37, 0xffff0000, v83
	v_pk_fma_f32 v[44:45], v[16:17], v[44:45], v[14:15]
	v_pk_mul_f32 v[110:111], v[96:97], v[110:111] op_sel:[1,0]
	v_pk_add_f32 v[36:37], v[44:45], v[36:37]
	v_pk_fma_f32 v[110:111], v[40:41], v[110:111], v[30:31]
	v_pk_add_f32 v[44:45], v[38:39], v[36:37]
	v_pk_add_f32 v[78:79], v[110:111], v[108:109]
	v_cvt_pk_bf16_f32 v39, v44, v45
	s_waitcnt vmcnt(4)
	v_lshlrev_b32_e32 v44, 16, v88
	v_and_b32_e32 v45, 0xffff0000, v88
	v_pk_add_f32 v[56:57], v[56:57], v[78:79]
	v_pk_add_f32 v[58:59], v[58:59], v[80:81]
	v_pk_add_f32 v[44:45], v[44:45], v[12:13] op_sel_hi:[1,0] neg_lo:[0,1] neg_hi:[0,1]
	v_cvt_pk_bf16_f32 v36, v56, v57
	v_cvt_pk_bf16_f32 v37, v58, v59
	v_cvt_pk_bf16_f32 v38, v72, v73
	v_pk_mul_f32 v[44:45], v[12:13], v[44:45] op_sel:[1,0]
	global_store_dwordx4 v[98:99], v[36:39], off offset:256 sc1
	v_pk_fma_f32 v[44:45], v[166:167], v[44:45], v[62:63]
	s_waitcnt vmcnt(3)
	v_lshlrev_b32_e32 v38, 16, v92
	v_and_b32_e32 v39, 0xffff0000, v92
	v_pk_add_f32 v[38:39], v[44:45], v[38:39]
	v_lshlrev_b32_e32 v44, 16, v89
	v_and_b32_e32 v45, 0xffff0000, v89
	v_pk_add_f32 v[44:45], v[44:45], v[12:13] op_sel_hi:[1,0] neg_lo:[0,1] neg_hi:[0,1]
	v_pk_add_f32 v[20:21], v[20:21], v[38:39]
	v_pk_mul_f32 v[44:45], v[12:13], v[44:45] op_sel:[1,0]
	v_lshlrev_b32_e32 v38, 16, v93
	v_and_b32_e32 v39, 0xffff0000, v93
	v_pk_fma_f32 v[44:45], v[60:61], v[44:45], v[54:55]
	v_mad_u64_u32 v[36:37], s[4:5], v116, s8, v[168:169]
	v_pk_add_f32 v[38:39], v[44:45], v[38:39]
	v_lshlrev_b32_e32 v44, 16, v90
	v_and_b32_e32 v45, 0xffff0000, v90
	v_pk_add_f32 v[44:45], v[44:45], v[12:13] op_sel_hi:[1,0] neg_lo:[0,1] neg_hi:[0,1]
	v_pk_add_f32 v[22:23], v[22:23], v[38:39]
	v_pk_mul_f32 v[44:45], v[12:13], v[44:45] op_sel:[1,0]
	v_lshlrev_b32_e32 v38, 16, v94
	v_and_b32_e32 v39, 0xffff0000, v94
	v_pk_fma_f32 v[34:35], v[52:53], v[44:45], v[34:35]
	v_lshl_add_u64 v[36:37], v[36:37], 0, v[164:165]
	v_pk_add_f32 v[34:35], v[34:35], v[38:39]
	v_lshlrev_b32_e32 v38, 16, v91
	v_and_b32_e32 v39, 0xffff0000, v91
	v_pk_add_f32 v[38:39], v[38:39], v[12:13] op_sel_hi:[1,0] neg_lo:[0,1] neg_hi:[0,1]
	v_pk_add_f32 v[34:35], v[8:9], v[34:35]
	v_pk_mul_f32 v[38:39], v[12:13], v[38:39] op_sel:[1,0]
	v_lshlrev_b32_e32 v8, 16, v95
	v_and_b32_e32 v9, 0xffff0000, v95
	v_pk_fma_f32 v[32:33], v[32:33], v[38:39], v[42:43]
	s_mov_b64 s[4:5], -1
	v_pk_add_f32 v[8:9], v[32:33], v[8:9]
	s_nop 0
	v_pk_add_f32 v[32:33], v[10:11], v[8:9]
	v_cvt_pk_bf16_f32 v8, v20, v21
	v_cvt_pk_bf16_f32 v9, v22, v23
	v_cvt_pk_bf16_f32 v10, v34, v35
	v_cvt_pk_bf16_f32 v11, v32, v33
	global_store_dwordx4 v[36:37], v[8:11], off sc1
	s_nop 1
	v_lshlrev_b32_e32 v10, 16, v64
	v_and_b32_e32 v11, 0xffff0000, v64
	v_pk_add_f32 v[10:11], v[10:11], v[12:13] op_sel_hi:[1,0] neg_lo:[0,1] neg_hi:[0,1]
	s_waitcnt vmcnt(3)
	v_lshlrev_b32_e32 v8, 16, v68
	v_pk_mul_f32 v[10:11], v[12:13], v[10:11] op_sel:[1,0]
	v_and_b32_e32 v9, 0xffff0000, v68
	v_pk_fma_f32 v[10:11], v[40:41], v[10:11], v[30:31]
	s_nop 0
	v_pk_add_f32 v[8:9], v[10:11], v[8:9]
	v_lshlrev_b32_e32 v10, 16, v65
	v_and_b32_e32 v11, 0xffff0000, v65
	v_pk_add_f32 v[10:11], v[10:11], v[12:13] op_sel_hi:[1,0] neg_lo:[0,1] neg_hi:[0,1]
	v_pk_add_f32 v[4:5], v[4:5], v[8:9]
	v_pk_mul_f32 v[10:11], v[12:13], v[10:11] op_sel:[1,0]
	v_lshlrev_b32_e32 v8, 16, v69
	v_and_b32_e32 v9, 0xffff0000, v69
	v_pk_fma_f32 v[10:11], v[28:29], v[10:11], v[26:27]
	s_nop 0
	v_pk_add_f32 v[8:9], v[10:11], v[8:9]
	v_lshlrev_b32_e32 v10, 16, v66
	v_and_b32_e32 v11, 0xffff0000, v66
	v_pk_add_f32 v[10:11], v[10:11], v[12:13] op_sel_hi:[1,0] neg_lo:[0,1] neg_hi:[0,1]
	v_pk_add_f32 v[6:7], v[6:7], v[8:9]
	v_pk_mul_f32 v[10:11], v[12:13], v[10:11] op_sel:[1,0]
	v_lshlrev_b32_e32 v8, 16, v70
	v_and_b32_e32 v9, 0xffff0000, v70
	v_pk_fma_f32 v[10:11], v[24:25], v[10:11], v[18:19]
	s_nop 0
	v_pk_add_f32 v[8:9], v[10:11], v[8:9]
	v_lshlrev_b32_e32 v10, 16, v67
	v_and_b32_e32 v11, 0xffff0000, v67
	v_pk_add_f32 v[10:11], v[10:11], v[12:13] op_sel_hi:[1,0] neg_lo:[0,1] neg_hi:[0,1]
	v_pk_add_f32 v[8:9], v[0:1], v[8:9]
	v_pk_mul_f32 v[10:11], v[12:13], v[10:11] op_sel:[1,0]
	v_lshlrev_b32_e32 v0, 16, v71
	v_and_b32_e32 v1, 0xffff0000, v71
	v_pk_fma_f32 v[10:11], v[16:17], v[10:11], v[14:15]
	s_nop 0
	v_pk_add_f32 v[0:1], v[10:11], v[0:1]
	s_nop 0
	v_pk_add_f32 v[10:11], v[2:3], v[0:1]
	v_cvt_pk_bf16_f32 v0, v4, v5
	v_cvt_pk_bf16_f32 v1, v6, v7
	v_cvt_pk_bf16_f32 v2, v8, v9
	v_cvt_pk_bf16_f32 v3, v10, v11
	global_store_dwordx4 v[36:37], v[0:3], off offset:256 sc1
	s_cbranch_vccnz .LBB0_1013
	v_readlane_b32 s0, v254, 17
	v_readlane_b32 s1, v254, 18
	s_andn2_b64 vcc, exec, s[0:1]
	s_cbranch_vccnz .LBB0_1012
	s_barrier
	s_branch .LBB0_1012
